# redundant s_setprio 0/1 pair in the middle of each 32-MFMA block removed
# baseline (speedup 1.0000x reference)
; #define PG8_STAGE(bufoff, gbase, voff) do { _Pragma("unroll") for (int _i = 0; _i < 2; ++_i) \
;         __builtin_amdgcn_global_load_lds((const unsigned*)((const char*)(gbase) + (voff)[_i]), (PG8_LAS unsigned*)(lds + (bufoff) + ldsw + _i * 8192), 16, 0, 0); } while (0)
; #define PG8_LDA(dst, b, h) do { _Pragma("unroll") for (int m = 0; m < 4; ++m) _Pragma("unroll") for (int k = 0; k < 2; ++k) dst[m][k] = *(const PG8_LAS bf16x8*)(lds + PG8_SA(b, h) + aoff + m * 2048 + k * 1024); } while (0)
; #define PG8_LDB(dst, b, h) do { _Pragma("unroll") for (int n = 0; n < 2; ++n) _Pragma("unroll") for (int k = 0; k < 2; ++k) dst[n][k] = *(const PG8_LAS bf16x8*)(lds + PG8_SB(b, h) + boff + n * 2048 + k * 1024); } while (0)
; #define PG8_MMA(ai, bj, At, Bt) do { __builtin_amdgcn_s_setprio(1); _Pragma("unroll") for (int m = 0; m < 4; ++m) _Pragma("unroll") for (int n = 0; n < 2; ++n) _Pragma("unroll") for (int k = 0; k < 2; ++k) \
;         acc[ai][bj][m][n] = __builtin_amdgcn_mfma_f32_16x16x32_bf16(Bt[n][k], At[m][k], acc[ai][bj][m][n], 0, 0, 0); __builtin_amdgcn_s_setprio(0); } while (0)
; #define PG8_WAIT_V(n) asm volatile("s_waitcnt vmcnt(" #n ")" ::: "memory")
; #define PG8_WAIT_L(n) asm volatile("s_waitcnt lgkmcnt(" #n ")" ::: "memory")
; #define PG8_BAR __builtin_amdgcn_s_barrier()
; #define PG8_SCHED __builtin_amdgcn_sched_barrier(0)
; template <class Epi, class Sched, bool ALIGN_EPI = false, bool SP2 = false>
; __device__ __forceinline__ void gemm_phase(PG8_LAS unsigned char* lds, const Gemm g, const Sched& S, const Epi& E) {
;     ...
;             PG8_LDB(B0, 0, 0); PG8_LDB(B1, 0, 1); PG8_SCHED; PG8_LDA(At, 0, 0); PG8_STAGE(PG8_SA(1, 1), a1 + hstepA, voffA);
;             PG8_WAIT_V(8); PG8_WAIT_L(0); PG8_BAR; PG8_MMA(0, 0, At, B0); PG8_MMA(0, 1, At, B1); PG8_BAR; PG8_SCHED;
;             PG8_LDA(At, 0, 1); PG8_STAGE(PG8_SB(0, 0), b2, voffB); PG8_STAGE(PG8_SB(0, 1), b2 + hstepB, voffB); PG8_STAGE(PG8_SA(0, 0), a2, voffA);
.LBB0_141:
	ds_read_b128 v[150:153], v143
	ds_read_b128 v[154:157], v143 offset:1024
	ds_read_b128 v[158:161], v143 offset:2048
	ds_read_b128 v[162:165], v143 offset:3072
	ds_read_b128 v[166:169], v144
	ds_read_b128 v[170:173], v144 offset:1024
	ds_read_b128 v[174:177], v144 offset:2048
	ds_read_b128 v[178:181], v144 offset:3072
	s_cmp_eq_u32 s94, 12
	s_cselect_b32 s97, s59, s71
	s_cselect_b32 s96, s92, s70
	s_cselect_b32 vcc_hi, s57, s73
	s_cselect_b32 vcc_lo, s93, s72
	s_movk_i32 s8, 0xc000
	v_lshl_add_u64 v[186:187], s[70:71], 0, v[128:129]
	s_mov_b32 s9, -1
	v_lshl_add_u64 v[220:221], v[186:187], 0, s[8:9]
	s_movk_i32 s8, 0xe000
	s_add_i32 m0, s18, 0xc000
	s_mov_b32 s9, -1
	ds_read_b128 v[182:185], v145
	ds_read_b128 v[190:193], v145 offset:1024
	ds_read_b128 v[194:197], v145 offset:2048
	ds_read_b128 v[198:201], v145 offset:3072
	ds_read_b128 v[202:205], v145 offset:4096
	ds_read_b128 v[206:209], v145 offset:5120
	ds_read_b128 v[210:213], v145 offset:6144
	ds_read_b128 v[214:217], v145 offset:7168
	global_load_lds_dwordx4 v[220:221], off
	v_lshl_add_u64 v[186:187], v[186:187], 0, s[8:9]
	s_add_i32 m0, s18, 0xe000
	s_nop 0
	global_load_lds_dwordx4 v[186:187], off
	s_waitcnt vmcnt(8)
	s_waitcnt lgkmcnt(0)
	s_barrier
	s_setprio 1
	s_waitcnt lgkmcnt(0)
	v_mfma_f32_16x16x32_bf16 v[116:119], v[150:153], v[182:185], v[116:119]
	v_mfma_f32_16x16x32_bf16 v[112:115], v[158:161], v[182:185], v[112:115]
	v_mfma_f32_16x16x32_bf16 v[108:111], v[150:153], v[194:197], v[108:111]
	v_mfma_f32_16x16x32_bf16 v[100:103], v[158:161], v[194:197], v[100:103]
	v_mfma_f32_16x16x32_bf16 v[92:95], v[150:153], v[202:205], v[92:95]
	v_mfma_f32_16x16x32_bf16 v[84:87], v[158:161], v[202:205], v[84:87]
	v_mfma_f32_16x16x32_bf16 v[76:79], v[150:153], v[210:213], v[76:79]
	v_mfma_f32_16x16x32_bf16 v[68:71], v[158:161], v[210:213], v[68:71]
	v_mfma_f32_16x16x32_bf16 v[116:119], v[154:157], v[190:193], v[116:119]
	v_mfma_f32_16x16x32_bf16 v[112:115], v[162:165], v[190:193], v[112:115]
	v_mfma_f32_16x16x32_bf16 v[108:111], v[154:157], v[198:201], v[108:111]
	v_mfma_f32_16x16x32_bf16 v[100:103], v[162:165], v[198:201], v[100:103]
	v_mfma_f32_16x16x32_bf16 v[92:95], v[154:157], v[206:209], v[92:95]
	v_mfma_f32_16x16x32_bf16 v[84:87], v[162:165], v[206:209], v[84:87]
	v_mfma_f32_16x16x32_bf16 v[76:79], v[154:157], v[214:217], v[76:79]
	v_mfma_f32_16x16x32_bf16 v[68:71], v[162:165], v[214:217], v[68:71]
	v_mfma_f32_16x16x32_bf16 v[124:127], v[166:169], v[182:185], v[124:127]
	v_mfma_f32_16x16x32_bf16 v[120:123], v[174:177], v[182:185], v[120:123]
	v_mfma_f32_16x16x32_bf16 v[104:107], v[166:169], v[194:197], v[104:107]
	v_mfma_f32_16x16x32_bf16 v[96:99], v[174:177], v[194:197], v[96:99]
	v_mfma_f32_16x16x32_bf16 v[88:91], v[166:169], v[202:205], v[88:91]
	v_mfma_f32_16x16x32_bf16 v[80:83], v[174:177], v[202:205], v[80:83]
	v_mfma_f32_16x16x32_bf16 v[72:75], v[166:169], v[210:213], v[72:75]
	v_mfma_f32_16x16x32_bf16 v[64:67], v[174:177], v[210:213], v[64:67]
	v_mfma_f32_16x16x32_bf16 v[124:127], v[170:173], v[190:193], v[124:127]
	v_mfma_f32_16x16x32_bf16 v[120:123], v[178:181], v[190:193], v[120:123]
	v_mfma_f32_16x16x32_bf16 v[104:107], v[170:173], v[198:201], v[104:107]
	v_mfma_f32_16x16x32_bf16 v[96:99], v[178:181], v[198:201], v[96:99]
	v_mfma_f32_16x16x32_bf16 v[88:91], v[170:173], v[206:209], v[88:91]
	v_mfma_f32_16x16x32_bf16 v[80:83], v[178:181], v[206:209], v[80:83]
	v_mfma_f32_16x16x32_bf16 v[72:75], v[170:173], v[214:217], v[72:75]
	v_mfma_f32_16x16x32_bf16 v[64:67], v[178:181], v[214:217], v[64:67]
	s_setprio 0
	s_barrier
	s_add_i32 s8, s86, s14
	v_lshl_add_u64 v[186:187], vcc, 0, v[128:129]
	s_mov_b32 m0, s8
	ds_read_b128 v[182:185], v145 offset:16384
	ds_read_b128 v[190:193], v145 offset:17408
	ds_read_b128 v[194:197], v145 offset:18432
	ds_read_b128 v[198:201], v145 offset:19456
	ds_read_b128 v[202:205], v145 offset:20480
	ds_read_b128 v[206:209], v145 offset:21504
	ds_read_b128 v[210:213], v145 offset:22528
	ds_read_b128 v[214:217], v145 offset:23552
	global_load_lds_dwordx4 v[186:187], off
	v_lshl_add_u64 v[220:221], v[186:187], 0, s[4:5]
	s_add_i32 m0, s8, 0x2000
	s_add_i32 s8, s89, s14
	global_load_lds_dwordx4 v[220:221], off
	v_lshl_add_u64 v[220:221], v[186:187], 0, s[6:7]
	s_mov_b32 m0, s8
	s_nop 0
	global_load_lds_dwordx4 v[220:221], off
	v_lshl_add_u64 v[220:221], v[186:187], 0, s[30:31]
	s_add_i32 m0, s8, 0x2000
	s_nop 0
	global_load_lds_dwordx4 v[220:221], off
	v_lshl_add_u64 v[220:221], s[96:97], 0, v[128:129]
	s_mov_b32 m0, s18
	v_lshl_add_u64 v[222:223], v[220:221], 0, s[4:5]
	global_load_lds_dwordx4 v[220:221], off
	s_mov_b32 m0, s19
	s_nop 0
	global_load_lds_dwordx4 v[222:223], off
	s_waitcnt vmcnt(8)
	s_waitcnt lgkmcnt(0)
	s_barrier
; #define PG8_STAGE(bufoff, gbase, voff) do { _Pragma("unroll") for (int _i = 0; _i < 2; ++_i) \
;         __builtin_amdgcn_global_load_lds((const unsigned*)((const char*)(gbase) + (voff)[_i]), (PG8_LAS unsigned*)(lds + (bufoff) + ldsw + _i * 8192), 16, 0, 0); } while (0)
; #define PG8_LDA(dst, b, h) do { _Pragma("unroll") for (int m = 0; m < 4; ++m) _Pragma("unroll") for (int k = 0; k < 2; ++k) dst[m][k] = *(const PG8_LAS bf16x8*)(lds + PG8_SA(b, h) + aoff + m * 2048 + k * 1024); } while (0)
; #define PG8_LDB(dst, b, h) do { _Pragma("unroll") for (int n = 0; n < 2; ++n) _Pragma("unroll") for (int k = 0; k < 2; ++k) dst[n][k] = *(const PG8_LAS bf16x8*)(lds + PG8_SB(b, h) + boff + n * 2048 + k * 1024); } while (0)
; #define PG8_MMA(ai, bj, At, Bt) do { __builtin_amdgcn_s_setprio(1); _Pragma("unroll") for (int m = 0; m < 4; ++m) _Pragma("unroll") for (int n = 0; n < 2; ++n) _Pragma("unroll") for (int k = 0; k < 2; ++k) \
;         acc[ai][bj][m][n] = __builtin_amdgcn_mfma_f32_16x16x32_bf16(Bt[n][k], At[m][k], acc[ai][bj][m][n], 0, 0, 0); __builtin_amdgcn_s_setprio(0); } while (0)
; #define PG8_WAIT_V(n) asm volatile("s_waitcnt vmcnt(" #n ")" ::: "memory")
; #define PG8_WAIT_L(n) asm volatile("s_waitcnt lgkmcnt(" #n ")" ::: "memory")
; #define PG8_BAR __builtin_amdgcn_s_barrier()
; #define PG8_SCHED __builtin_amdgcn_sched_barrier(0)
; template <class Epi, class Sched, bool ALIGN_EPI = false, bool SP2 = false>
; __device__ __forceinline__ void gemm_phase(PG8_LAS unsigned char* lds, const Gemm g, const Sched& S, const Epi& E) {
;     ...
;             PG8_WAIT_V(8); PG8_WAIT_L(0); PG8_BAR; PG8_MMA(1, 0, At, B0); PG8_MMA(1, 1, At, B1); PG8_BAR; PG8_SCHED;
;             PG8_LDB(B0, 1, 0); PG8_LDB(B1, 1, 1); PG8_SCHED; PG8_LDA(At, 1, 0); PG8_STAGE(PG8_SA(0, 1), a2 + hstepA, voffA);
;             PG8_WAIT_V(8); PG8_WAIT_L(0); PG8_BAR; PG8_MMA(0, 0, At, B0); PG8_MMA(0, 1, At, B1); PG8_BAR; PG8_SCHED;
	s_setprio 1
	s_waitcnt lgkmcnt(0)
	v_mfma_f32_16x16x32_bf16 v[60:63], v[150:153], v[182:185], v[60:63]
	v_mfma_f32_16x16x32_bf16 v[52:55], v[158:161], v[182:185], v[52:55]
	v_mfma_f32_16x16x32_bf16 v[44:47], v[150:153], v[194:197], v[44:47]
	v_mfma_f32_16x16x32_bf16 v[36:39], v[158:161], v[194:197], v[36:39]
	v_mfma_f32_16x16x32_bf16 v[28:31], v[150:153], v[202:205], v[28:31]
	v_mfma_f32_16x16x32_bf16 v[20:23], v[158:161], v[202:205], v[20:23]
	v_mfma_f32_16x16x32_bf16 v[12:15], v[150:153], v[210:213], v[12:15]
	v_mfma_f32_16x16x32_bf16 v[4:7], v[158:161], v[210:213], v[4:7]
	v_mfma_f32_16x16x32_bf16 v[60:63], v[154:157], v[190:193], v[60:63]
	v_mfma_f32_16x16x32_bf16 v[52:55], v[162:165], v[190:193], v[52:55]
	v_mfma_f32_16x16x32_bf16 v[44:47], v[154:157], v[198:201], v[44:47]
	v_mfma_f32_16x16x32_bf16 v[36:39], v[162:165], v[198:201], v[36:39]
	v_mfma_f32_16x16x32_bf16 v[28:31], v[154:157], v[206:209], v[28:31]
	v_mfma_f32_16x16x32_bf16 v[20:23], v[162:165], v[206:209], v[20:23]
	v_mfma_f32_16x16x32_bf16 v[12:15], v[154:157], v[214:217], v[12:15]
	v_mfma_f32_16x16x32_bf16 v[4:7], v[162:165], v[214:217], v[4:7]
	v_mfma_f32_16x16x32_bf16 v[56:59], v[166:169], v[182:185], v[56:59]
	v_mfma_f32_16x16x32_bf16 v[48:51], v[174:177], v[182:185], v[48:51]
	v_mfma_f32_16x16x32_bf16 v[40:43], v[166:169], v[194:197], v[40:43]
	v_mfma_f32_16x16x32_bf16 v[32:35], v[174:177], v[194:197], v[32:35]
	v_mfma_f32_16x16x32_bf16 v[24:27], v[166:169], v[202:205], v[24:27]
	v_mfma_f32_16x16x32_bf16 v[16:19], v[174:177], v[202:205], v[16:19]
	v_mfma_f32_16x16x32_bf16 v[8:11], v[166:169], v[210:213], v[8:11]
	v_mfma_f32_16x16x32_bf16 v[0:3], v[174:177], v[210:213], v[0:3]
	v_mfma_f32_16x16x32_bf16 v[56:59], v[170:173], v[190:193], v[56:59]
	v_mfma_f32_16x16x32_bf16 v[48:51], v[178:181], v[190:193], v[48:51]
	v_mfma_f32_16x16x32_bf16 v[40:43], v[170:173], v[198:201], v[40:43]
	v_mfma_f32_16x16x32_bf16 v[32:35], v[178:181], v[198:201], v[32:35]
	v_mfma_f32_16x16x32_bf16 v[24:27], v[170:173], v[206:209], v[24:27]
	v_mfma_f32_16x16x32_bf16 v[16:19], v[178:181], v[206:209], v[16:19]
	v_mfma_f32_16x16x32_bf16 v[8:11], v[170:173], v[214:217], v[8:11]
	v_mfma_f32_16x16x32_bf16 v[0:3], v[178:181], v[214:217], v[0:3]
	s_setprio 0
	s_barrier
	ds_read_b128 v[150:153], v146
	ds_read_b128 v[154:157], v146 offset:1024
	ds_read_b128 v[158:161], v146 offset:2048
	ds_read_b128 v[162:165], v146 offset:3072
	ds_read_b128 v[166:169], v147
	ds_read_b128 v[170:173], v147 offset:1024
	ds_read_b128 v[174:177], v147 offset:2048
	ds_read_b128 v[178:181], v147 offset:3072
	s_mov_b32 m0, s74
	v_lshl_add_u64 v[222:223], v[220:221], 0, s[6:7]
	ds_read_b128 v[182:185], v145 offset:32768
	ds_read_b128 v[190:193], v145 offset:33792
	ds_read_b128 v[194:197], v145 offset:34816
	ds_read_b128 v[198:201], v145 offset:35840
	ds_read_b128 v[202:205], v145 offset:36864
	ds_read_b128 v[206:209], v145 offset:37888
	ds_read_b128 v[210:213], v145 offset:38912
	ds_read_b128 v[214:217], v145 offset:39936
	global_load_lds_dwordx4 v[222:223], off
	v_lshl_add_u64 v[222:223], v[220:221], 0, s[30:31]
	s_mov_b32 m0, s75
	s_nop 0
	global_load_lds_dwordx4 v[222:223], off
	s_waitcnt vmcnt(8)
	s_waitcnt lgkmcnt(0)
	s_barrier
	s_setprio 1
	s_waitcnt lgkmcnt(0)
	v_mfma_f32_16x16x32_bf16 v[116:119], v[150:153], v[182:185], v[116:119]
	v_mfma_f32_16x16x32_bf16 v[112:115], v[158:161], v[182:185], v[112:115]
	v_mfma_f32_16x16x32_bf16 v[108:111], v[150:153], v[194:197], v[108:111]
	v_mfma_f32_16x16x32_bf16 v[100:103], v[158:161], v[194:197], v[100:103]
	v_mfma_f32_16x16x32_bf16 v[92:95], v[150:153], v[202:205], v[92:95]
	v_mfma_f32_16x16x32_bf16 v[84:87], v[158:161], v[202:205], v[84:87]
	v_mfma_f32_16x16x32_bf16 v[76:79], v[150:153], v[210:213], v[76:79]
	v_mfma_f32_16x16x32_bf16 v[68:71], v[158:161], v[210:213], v[68:71]
	v_mfma_f32_16x16x32_bf16 v[116:119], v[154:157], v[190:193], v[116:119]
	v_mfma_f32_16x16x32_bf16 v[112:115], v[162:165], v[190:193], v[112:115]
	v_mfma_f32_16x16x32_bf16 v[108:111], v[154:157], v[198:201], v[108:111]
	v_mfma_f32_16x16x32_bf16 v[100:103], v[162:165], v[198:201], v[100:103]
	v_mfma_f32_16x16x32_bf16 v[92:95], v[154:157], v[206:209], v[92:95]
	v_mfma_f32_16x16x32_bf16 v[84:87], v[162:165], v[206:209], v[84:87]
	v_mfma_f32_16x16x32_bf16 v[76:79], v[154:157], v[214:217], v[76:79]
	v_mfma_f32_16x16x32_bf16 v[68:71], v[162:165], v[214:217], v[68:71]
	v_mfma_f32_16x16x32_bf16 v[124:127], v[166:169], v[182:185], v[124:127]
	v_mfma_f32_16x16x32_bf16 v[120:123], v[174:177], v[182:185], v[120:123]
	v_mfma_f32_16x16x32_bf16 v[104:107], v[166:169], v[194:197], v[104:107]
	v_mfma_f32_16x16x32_bf16 v[96:99], v[174:177], v[194:197], v[96:99]
	v_mfma_f32_16x16x32_bf16 v[88:91], v[166:169], v[202:205], v[88:91]
	v_mfma_f32_16x16x32_bf16 v[80:83], v[174:177], v[202:205], v[80:83]
	v_mfma_f32_16x16x32_bf16 v[72:75], v[166:169], v[210:213], v[72:75]
	v_mfma_f32_16x16x32_bf16 v[64:67], v[174:177], v[210:213], v[64:67]
	v_mfma_f32_16x16x32_bf16 v[124:127], v[170:173], v[190:193], v[124:127]
	v_mfma_f32_16x16x32_bf16 v[120:123], v[178:181], v[190:193], v[120:123]
	v_mfma_f32_16x16x32_bf16 v[104:107], v[170:173], v[198:201], v[104:107]
	v_mfma_f32_16x16x32_bf16 v[96:99], v[178:181], v[198:201], v[96:99]
	v_mfma_f32_16x16x32_bf16 v[88:91], v[170:173], v[206:209], v[88:91]
	v_mfma_f32_16x16x32_bf16 v[80:83], v[178:181], v[206:209], v[80:83]
	v_mfma_f32_16x16x32_bf16 v[72:75], v[170:173], v[214:217], v[72:75]
	v_mfma_f32_16x16x32_bf16 v[64:67], v[178:181], v[214:217], v[64:67]
	s_setprio 0
	s_barrier
; #define PG8_STAGE(bufoff, gbase, voff) do { _Pragma("unroll") for (int _i = 0; _i < 2; ++_i) \
;         __builtin_amdgcn_global_load_lds((const unsigned*)((const char*)(gbase) + (voff)[_i]), (PG8_LAS unsigned*)(lds + (bufoff) + ldsw + _i * 8192), 16, 0, 0); } while (0)
; #define PG8_LDA(dst, b, h) do { _Pragma("unroll") for (int m = 0; m < 4; ++m) _Pragma("unroll") for (int k = 0; k < 2; ++k) dst[m][k] = *(const PG8_LAS bf16x8*)(lds + PG8_SA(b, h) + aoff + m * 2048 + k * 1024); } while (0)
; #define PG8_MMA(ai, bj, At, Bt) do { __builtin_amdgcn_s_setprio(1); _Pragma("unroll") for (int m = 0; m < 4; ++m) _Pragma("unroll") for (int n = 0; n < 2; ++n) _Pragma("unroll") for (int k = 0; k < 2; ++k) \
;         acc[ai][bj][m][n] = __builtin_amdgcn_mfma_f32_16x16x32_bf16(Bt[n][k], At[m][k], acc[ai][bj][m][n], 0, 0, 0); __builtin_amdgcn_s_setprio(0); } while (0)
; #define PG8_WAIT_V(n) asm volatile("s_waitcnt vmcnt(" #n ")" ::: "memory")
; #define PG8_WAIT_L(n) asm volatile("s_waitcnt lgkmcnt(" #n ")" ::: "memory")
; #define PG8_BAR __builtin_amdgcn_s_barrier()
; #define PG8_SCHED __builtin_amdgcn_sched_barrier(0)
; template <class Epi, class Sched, bool ALIGN_EPI = false, bool SP2 = false>
; __device__ __forceinline__ void gemm_phase(PG8_LAS unsigned char* lds, const Gemm g, const Sched& S, const Epi& E) {
;     ...
;         for (int t = 0; t < nt; t += 2) {
;             const bool last = (t == nt - 2);
;             const char* a1 = cA + (size_t)(t + 1) * kstepA;
;             const char* a2 = last ? nA : cA + (size_t)(t + 2) * kstepA; const char* b2 = last ? nB : cB + (size_t)(t + 2) * kstep;
;             const char* a3 = a2 + kstepA; const char* b3 = b2 + kstep;
;     ...
;             PG8_LDA(At, 1, 1); PG8_STAGE(PG8_SB(1, 0), b3, voffB); PG8_STAGE(PG8_SB(1, 1), b3 + hstepB, voffB); PG8_STAGE(PG8_SA(1, 0), a3, voffA);
;             PG8_WAIT_V(8); PG8_WAIT_L(0); PG8_BAR; PG8_MMA(1, 0, At, B0); PG8_MMA(1, 1, At, B1); PG8_BAR; PG8_SCHED;
	s_add_i32 s8, s90, s14
	v_lshl_add_u64 v[222:223], v[186:187], 0, s[34:35]
	s_mov_b32 m0, s8
	ds_read_b128 v[182:185], v145 offset:49152
	ds_read_b128 v[190:193], v145 offset:50176
	ds_read_b128 v[194:197], v145 offset:51200
	ds_read_b128 v[198:201], v145 offset:52224
	ds_read_b128 v[202:205], v145 offset:53248
	ds_read_b128 v[206:209], v145 offset:54272
	ds_read_b128 v[210:213], v145 offset:55296
	ds_read_b128 v[214:217], v145 offset:56320
	global_load_lds_dwordx4 v[222:223], off
	v_lshl_add_u64 v[222:223], v[186:187], 0, s[36:37]
	s_add_i32 m0, s8, 0x2000
	s_add_i32 s8, s91, s14
	global_load_lds_dwordx4 v[222:223], off
	v_lshl_add_u64 v[222:223], v[186:187], 0, s[38:39]
	s_mov_b32 m0, s8
	v_lshl_add_u64 v[186:187], v[186:187], 0, s[40:41]
	global_load_lds_dwordx4 v[222:223], off
	s_add_i32 m0, s8, 0x2000
	s_nop 0
	global_load_lds_dwordx4 v[186:187], off
	v_lshl_add_u64 v[186:187], v[220:221], 0, s[34:35]
	s_mov_b32 m0, s76
	s_nop 0
	global_load_lds_dwordx4 v[186:187], off
	v_lshl_add_u64 v[186:187], v[220:221], 0, s[36:37]
	s_mov_b32 m0, s77
	s_nop 0
	global_load_lds_dwordx4 v[186:187], off
	s_waitcnt vmcnt(8)
	s_waitcnt lgkmcnt(0)
	s_barrier
	s_setprio 1
	s_waitcnt lgkmcnt(0)
	v_mfma_f32_16x16x32_bf16 v[60:63], v[150:153], v[182:185], v[60:63]
	v_mfma_f32_16x16x32_bf16 v[52:55], v[158:161], v[182:185], v[52:55]
	v_mfma_f32_16x16x32_bf16 v[44:47], v[150:153], v[194:197], v[44:47]
	v_mfma_f32_16x16x32_bf16 v[36:39], v[158:161], v[194:197], v[36:39]
	v_mfma_f32_16x16x32_bf16 v[28:31], v[150:153], v[202:205], v[28:31]
	v_mfma_f32_16x16x32_bf16 v[20:23], v[158:161], v[202:205], v[20:23]
	v_mfma_f32_16x16x32_bf16 v[12:15], v[150:153], v[210:213], v[12:15]
	v_mfma_f32_16x16x32_bf16 v[4:7], v[158:161], v[210:213], v[4:7]
	v_mfma_f32_16x16x32_bf16 v[60:63], v[154:157], v[190:193], v[60:63]
	v_mfma_f32_16x16x32_bf16 v[52:55], v[162:165], v[190:193], v[52:55]
	v_mfma_f32_16x16x32_bf16 v[44:47], v[154:157], v[198:201], v[44:47]
	v_mfma_f32_16x16x32_bf16 v[36:39], v[162:165], v[198:201], v[36:39]
	v_mfma_f32_16x16x32_bf16 v[28:31], v[154:157], v[206:209], v[28:31]
	v_mfma_f32_16x16x32_bf16 v[20:23], v[162:165], v[206:209], v[20:23]
	v_mfma_f32_16x16x32_bf16 v[12:15], v[154:157], v[214:217], v[12:15]
	v_mfma_f32_16x16x32_bf16 v[4:7], v[162:165], v[214:217], v[4:7]
	v_mfma_f32_16x16x32_bf16 v[56:59], v[166:169], v[182:185], v[56:59]
	v_mfma_f32_16x16x32_bf16 v[48:51], v[174:177], v[182:185], v[48:51]
	v_mfma_f32_16x16x32_bf16 v[40:43], v[166:169], v[194:197], v[40:43]
	v_mfma_f32_16x16x32_bf16 v[32:35], v[174:177], v[194:197], v[32:35]
	v_mfma_f32_16x16x32_bf16 v[24:27], v[166:169], v[202:205], v[24:27]
	v_mfma_f32_16x16x32_bf16 v[16:19], v[174:177], v[202:205], v[16:19]
	v_mfma_f32_16x16x32_bf16 v[8:11], v[166:169], v[210:213], v[8:11]
	v_mfma_f32_16x16x32_bf16 v[0:3], v[174:177], v[210:213], v[0:3]
	v_mfma_f32_16x16x32_bf16 v[56:59], v[170:173], v[190:193], v[56:59]
	v_mfma_f32_16x16x32_bf16 v[48:51], v[178:181], v[190:193], v[48:51]
	v_mfma_f32_16x16x32_bf16 v[40:43], v[170:173], v[198:201], v[40:43]
	v_mfma_f32_16x16x32_bf16 v[32:35], v[178:181], v[198:201], v[32:35]
	v_mfma_f32_16x16x32_bf16 v[24:27], v[170:173], v[206:209], v[24:27]
	v_mfma_f32_16x16x32_bf16 v[16:19], v[178:181], v[206:209], v[16:19]
	v_mfma_f32_16x16x32_bf16 v[8:11], v[170:173], v[214:217], v[8:11]
	v_mfma_f32_16x16x32_bf16 v[0:3], v[178:181], v[214:217], v[0:3]
	s_setprio 0
	s_barrier
	s_add_i32 s94, s94, 2
	s_add_u32 s70, s70, 0x10000
	s_addc_u32 s71, s71, 0
	s_add_u32 s72, s72, 0x10000
	s_addc_u32 s73, s73, 0
	s_cmp_gt_u32 s94, 13
	s_cbranch_scc0 .LBB0_141
	s_and_b64 vcc, exec, s[54:55]
	s_cbranch_vccz .LBB0_144
	s_barrier

; #define PG8_STAGE(bufoff, gbase, voff) do { _Pragma("unroll") for (int _i = 0; _i < 2; ++_i) \
;         __builtin_amdgcn_global_load_lds((const unsigned*)((const char*)(gbase) + (voff)[_i]), (PG8_LAS unsigned*)(lds + (bufoff) + ldsw + _i * 8192), 16, 0, 0); } while (0)
; #define PG8_LDA(dst, b, h) do { _Pragma("unroll") for (int m = 0; m < 4; ++m) _Pragma("unroll") for (int k = 0; k < 2; ++k) dst[m][k] = *(const PG8_LAS bf16x8*)(lds + PG8_SA(b, h) + aoff + m * 2048 + k * 1024); } while (0)
; #define PG8_LDB(dst, b, h) do { _Pragma("unroll") for (int n = 0; n < 2; ++n) _Pragma("unroll") for (int k = 0; k < 2; ++k) dst[n][k] = *(const PG8_LAS bf16x8*)(lds + PG8_SB(b, h) + boff + n * 2048 + k * 1024); } while (0)
; #define PG8_MMA(ai, bj, At, Bt) do { __builtin_amdgcn_s_setprio(1); _Pragma("unroll") for (int m = 0; m < 4; ++m) _Pragma("unroll") for (int n = 0; n < 2; ++n) _Pragma("unroll") for (int k = 0; k < 2; ++k) \
;         acc[ai][bj][m][n] = __builtin_amdgcn_mfma_f32_16x16x32_bf16(Bt[n][k], At[m][k], acc[ai][bj][m][n], 0, 0, 0); __builtin_amdgcn_s_setprio(0); } while (0)
; #define PG8_WAIT_V(n) asm volatile("s_waitcnt vmcnt(" #n ")" ::: "memory")
; #define PG8_WAIT_L(n) asm volatile("s_waitcnt lgkmcnt(" #n ")" ::: "memory")
; #define PG8_BAR __builtin_amdgcn_s_barrier()
; #define PG8_SCHED __builtin_amdgcn_sched_barrier(0)
; template <class Epi, class Sched, bool ALIGN_EPI = false, bool SP2 = false>
; __device__ __forceinline__ void gemm_phase(PG8_LAS unsigned char* lds, const Gemm g, const Sched& S, const Epi& E) {
;     ...
;             PG8_LDB(B0, 0, 0); PG8_LDB(B1, 0, 1); PG8_SCHED; PG8_LDA(At, 0, 0); PG8_STAGE(PG8_SA(1, 1), a1 + hstepA, voffA);
;             PG8_WAIT_V(8); PG8_WAIT_L(0); PG8_BAR; PG8_MMA(0, 0, At, B0); PG8_MMA(0, 1, At, B1); PG8_BAR; PG8_SCHED;
;             PG8_LDA(At, 0, 1); PG8_STAGE(PG8_SB(0, 0), b2, voffB); PG8_STAGE(PG8_SB(0, 1), b2 + hstepB, voffB); PG8_STAGE(PG8_SA(0, 0), a2, voffA);
.LBB0_226:
	ds_read_b128 v[112:115], v210
	ds_read_b128 v[124:127], v210 offset:1024
	ds_read_b128 v[136:139], v210 offset:2048
	ds_read_b128 v[140:143], v210 offset:3072
	ds_read_b128 v[144:147], v211
	ds_read_b128 v[148:151], v211 offset:1024
	ds_read_b128 v[152:155], v211 offset:2048
	ds_read_b128 v[156:159], v211 offset:3072
	s_cmp_eq_u32 s73, 40
	s_cselect_b32 s9, s1, s69
	s_cselect_b32 s8, s0, s68
	s_cselect_b32 s75, s63, s71
	s_cselect_b32 s74, s62, s70
	v_lshl_add_u64 v[208:209], s[68:69], 0, v[184:185]
	v_lshl_add_u64 v[216:217], v[208:209], 0, s[96:97]
	s_add_i32 m0, s15, 0xc000
	ds_read_b128 v[160:163], v212
	ds_read_b128 v[164:167], v212 offset:1024
	ds_read_b128 v[168:171], v212 offset:2048
	ds_read_b128 v[172:175], v212 offset:3072
	ds_read_b128 v[176:179], v212 offset:4096
	ds_read_b128 v[180:183], v212 offset:5120
	ds_read_b128 v[220:223], v212 offset:6144
	ds_read_b128 v[224:227], v212 offset:7168
	global_load_lds_dwordx4 v[216:217], off
	v_lshl_add_u64 v[208:209], v[208:209], 0, s[60:61]
	s_add_i32 m0, s15, 0xe000
	s_nop 0
	global_load_lds_dwordx4 v[208:209], off
	s_waitcnt vmcnt(8)
	s_waitcnt lgkmcnt(0)
	s_barrier
	s_setprio 1
	s_waitcnt lgkmcnt(0)
	v_mfma_f32_16x16x32_bf16 v[132:135], v[112:115], v[160:163], v[132:135]
	v_mfma_f32_16x16x32_bf16 v[128:131], v[136:139], v[160:163], v[128:131]
	v_mfma_f32_16x16x32_bf16 v[108:111], v[112:115], v[168:171], v[108:111]
	v_mfma_f32_16x16x32_bf16 v[104:107], v[136:139], v[168:171], v[104:107]
	v_mfma_f32_16x16x32_bf16 v[92:95], v[112:115], v[176:179], v[92:95]
	v_mfma_f32_16x16x32_bf16 v[88:91], v[136:139], v[176:179], v[88:91]
	v_mfma_f32_16x16x32_bf16 v[76:79], v[112:115], v[220:223], v[76:79]
	v_mfma_f32_16x16x32_bf16 v[72:75], v[136:139], v[220:223], v[72:75]
	v_mfma_f32_16x16x32_bf16 v[132:135], v[124:127], v[164:167], v[132:135]
	v_mfma_f32_16x16x32_bf16 v[128:131], v[140:143], v[164:167], v[128:131]
	v_mfma_f32_16x16x32_bf16 v[108:111], v[124:127], v[172:175], v[108:111]
	v_mfma_f32_16x16x32_bf16 v[104:107], v[140:143], v[172:175], v[104:107]
	v_mfma_f32_16x16x32_bf16 v[92:95], v[124:127], v[180:183], v[92:95]
	v_mfma_f32_16x16x32_bf16 v[88:91], v[140:143], v[180:183], v[88:91]
	v_mfma_f32_16x16x32_bf16 v[76:79], v[124:127], v[224:227], v[76:79]
	v_mfma_f32_16x16x32_bf16 v[72:75], v[140:143], v[224:227], v[72:75]
	v_mfma_f32_16x16x32_bf16 v[120:123], v[144:147], v[160:163], v[120:123]
	v_mfma_f32_16x16x32_bf16 v[116:119], v[152:155], v[160:163], v[116:119]
	v_mfma_f32_16x16x32_bf16 v[100:103], v[144:147], v[168:171], v[100:103]
	v_mfma_f32_16x16x32_bf16 v[96:99], v[152:155], v[168:171], v[96:99]
	v_mfma_f32_16x16x32_bf16 v[84:87], v[144:147], v[176:179], v[84:87]
	v_mfma_f32_16x16x32_bf16 v[80:83], v[152:155], v[176:179], v[80:83]
	v_mfma_f32_16x16x32_bf16 v[68:71], v[144:147], v[220:223], v[68:71]
	v_mfma_f32_16x16x32_bf16 v[64:67], v[152:155], v[220:223], v[64:67]
	v_mfma_f32_16x16x32_bf16 v[120:123], v[148:151], v[164:167], v[120:123]
	v_mfma_f32_16x16x32_bf16 v[116:119], v[156:159], v[164:167], v[116:119]
	v_mfma_f32_16x16x32_bf16 v[100:103], v[148:151], v[172:175], v[100:103]
	v_mfma_f32_16x16x32_bf16 v[96:99], v[156:159], v[172:175], v[96:99]
	v_mfma_f32_16x16x32_bf16 v[84:87], v[148:151], v[180:183], v[84:87]
	v_mfma_f32_16x16x32_bf16 v[80:83], v[156:159], v[180:183], v[80:83]
	v_mfma_f32_16x16x32_bf16 v[68:71], v[148:151], v[224:227], v[68:71]
	v_mfma_f32_16x16x32_bf16 v[64:67], v[156:159], v[224:227], v[64:67]
	s_setprio 0
	s_barrier
	s_add_i32 s33, s89, s14
	v_lshl_add_u64 v[208:209], s[74:75], 0, v[184:185]
	s_mov_b32 m0, s33
	ds_read_b128 v[160:163], v212 offset:16384
	ds_read_b128 v[164:167], v212 offset:17408
	ds_read_b128 v[168:171], v212 offset:18432
	ds_read_b128 v[172:175], v212 offset:19456
	ds_read_b128 v[176:179], v212 offset:20480
	ds_read_b128 v[180:183], v212 offset:21504
	ds_read_b128 v[220:223], v212 offset:22528
	ds_read_b128 v[224:227], v212 offset:23552
	global_load_lds_dwordx4 v[208:209], off
	v_lshl_add_u64 v[216:217], v[208:209], 0, s[30:31]
	s_add_i32 m0, s33, 0x2000
	s_add_i32 s33, s90, s14
	global_load_lds_dwordx4 v[216:217], off
	v_lshl_add_u64 v[216:217], v[208:209], 0, s[34:35]
	s_mov_b32 m0, s33
	s_nop 0
	global_load_lds_dwordx4 v[216:217], off
	v_lshl_add_u64 v[216:217], v[208:209], 0, s[36:37]
	s_add_i32 m0, s33, 0x2000
	s_nop 0
	global_load_lds_dwordx4 v[216:217], off
	v_lshl_add_u64 v[216:217], s[8:9], 0, v[184:185]
	s_mov_b32 m0, s15
	v_lshl_add_u64 v[228:229], v[216:217], 0, s[30:31]
	global_load_lds_dwordx4 v[216:217], off
	s_mov_b32 m0, s17
	s_nop 0
	global_load_lds_dwordx4 v[228:229], off
	s_waitcnt vmcnt(8)
	s_waitcnt lgkmcnt(0)
	s_barrier
; #define PG8_STAGE(bufoff, gbase, voff) do { _Pragma("unroll") for (int _i = 0; _i < 2; ++_i) \
;         __builtin_amdgcn_global_load_lds((const unsigned*)((const char*)(gbase) + (voff)[_i]), (PG8_LAS unsigned*)(lds + (bufoff) + ldsw + _i * 8192), 16, 0, 0); } while (0)
; #define PG8_LDA(dst, b, h) do { _Pragma("unroll") for (int m = 0; m < 4; ++m) _Pragma("unroll") for (int k = 0; k < 2; ++k) dst[m][k] = *(const PG8_LAS bf16x8*)(lds + PG8_SA(b, h) + aoff + m * 2048 + k * 1024); } while (0)
; #define PG8_LDB(dst, b, h) do { _Pragma("unroll") for (int n = 0; n < 2; ++n) _Pragma("unroll") for (int k = 0; k < 2; ++k) dst[n][k] = *(const PG8_LAS bf16x8*)(lds + PG8_SB(b, h) + boff + n * 2048 + k * 1024); } while (0)
; #define PG8_MMA(ai, bj, At, Bt) do { __builtin_amdgcn_s_setprio(1); _Pragma("unroll") for (int m = 0; m < 4; ++m) _Pragma("unroll") for (int n = 0; n < 2; ++n) _Pragma("unroll") for (int k = 0; k < 2; ++k) \
;         acc[ai][bj][m][n] = __builtin_amdgcn_mfma_f32_16x16x32_bf16(Bt[n][k], At[m][k], acc[ai][bj][m][n], 0, 0, 0); __builtin_amdgcn_s_setprio(0); } while (0)
; #define PG8_WAIT_V(n) asm volatile("s_waitcnt vmcnt(" #n ")" ::: "memory")
; #define PG8_WAIT_L(n) asm volatile("s_waitcnt lgkmcnt(" #n ")" ::: "memory")
; #define PG8_BAR __builtin_amdgcn_s_barrier()
; #define PG8_SCHED __builtin_amdgcn_sched_barrier(0)
; template <class Epi, class Sched, bool ALIGN_EPI = false, bool SP2 = false>
; __device__ __forceinline__ void gemm_phase(PG8_LAS unsigned char* lds, const Gemm g, const Sched& S, const Epi& E) {
;     ...
;             PG8_WAIT_V(8); PG8_WAIT_L(0); PG8_BAR; PG8_MMA(1, 0, At, B0); PG8_MMA(1, 1, At, B1); PG8_BAR; PG8_SCHED;
;             PG8_LDB(B0, 1, 0); PG8_LDB(B1, 1, 1); PG8_SCHED; PG8_LDA(At, 1, 0); PG8_STAGE(PG8_SA(0, 1), a2 + hstepA, voffA);
;             PG8_WAIT_V(8); PG8_WAIT_L(0); PG8_BAR; PG8_MMA(0, 0, At, B0); PG8_MMA(0, 1, At, B1); PG8_BAR; PG8_SCHED;
	s_setprio 1
	s_waitcnt lgkmcnt(0)
	v_mfma_f32_16x16x32_bf16 v[60:63], v[112:115], v[160:163], v[60:63]
	v_mfma_f32_16x16x32_bf16 v[56:59], v[136:139], v[160:163], v[56:59]
	v_mfma_f32_16x16x32_bf16 v[44:47], v[112:115], v[168:171], v[44:47]
	v_mfma_f32_16x16x32_bf16 v[40:43], v[136:139], v[168:171], v[40:43]
	v_mfma_f32_16x16x32_bf16 v[28:31], v[112:115], v[176:179], v[28:31]
	v_mfma_f32_16x16x32_bf16 v[24:27], v[136:139], v[176:179], v[24:27]
	v_mfma_f32_16x16x32_bf16 v[12:15], v[112:115], v[220:223], v[12:15]
	v_mfma_f32_16x16x32_bf16 v[8:11], v[136:139], v[220:223], v[8:11]
	v_mfma_f32_16x16x32_bf16 v[60:63], v[124:127], v[164:167], v[60:63]
	v_mfma_f32_16x16x32_bf16 v[56:59], v[140:143], v[164:167], v[56:59]
	v_mfma_f32_16x16x32_bf16 v[44:47], v[124:127], v[172:175], v[44:47]
	v_mfma_f32_16x16x32_bf16 v[40:43], v[140:143], v[172:175], v[40:43]
	v_mfma_f32_16x16x32_bf16 v[28:31], v[124:127], v[180:183], v[28:31]
	v_mfma_f32_16x16x32_bf16 v[24:27], v[140:143], v[180:183], v[24:27]
	v_mfma_f32_16x16x32_bf16 v[12:15], v[124:127], v[224:227], v[12:15]
	v_mfma_f32_16x16x32_bf16 v[8:11], v[140:143], v[224:227], v[8:11]
	v_mfma_f32_16x16x32_bf16 v[52:55], v[144:147], v[160:163], v[52:55]
	v_mfma_f32_16x16x32_bf16 v[48:51], v[152:155], v[160:163], v[48:51]
	v_mfma_f32_16x16x32_bf16 v[36:39], v[144:147], v[168:171], v[36:39]
	v_mfma_f32_16x16x32_bf16 v[32:35], v[152:155], v[168:171], v[32:35]
	v_mfma_f32_16x16x32_bf16 v[20:23], v[144:147], v[176:179], v[20:23]
	v_mfma_f32_16x16x32_bf16 v[16:19], v[152:155], v[176:179], v[16:19]
	v_mfma_f32_16x16x32_bf16 v[4:7], v[144:147], v[220:223], v[4:7]
	v_mfma_f32_16x16x32_bf16 v[0:3], v[152:155], v[220:223], v[0:3]
	v_mfma_f32_16x16x32_bf16 v[52:55], v[148:151], v[164:167], v[52:55]
	v_mfma_f32_16x16x32_bf16 v[48:51], v[156:159], v[164:167], v[48:51]
	v_mfma_f32_16x16x32_bf16 v[36:39], v[148:151], v[172:175], v[36:39]
	v_mfma_f32_16x16x32_bf16 v[32:35], v[156:159], v[172:175], v[32:35]
	v_mfma_f32_16x16x32_bf16 v[20:23], v[148:151], v[180:183], v[20:23]
	v_mfma_f32_16x16x32_bf16 v[16:19], v[156:159], v[180:183], v[16:19]
	v_mfma_f32_16x16x32_bf16 v[4:7], v[148:151], v[224:227], v[4:7]
	v_mfma_f32_16x16x32_bf16 v[0:3], v[156:159], v[224:227], v[0:3]
	s_setprio 0
	s_barrier
	ds_read_b128 v[112:115], v213
	ds_read_b128 v[124:127], v213 offset:1024
	ds_read_b128 v[136:139], v213 offset:2048
	ds_read_b128 v[140:143], v213 offset:3072
	ds_read_b128 v[144:147], v214
	ds_read_b128 v[148:151], v214 offset:1024
	ds_read_b128 v[152:155], v214 offset:2048
	ds_read_b128 v[156:159], v214 offset:3072
	s_mov_b32 m0, s18
	v_lshl_add_u64 v[228:229], v[216:217], 0, s[34:35]
	ds_read_b128 v[160:163], v212 offset:32768
	ds_read_b128 v[164:167], v212 offset:33792
	ds_read_b128 v[168:171], v212 offset:34816
	ds_read_b128 v[172:175], v212 offset:35840
	ds_read_b128 v[176:179], v212 offset:36864
	ds_read_b128 v[180:183], v212 offset:37888
	ds_read_b128 v[220:223], v212 offset:38912
	ds_read_b128 v[224:227], v212 offset:39936
	global_load_lds_dwordx4 v[228:229], off
	v_lshl_add_u64 v[228:229], v[216:217], 0, s[36:37]
	s_mov_b32 m0, s19
	s_nop 0
	global_load_lds_dwordx4 v[228:229], off
	s_waitcnt vmcnt(8)
	s_waitcnt lgkmcnt(0)
	s_barrier
	s_setprio 1
	s_waitcnt lgkmcnt(0)
	v_mfma_f32_16x16x32_bf16 v[132:135], v[112:115], v[160:163], v[132:135]
	v_mfma_f32_16x16x32_bf16 v[128:131], v[136:139], v[160:163], v[128:131]
	v_mfma_f32_16x16x32_bf16 v[108:111], v[112:115], v[168:171], v[108:111]
	v_mfma_f32_16x16x32_bf16 v[104:107], v[136:139], v[168:171], v[104:107]
	v_mfma_f32_16x16x32_bf16 v[92:95], v[112:115], v[176:179], v[92:95]
	v_mfma_f32_16x16x32_bf16 v[88:91], v[136:139], v[176:179], v[88:91]
	v_mfma_f32_16x16x32_bf16 v[76:79], v[112:115], v[220:223], v[76:79]
	v_mfma_f32_16x16x32_bf16 v[72:75], v[136:139], v[220:223], v[72:75]
	v_mfma_f32_16x16x32_bf16 v[132:135], v[124:127], v[164:167], v[132:135]
	v_mfma_f32_16x16x32_bf16 v[128:131], v[140:143], v[164:167], v[128:131]
	v_mfma_f32_16x16x32_bf16 v[108:111], v[124:127], v[172:175], v[108:111]
	v_mfma_f32_16x16x32_bf16 v[104:107], v[140:143], v[172:175], v[104:107]
	v_mfma_f32_16x16x32_bf16 v[92:95], v[124:127], v[180:183], v[92:95]
	v_mfma_f32_16x16x32_bf16 v[88:91], v[140:143], v[180:183], v[88:91]
	v_mfma_f32_16x16x32_bf16 v[76:79], v[124:127], v[224:227], v[76:79]
	v_mfma_f32_16x16x32_bf16 v[72:75], v[140:143], v[224:227], v[72:75]
	v_mfma_f32_16x16x32_bf16 v[120:123], v[144:147], v[160:163], v[120:123]
	v_mfma_f32_16x16x32_bf16 v[116:119], v[152:155], v[160:163], v[116:119]
	v_mfma_f32_16x16x32_bf16 v[100:103], v[144:147], v[168:171], v[100:103]
	v_mfma_f32_16x16x32_bf16 v[96:99], v[152:155], v[168:171], v[96:99]
	v_mfma_f32_16x16x32_bf16 v[84:87], v[144:147], v[176:179], v[84:87]
	v_mfma_f32_16x16x32_bf16 v[80:83], v[152:155], v[176:179], v[80:83]
	v_mfma_f32_16x16x32_bf16 v[68:71], v[144:147], v[220:223], v[68:71]
	v_mfma_f32_16x16x32_bf16 v[64:67], v[152:155], v[220:223], v[64:67]
	v_mfma_f32_16x16x32_bf16 v[120:123], v[148:151], v[164:167], v[120:123]
	v_mfma_f32_16x16x32_bf16 v[116:119], v[156:159], v[164:167], v[116:119]
	v_mfma_f32_16x16x32_bf16 v[100:103], v[148:151], v[172:175], v[100:103]
	v_mfma_f32_16x16x32_bf16 v[96:99], v[156:159], v[172:175], v[96:99]
	v_mfma_f32_16x16x32_bf16 v[84:87], v[148:151], v[180:183], v[84:87]
	v_mfma_f32_16x16x32_bf16 v[80:83], v[156:159], v[180:183], v[80:83]
	v_mfma_f32_16x16x32_bf16 v[68:71], v[148:151], v[224:227], v[68:71]
	v_mfma_f32_16x16x32_bf16 v[64:67], v[156:159], v[224:227], v[64:67]
	s_setprio 0
	s_barrier
; #define PG8_STAGE(bufoff, gbase, voff) do { _Pragma("unroll") for (int _i = 0; _i < 2; ++_i) \
;         __builtin_amdgcn_global_load_lds((const unsigned*)((const char*)(gbase) + (voff)[_i]), (PG8_LAS unsigned*)(lds + (bufoff) + ldsw + _i * 8192), 16, 0, 0); } while (0)
; #define PG8_LDA(dst, b, h) do { _Pragma("unroll") for (int m = 0; m < 4; ++m) _Pragma("unroll") for (int k = 0; k < 2; ++k) dst[m][k] = *(const PG8_LAS bf16x8*)(lds + PG8_SA(b, h) + aoff + m * 2048 + k * 1024); } while (0)
; #define PG8_MMA(ai, bj, At, Bt) do { __builtin_amdgcn_s_setprio(1); _Pragma("unroll") for (int m = 0; m < 4; ++m) _Pragma("unroll") for (int n = 0; n < 2; ++n) _Pragma("unroll") for (int k = 0; k < 2; ++k) \
;         acc[ai][bj][m][n] = __builtin_amdgcn_mfma_f32_16x16x32_bf16(Bt[n][k], At[m][k], acc[ai][bj][m][n], 0, 0, 0); __builtin_amdgcn_s_setprio(0); } while (0)
; #define PG8_WAIT_V(n) asm volatile("s_waitcnt vmcnt(" #n ")" ::: "memory")
; #define PG8_WAIT_L(n) asm volatile("s_waitcnt lgkmcnt(" #n ")" ::: "memory")
; #define PG8_BAR __builtin_amdgcn_s_barrier()
; #define PG8_SCHED __builtin_amdgcn_sched_barrier(0)
; template <class Epi, class Sched, bool ALIGN_EPI = false, bool SP2 = false>
; __device__ __forceinline__ void gemm_phase(PG8_LAS unsigned char* lds, const Gemm g, const Sched& S, const Epi& E) {
;     ...
;         for (int t = 0; t < nt; t += 2) {
;             const bool last = (t == nt - 2);
;             const char* a1 = cA + (size_t)(t + 1) * kstepA;
;             const char* a2 = last ? nA : cA + (size_t)(t + 2) * kstepA; const char* b2 = last ? nB : cB + (size_t)(t + 2) * kstep;
;             const char* a3 = a2 + kstepA; const char* b3 = b2 + kstep;
;     ...
;             PG8_LDA(At, 1, 1); PG8_STAGE(PG8_SB(1, 0), b3, voffB); PG8_STAGE(PG8_SB(1, 1), b3 + hstepB, voffB); PG8_STAGE(PG8_SA(1, 0), a3, voffA);
;             PG8_WAIT_V(8); PG8_WAIT_L(0); PG8_BAR; PG8_MMA(1, 0, At, B0); PG8_MMA(1, 1, At, B1); PG8_BAR; PG8_SCHED;
	s_add_i32 s8, s91, s14
	v_lshl_add_u64 v[228:229], v[208:209], 0, s[38:39]
	s_mov_b32 m0, s8
	ds_read_b128 v[160:163], v212 offset:49152
	ds_read_b128 v[164:167], v212 offset:50176
	ds_read_b128 v[168:171], v212 offset:51200
	ds_read_b128 v[172:175], v212 offset:52224
	ds_read_b128 v[176:179], v212 offset:53248
	ds_read_b128 v[180:183], v212 offset:54272
	ds_read_b128 v[220:223], v212 offset:55296
	ds_read_b128 v[224:227], v212 offset:56320
	global_load_lds_dwordx4 v[228:229], off
	v_lshl_add_u64 v[228:229], v[208:209], 0, s[40:41]
	s_add_i32 m0, s8, 0x2000
	s_add_i32 s8, s92, s14
	global_load_lds_dwordx4 v[228:229], off
	v_lshl_add_u64 v[228:229], v[208:209], 0, s[52:53]
	s_mov_b32 m0, s8
	v_lshl_add_u64 v[208:209], v[208:209], 0, s[54:55]
	global_load_lds_dwordx4 v[228:229], off
	s_add_i32 m0, s8, 0x2000
	s_nop 0
	global_load_lds_dwordx4 v[208:209], off
	v_lshl_add_u64 v[208:209], v[216:217], 0, s[38:39]
	s_mov_b32 m0, s78
	s_nop 0
	global_load_lds_dwordx4 v[208:209], off
	v_lshl_add_u64 v[208:209], v[216:217], 0, s[40:41]
	s_mov_b32 m0, s79
	s_nop 0
	global_load_lds_dwordx4 v[208:209], off
	s_waitcnt vmcnt(8)
	s_waitcnt lgkmcnt(0)
	s_barrier
	s_setprio 1
	s_waitcnt lgkmcnt(0)
	v_mfma_f32_16x16x32_bf16 v[60:63], v[112:115], v[160:163], v[60:63]
	v_mfma_f32_16x16x32_bf16 v[56:59], v[136:139], v[160:163], v[56:59]
	v_mfma_f32_16x16x32_bf16 v[44:47], v[112:115], v[168:171], v[44:47]
	v_mfma_f32_16x16x32_bf16 v[40:43], v[136:139], v[168:171], v[40:43]
	v_mfma_f32_16x16x32_bf16 v[28:31], v[112:115], v[176:179], v[28:31]
	v_mfma_f32_16x16x32_bf16 v[24:27], v[136:139], v[176:179], v[24:27]
	v_mfma_f32_16x16x32_bf16 v[12:15], v[112:115], v[220:223], v[12:15]
	v_mfma_f32_16x16x32_bf16 v[8:11], v[136:139], v[220:223], v[8:11]
	v_mfma_f32_16x16x32_bf16 v[60:63], v[124:127], v[164:167], v[60:63]
	v_mfma_f32_16x16x32_bf16 v[56:59], v[140:143], v[164:167], v[56:59]
	v_mfma_f32_16x16x32_bf16 v[44:47], v[124:127], v[172:175], v[44:47]
	v_mfma_f32_16x16x32_bf16 v[40:43], v[140:143], v[172:175], v[40:43]
	v_mfma_f32_16x16x32_bf16 v[28:31], v[124:127], v[180:183], v[28:31]
	v_mfma_f32_16x16x32_bf16 v[24:27], v[140:143], v[180:183], v[24:27]
	v_mfma_f32_16x16x32_bf16 v[12:15], v[124:127], v[224:227], v[12:15]
	v_mfma_f32_16x16x32_bf16 v[8:11], v[140:143], v[224:227], v[8:11]
	v_mfma_f32_16x16x32_bf16 v[52:55], v[144:147], v[160:163], v[52:55]
	v_mfma_f32_16x16x32_bf16 v[48:51], v[152:155], v[160:163], v[48:51]
	v_mfma_f32_16x16x32_bf16 v[36:39], v[144:147], v[168:171], v[36:39]
	v_mfma_f32_16x16x32_bf16 v[32:35], v[152:155], v[168:171], v[32:35]
	v_mfma_f32_16x16x32_bf16 v[20:23], v[144:147], v[176:179], v[20:23]
	v_mfma_f32_16x16x32_bf16 v[16:19], v[152:155], v[176:179], v[16:19]
	v_mfma_f32_16x16x32_bf16 v[4:7], v[144:147], v[220:223], v[4:7]
	v_mfma_f32_16x16x32_bf16 v[0:3], v[152:155], v[220:223], v[0:3]
	v_mfma_f32_16x16x32_bf16 v[52:55], v[148:151], v[164:167], v[52:55]
	v_mfma_f32_16x16x32_bf16 v[48:51], v[156:159], v[164:167], v[48:51]
	v_mfma_f32_16x16x32_bf16 v[36:39], v[148:151], v[172:175], v[36:39]
	v_mfma_f32_16x16x32_bf16 v[32:35], v[156:159], v[172:175], v[32:35]
	v_mfma_f32_16x16x32_bf16 v[20:23], v[148:151], v[180:183], v[20:23]
	v_mfma_f32_16x16x32_bf16 v[16:19], v[156:159], v[180:183], v[16:19]
	v_mfma_f32_16x16x32_bf16 v[4:7], v[148:151], v[224:227], v[4:7]
	v_mfma_f32_16x16x32_bf16 v[0:3], v[156:159], v[224:227], v[0:3]
	s_setprio 0
	s_barrier
	s_add_i32 s73, s73, 2
	s_add_u32 s68, s68, 0x10000
	s_addc_u32 s69, s69, 0
	s_add_u32 s70, s70, 0x10000
	s_addc_u32 s71, s71, 0
	s_cmp_gt_u32 s73, 41
	s_cbranch_scc0 .LBB0_226
	s_and_b64 vcc, exec, s[58:59]
	s_cbranch_vccz .LBB0_229
	s_barrier

; #define PG8_STAGE(bufoff, gbase, voff) do { _Pragma("unroll") for (int _i = 0; _i < 2; ++_i) \
;         __builtin_amdgcn_global_load_lds((const unsigned*)((const char*)(gbase) + (voff)[_i]), (PG8_LAS unsigned*)(lds + (bufoff) + ldsw + _i * 8192), 16, 0, 0); } while (0)
; #define PG8_LDA(dst, b, h) do { _Pragma("unroll") for (int m = 0; m < 4; ++m) _Pragma("unroll") for (int k = 0; k < 2; ++k) dst[m][k] = *(const PG8_LAS bf16x8*)(lds + PG8_SA(b, h) + aoff + m * 2048 + k * 1024); } while (0)
; #define PG8_LDB(dst, b, h) do { _Pragma("unroll") for (int n = 0; n < 2; ++n) _Pragma("unroll") for (int k = 0; k < 2; ++k) dst[n][k] = *(const PG8_LAS bf16x8*)(lds + PG8_SB(b, h) + boff + n * 2048 + k * 1024); } while (0)
; #define PG8_MMA(ai, bj, At, Bt) do { __builtin_amdgcn_s_setprio(1); _Pragma("unroll") for (int m = 0; m < 4; ++m) _Pragma("unroll") for (int n = 0; n < 2; ++n) _Pragma("unroll") for (int k = 0; k < 2; ++k) \
;         acc[ai][bj][m][n] = __builtin_amdgcn_mfma_f32_16x16x32_bf16(Bt[n][k], At[m][k], acc[ai][bj][m][n], 0, 0, 0); __builtin_amdgcn_s_setprio(0); } while (0)
; #define PG8_WAIT_V(n) asm volatile("s_waitcnt vmcnt(" #n ")" ::: "memory")
; #define PG8_WAIT_L(n) asm volatile("s_waitcnt lgkmcnt(" #n ")" ::: "memory")
; #define PG8_BAR __builtin_amdgcn_s_barrier()
; #define PG8_SCHED __builtin_amdgcn_sched_barrier(0)
; template <class Epi, class Sched, bool ALIGN_EPI = false, bool SP2 = false>
; __device__ __forceinline__ void gemm_phase(PG8_LAS unsigned char* lds, const Gemm g, const Sched& S, const Epi& E) {
;     ...
;             PG8_LDB(B0, 0, 0); PG8_LDB(B1, 0, 1); PG8_SCHED; PG8_LDA(At, 0, 0); PG8_STAGE(PG8_SA(1, 1), a1 + hstepA, voffA);
;             PG8_WAIT_V(8); PG8_WAIT_L(0); PG8_BAR; PG8_MMA(0, 0, At, B0); PG8_MMA(0, 1, At, B1); PG8_BAR; PG8_SCHED;
;             PG8_LDA(At, 0, 1); PG8_STAGE(PG8_SB(0, 0), b2, voffB); PG8_STAGE(PG8_SB(0, 1), b2 + hstepB, voffB); PG8_STAGE(PG8_SA(0, 0), a2, voffA);
.LBB0_315:
	ds_read_b128 v[140:143], v159
	ds_read_b128 v[144:147], v159 offset:1024
	ds_read_b128 v[148:151], v159 offset:2048
	ds_read_b128 v[166:169], v159 offset:3072
	ds_read_b128 v[170:173], v160
	ds_read_b128 v[174:177], v160 offset:1024
	ds_read_b128 v[178:181], v160 offset:2048
	ds_read_b128 v[182:185], v160 offset:3072
	s_cmp_eq_u32 s76, 12
	s_cselect_b32 s9, s7, s5
	s_cselect_b32 s8, s63, s4
	s_cselect_b32 vcc_hi, s61, s75
	s_cselect_b32 vcc_lo, s73, s74
	s_movk_i32 s78, 0xc000
	v_lshl_add_u64 v[2:3], s[4:5], 0, v[132:133]
	s_mov_b32 s79, -1
	v_lshl_add_u64 v[152:153], v[2:3], 0, s[78:79]
	s_movk_i32 s78, 0xe000
	s_add_i32 m0, s90, 0xc000
	s_mov_b32 s79, -1
	ds_read_b128 v[190:193], v161
	ds_read_b128 v[194:197], v161 offset:1024
	ds_read_b128 v[198:201], v161 offset:2048
	ds_read_b128 v[202:205], v161 offset:3072
	ds_read_b128 v[206:209], v161 offset:4096
	ds_read_b128 v[210:213], v161 offset:5120
	ds_read_b128 v[214:217], v161 offset:6144
	ds_read_b128 v[220:223], v161 offset:7168
	global_load_lds_dwordx4 v[152:153], off
	v_lshl_add_u64 v[2:3], v[2:3], 0, s[78:79]
	s_add_i32 m0, s90, 0xe000
	s_nop 0
	global_load_lds_dwordx4 v[2:3], off
	s_waitcnt vmcnt(8)
	s_waitcnt lgkmcnt(0)
	s_barrier
	s_setprio 1
	s_waitcnt lgkmcnt(0)
	v_mfma_f32_16x16x32_bf16 v[128:131], v[140:143], v[190:193], v[128:131]
	v_mfma_f32_16x16x32_bf16 v[124:127], v[148:151], v[190:193], v[124:127]
	v_mfma_f32_16x16x32_bf16 v[112:115], v[140:143], v[198:201], v[112:115]
	v_mfma_f32_16x16x32_bf16 v[108:111], v[148:151], v[198:201], v[108:111]
	v_mfma_f32_16x16x32_bf16 v[96:99], v[140:143], v[206:209], v[96:99]
	v_mfma_f32_16x16x32_bf16 v[92:95], v[148:151], v[206:209], v[92:95]
	v_mfma_f32_16x16x32_bf16 v[80:83], v[140:143], v[214:217], v[80:83]
	v_mfma_f32_16x16x32_bf16 v[76:79], v[148:151], v[214:217], v[76:79]
	v_mfma_f32_16x16x32_bf16 v[128:131], v[144:147], v[194:197], v[128:131]
	v_mfma_f32_16x16x32_bf16 v[124:127], v[166:169], v[194:197], v[124:127]
	v_mfma_f32_16x16x32_bf16 v[112:115], v[144:147], v[202:205], v[112:115]
	v_mfma_f32_16x16x32_bf16 v[108:111], v[166:169], v[202:205], v[108:111]
	v_mfma_f32_16x16x32_bf16 v[96:99], v[144:147], v[210:213], v[96:99]
	v_mfma_f32_16x16x32_bf16 v[92:95], v[166:169], v[210:213], v[92:95]
	v_mfma_f32_16x16x32_bf16 v[80:83], v[144:147], v[220:223], v[80:83]
	v_mfma_f32_16x16x32_bf16 v[76:79], v[166:169], v[220:223], v[76:79]
	v_mfma_f32_16x16x32_bf16 v[120:123], v[170:173], v[190:193], v[120:123]
	v_mfma_f32_16x16x32_bf16 v[116:119], v[178:181], v[190:193], v[116:119]
	v_mfma_f32_16x16x32_bf16 v[104:107], v[170:173], v[198:201], v[104:107]
	v_mfma_f32_16x16x32_bf16 v[100:103], v[178:181], v[198:201], v[100:103]
	v_mfma_f32_16x16x32_bf16 v[88:91], v[170:173], v[206:209], v[88:91]
	v_mfma_f32_16x16x32_bf16 v[84:87], v[178:181], v[206:209], v[84:87]
	v_mfma_f32_16x16x32_bf16 v[72:75], v[170:173], v[214:217], v[72:75]
	v_mfma_f32_16x16x32_bf16 v[68:71], v[178:181], v[214:217], v[68:71]
	v_mfma_f32_16x16x32_bf16 v[120:123], v[174:177], v[194:197], v[120:123]
	v_mfma_f32_16x16x32_bf16 v[116:119], v[182:185], v[194:197], v[116:119]
	v_mfma_f32_16x16x32_bf16 v[104:107], v[174:177], v[202:205], v[104:107]
	v_mfma_f32_16x16x32_bf16 v[100:103], v[182:185], v[202:205], v[100:103]
	v_mfma_f32_16x16x32_bf16 v[88:91], v[174:177], v[210:213], v[88:91]
	v_mfma_f32_16x16x32_bf16 v[84:87], v[182:185], v[210:213], v[84:87]
	v_mfma_f32_16x16x32_bf16 v[72:75], v[174:177], v[220:223], v[72:75]
	v_mfma_f32_16x16x32_bf16 v[68:71], v[182:185], v[220:223], v[68:71]
	s_setprio 0
	s_barrier
	s_add_i32 s77, s15, s89
	v_lshl_add_u64 v[152:153], vcc, 0, v[132:133]
	s_mov_b32 m0, s77
	ds_read_b128 v[190:193], v161 offset:16384
	ds_read_b128 v[194:197], v161 offset:17408
	ds_read_b128 v[198:201], v161 offset:18432
	ds_read_b128 v[202:205], v161 offset:19456
	ds_read_b128 v[206:209], v161 offset:20480
	ds_read_b128 v[210:213], v161 offset:21504
	ds_read_b128 v[214:217], v161 offset:22528
	ds_read_b128 v[220:223], v161 offset:23552
	global_load_lds_dwordx4 v[152:153], off
	v_lshl_add_u64 v[2:3], v[152:153], 0, s[30:31]
	s_add_i32 m0, s77, 0x2000
	s_add_i32 s77, s18, s89
	global_load_lds_dwordx4 v[2:3], off
	v_lshl_add_u64 v[2:3], v[152:153], 0, s[34:35]
	s_mov_b32 m0, s77
	v_lshl_add_u64 v[186:187], s[8:9], 0, v[132:133]
	global_load_lds_dwordx4 v[2:3], off
	v_lshl_add_u64 v[2:3], v[152:153], 0, s[36:37]
	s_add_i32 m0, s77, 0x2000
	s_nop 0
	global_load_lds_dwordx4 v[2:3], off
	s_mov_b32 m0, s90
	v_lshl_add_u64 v[2:3], v[186:187], 0, s[30:31]
	global_load_lds_dwordx4 v[186:187], off
	s_mov_b32 m0, s91
	s_nop 0
	global_load_lds_dwordx4 v[2:3], off
	s_waitcnt vmcnt(8)
	s_waitcnt lgkmcnt(0)
	s_barrier
; #define PG8_STAGE(bufoff, gbase, voff) do { _Pragma("unroll") for (int _i = 0; _i < 2; ++_i) \
;         __builtin_amdgcn_global_load_lds((const unsigned*)((const char*)(gbase) + (voff)[_i]), (PG8_LAS unsigned*)(lds + (bufoff) + ldsw + _i * 8192), 16, 0, 0); } while (0)
; #define PG8_LDA(dst, b, h) do { _Pragma("unroll") for (int m = 0; m < 4; ++m) _Pragma("unroll") for (int k = 0; k < 2; ++k) dst[m][k] = *(const PG8_LAS bf16x8*)(lds + PG8_SA(b, h) + aoff + m * 2048 + k * 1024); } while (0)
; #define PG8_LDB(dst, b, h) do { _Pragma("unroll") for (int n = 0; n < 2; ++n) _Pragma("unroll") for (int k = 0; k < 2; ++k) dst[n][k] = *(const PG8_LAS bf16x8*)(lds + PG8_SB(b, h) + boff + n * 2048 + k * 1024); } while (0)
; #define PG8_MMA(ai, bj, At, Bt) do { __builtin_amdgcn_s_setprio(1); _Pragma("unroll") for (int m = 0; m < 4; ++m) _Pragma("unroll") for (int n = 0; n < 2; ++n) _Pragma("unroll") for (int k = 0; k < 2; ++k) \
;         acc[ai][bj][m][n] = __builtin_amdgcn_mfma_f32_16x16x32_bf16(Bt[n][k], At[m][k], acc[ai][bj][m][n], 0, 0, 0); __builtin_amdgcn_s_setprio(0); } while (0)
; #define PG8_WAIT_V(n) asm volatile("s_waitcnt vmcnt(" #n ")" ::: "memory")
; #define PG8_WAIT_L(n) asm volatile("s_waitcnt lgkmcnt(" #n ")" ::: "memory")
; #define PG8_BAR __builtin_amdgcn_s_barrier()
; #define PG8_SCHED __builtin_amdgcn_sched_barrier(0)
; template <class Epi, class Sched, bool ALIGN_EPI = false, bool SP2 = false>
; __device__ __forceinline__ void gemm_phase(PG8_LAS unsigned char* lds, const Gemm g, const Sched& S, const Epi& E) {
;     ...
;             PG8_WAIT_V(8); PG8_WAIT_L(0); PG8_BAR; PG8_MMA(1, 0, At, B0); PG8_MMA(1, 1, At, B1); PG8_BAR; PG8_SCHED;
;             PG8_LDB(B0, 1, 0); PG8_LDB(B1, 1, 1); PG8_SCHED; PG8_LDA(At, 1, 0); PG8_STAGE(PG8_SA(0, 1), a2 + hstepA, voffA);
;             PG8_WAIT_V(8); PG8_WAIT_L(0); PG8_BAR; PG8_MMA(0, 0, At, B0); PG8_MMA(0, 1, At, B1); PG8_BAR; PG8_SCHED;
	s_setprio 1
	s_waitcnt lgkmcnt(0)
	v_mfma_f32_16x16x32_bf16 v[64:67], v[140:143], v[190:193], v[64:67]
	v_mfma_f32_16x16x32_bf16 v[60:63], v[148:151], v[190:193], v[60:63]
	v_mfma_f32_16x16x32_bf16 v[48:51], v[140:143], v[198:201], v[48:51]
	v_mfma_f32_16x16x32_bf16 v[44:47], v[148:151], v[198:201], v[44:47]
	v_mfma_f32_16x16x32_bf16 v[32:35], v[140:143], v[206:209], v[32:35]
	v_mfma_f32_16x16x32_bf16 v[28:31], v[148:151], v[206:209], v[28:31]
	v_mfma_f32_16x16x32_bf16 v[16:19], v[140:143], v[214:217], v[16:19]
	v_mfma_f32_16x16x32_bf16 v[12:15], v[148:151], v[214:217], v[12:15]
	v_mfma_f32_16x16x32_bf16 v[64:67], v[144:147], v[194:197], v[64:67]
	v_mfma_f32_16x16x32_bf16 v[60:63], v[166:169], v[194:197], v[60:63]
	v_mfma_f32_16x16x32_bf16 v[48:51], v[144:147], v[202:205], v[48:51]
	v_mfma_f32_16x16x32_bf16 v[44:47], v[166:169], v[202:205], v[44:47]
	v_mfma_f32_16x16x32_bf16 v[32:35], v[144:147], v[210:213], v[32:35]
	v_mfma_f32_16x16x32_bf16 v[28:31], v[166:169], v[210:213], v[28:31]
	v_mfma_f32_16x16x32_bf16 v[16:19], v[144:147], v[220:223], v[16:19]
	v_mfma_f32_16x16x32_bf16 v[12:15], v[166:169], v[220:223], v[12:15]
	v_mfma_f32_16x16x32_bf16 v[56:59], v[170:173], v[190:193], v[56:59]
	v_mfma_f32_16x16x32_bf16 v[52:55], v[178:181], v[190:193], v[52:55]
	v_mfma_f32_16x16x32_bf16 v[40:43], v[170:173], v[198:201], v[40:43]
	v_mfma_f32_16x16x32_bf16 v[36:39], v[178:181], v[198:201], v[36:39]
	v_mfma_f32_16x16x32_bf16 v[24:27], v[170:173], v[206:209], v[24:27]
	v_mfma_f32_16x16x32_bf16 v[20:23], v[178:181], v[206:209], v[20:23]
	v_mfma_f32_16x16x32_bf16 v[8:11], v[170:173], v[214:217], v[8:11]
	v_mfma_f32_16x16x32_bf16 v[2:5], v[178:181], v[214:217], v[4:7]
	v_mfma_f32_16x16x32_bf16 v[56:59], v[174:177], v[194:197], v[56:59]
	v_mfma_f32_16x16x32_bf16 v[52:55], v[182:185], v[194:197], v[52:55]
	v_mfma_f32_16x16x32_bf16 v[40:43], v[174:177], v[202:205], v[40:43]
	v_mfma_f32_16x16x32_bf16 v[36:39], v[182:185], v[202:205], v[36:39]
	v_mfma_f32_16x16x32_bf16 v[24:27], v[174:177], v[210:213], v[24:27]
	v_mfma_f32_16x16x32_bf16 v[20:23], v[182:185], v[210:213], v[20:23]
	v_mfma_f32_16x16x32_bf16 v[8:11], v[174:177], v[220:223], v[8:11]
	v_mfma_f32_16x16x32_bf16 v[2:5], v[182:185], v[220:223], v[2:5]
	s_setprio 0
	s_barrier
	ds_read_b128 v[140:143], v162
	ds_read_b128 v[144:147], v162 offset:1024
	ds_read_b128 v[148:151], v162 offset:2048
	ds_read_b128 v[166:169], v162 offset:3072
	ds_read_b128 v[170:173], v163
	ds_read_b128 v[174:177], v163 offset:1024
	ds_read_b128 v[178:181], v163 offset:2048
	ds_read_b128 v[182:185], v163 offset:3072
	s_mov_b32 m0, s92
	v_lshl_add_u64 v[6:7], v[186:187], 0, s[34:35]
	ds_read_b128 v[190:193], v161 offset:32768
	ds_read_b128 v[194:197], v161 offset:33792
	ds_read_b128 v[198:201], v161 offset:34816
	ds_read_b128 v[202:205], v161 offset:35840
	ds_read_b128 v[206:209], v161 offset:36864
	ds_read_b128 v[210:213], v161 offset:37888
	ds_read_b128 v[214:217], v161 offset:38912
	ds_read_b128 v[220:223], v161 offset:39936
	global_load_lds_dwordx4 v[6:7], off
	v_lshl_add_u64 v[6:7], v[186:187], 0, s[36:37]
	s_mov_b32 m0, s93
	s_nop 0
	global_load_lds_dwordx4 v[6:7], off
	s_waitcnt vmcnt(8)
	s_waitcnt lgkmcnt(0)
	s_barrier
	s_setprio 1
	s_waitcnt lgkmcnt(0)
	v_mfma_f32_16x16x32_bf16 v[128:131], v[140:143], v[190:193], v[128:131]
	v_mfma_f32_16x16x32_bf16 v[124:127], v[148:151], v[190:193], v[124:127]
	v_mfma_f32_16x16x32_bf16 v[112:115], v[140:143], v[198:201], v[112:115]
	v_mfma_f32_16x16x32_bf16 v[108:111], v[148:151], v[198:201], v[108:111]
	v_mfma_f32_16x16x32_bf16 v[96:99], v[140:143], v[206:209], v[96:99]
	v_mfma_f32_16x16x32_bf16 v[92:95], v[148:151], v[206:209], v[92:95]
	v_mfma_f32_16x16x32_bf16 v[80:83], v[140:143], v[214:217], v[80:83]
	v_mfma_f32_16x16x32_bf16 v[76:79], v[148:151], v[214:217], v[76:79]
	v_mfma_f32_16x16x32_bf16 v[128:131], v[144:147], v[194:197], v[128:131]
	v_mfma_f32_16x16x32_bf16 v[124:127], v[166:169], v[194:197], v[124:127]
	v_mfma_f32_16x16x32_bf16 v[112:115], v[144:147], v[202:205], v[112:115]
	v_mfma_f32_16x16x32_bf16 v[108:111], v[166:169], v[202:205], v[108:111]
	v_mfma_f32_16x16x32_bf16 v[96:99], v[144:147], v[210:213], v[96:99]
	v_mfma_f32_16x16x32_bf16 v[92:95], v[166:169], v[210:213], v[92:95]
	v_mfma_f32_16x16x32_bf16 v[80:83], v[144:147], v[220:223], v[80:83]
	v_mfma_f32_16x16x32_bf16 v[76:79], v[166:169], v[220:223], v[76:79]
	v_mfma_f32_16x16x32_bf16 v[120:123], v[170:173], v[190:193], v[120:123]
	v_mfma_f32_16x16x32_bf16 v[116:119], v[178:181], v[190:193], v[116:119]
	v_mfma_f32_16x16x32_bf16 v[104:107], v[170:173], v[198:201], v[104:107]
	v_mfma_f32_16x16x32_bf16 v[100:103], v[178:181], v[198:201], v[100:103]
	v_mfma_f32_16x16x32_bf16 v[88:91], v[170:173], v[206:209], v[88:91]
	v_mfma_f32_16x16x32_bf16 v[84:87], v[178:181], v[206:209], v[84:87]
	v_mfma_f32_16x16x32_bf16 v[72:75], v[170:173], v[214:217], v[72:75]
	v_mfma_f32_16x16x32_bf16 v[68:71], v[178:181], v[214:217], v[68:71]
	v_mfma_f32_16x16x32_bf16 v[120:123], v[174:177], v[194:197], v[120:123]
	v_mfma_f32_16x16x32_bf16 v[116:119], v[182:185], v[194:197], v[116:119]
	v_mfma_f32_16x16x32_bf16 v[104:107], v[174:177], v[202:205], v[104:107]
	v_mfma_f32_16x16x32_bf16 v[100:103], v[182:185], v[202:205], v[100:103]
	v_mfma_f32_16x16x32_bf16 v[88:91], v[174:177], v[210:213], v[88:91]
	v_mfma_f32_16x16x32_bf16 v[84:87], v[182:185], v[210:213], v[84:87]
	v_mfma_f32_16x16x32_bf16 v[72:75], v[174:177], v[220:223], v[72:75]
	v_mfma_f32_16x16x32_bf16 v[68:71], v[182:185], v[220:223], v[68:71]
	s_setprio 0
	s_barrier
; #define PG8_STAGE(bufoff, gbase, voff) do { _Pragma("unroll") for (int _i = 0; _i < 2; ++_i) \
;         __builtin_amdgcn_global_load_lds((const unsigned*)((const char*)(gbase) + (voff)[_i]), (PG8_LAS unsigned*)(lds + (bufoff) + ldsw + _i * 8192), 16, 0, 0); } while (0)
; #define PG8_LDA(dst, b, h) do { _Pragma("unroll") for (int m = 0; m < 4; ++m) _Pragma("unroll") for (int k = 0; k < 2; ++k) dst[m][k] = *(const PG8_LAS bf16x8*)(lds + PG8_SA(b, h) + aoff + m * 2048 + k * 1024); } while (0)
; #define PG8_MMA(ai, bj, At, Bt) do { __builtin_amdgcn_s_setprio(1); _Pragma("unroll") for (int m = 0; m < 4; ++m) _Pragma("unroll") for (int n = 0; n < 2; ++n) _Pragma("unroll") for (int k = 0; k < 2; ++k) \
;         acc[ai][bj][m][n] = __builtin_amdgcn_mfma_f32_16x16x32_bf16(Bt[n][k], At[m][k], acc[ai][bj][m][n], 0, 0, 0); __builtin_amdgcn_s_setprio(0); } while (0)
; #define PG8_WAIT_V(n) asm volatile("s_waitcnt vmcnt(" #n ")" ::: "memory")
; #define PG8_WAIT_L(n) asm volatile("s_waitcnt lgkmcnt(" #n ")" ::: "memory")
; #define PG8_BAR __builtin_amdgcn_s_barrier()
; #define PG8_SCHED __builtin_amdgcn_sched_barrier(0)
; template <class Epi, class Sched, bool ALIGN_EPI = false, bool SP2 = false>
; __device__ __forceinline__ void gemm_phase(PG8_LAS unsigned char* lds, const Gemm g, const Sched& S, const Epi& E) {
;     ...
;         for (int t = 0; t < nt; t += 2) {
;             const bool last = (t == nt - 2);
;             const char* a1 = cA + (size_t)(t + 1) * kstepA;
;             const char* a2 = last ? nA : cA + (size_t)(t + 2) * kstepA; const char* b2 = last ? nB : cB + (size_t)(t + 2) * kstep;
;             const char* a3 = a2 + kstepA; const char* b3 = b2 + kstep;
;     ...
;             PG8_LDA(At, 1, 1); PG8_STAGE(PG8_SB(1, 0), b3, voffB); PG8_STAGE(PG8_SB(1, 1), b3 + hstepB, voffB); PG8_STAGE(PG8_SA(1, 0), a3, voffA);
;             PG8_WAIT_V(8); PG8_WAIT_L(0); PG8_BAR; PG8_MMA(1, 0, At, B0); PG8_MMA(1, 1, At, B1); PG8_BAR; PG8_SCHED;
	s_add_i32 s8, s19, s89
	v_lshl_add_u64 v[6:7], v[152:153], 0, s[38:39]
	s_mov_b32 m0, s8
	ds_read_b128 v[190:193], v161 offset:49152
	ds_read_b128 v[194:197], v161 offset:50176
	ds_read_b128 v[198:201], v161 offset:51200
	ds_read_b128 v[202:205], v161 offset:52224
	ds_read_b128 v[206:209], v161 offset:53248
	ds_read_b128 v[210:213], v161 offset:54272
	ds_read_b128 v[214:217], v161 offset:55296
	ds_read_b128 v[220:223], v161 offset:56320
	global_load_lds_dwordx4 v[6:7], off
	v_lshl_add_u64 v[6:7], v[152:153], 0, s[40:41]
	s_add_i32 m0, s8, 0x2000
	s_add_i32 s8, s80, s89
	global_load_lds_dwordx4 v[6:7], off
	v_lshl_add_u64 v[6:7], v[152:153], 0, s[52:53]
	s_mov_b32 m0, s8
	s_nop 0
	global_load_lds_dwordx4 v[6:7], off
	v_lshl_add_u64 v[6:7], v[152:153], 0, s[54:55]
	s_add_i32 m0, s8, 0x2000
	s_nop 0
	global_load_lds_dwordx4 v[6:7], off
	v_lshl_add_u64 v[6:7], v[186:187], 0, s[38:39]
	s_mov_b32 m0, s94
	s_nop 0
	global_load_lds_dwordx4 v[6:7], off
	v_lshl_add_u64 v[6:7], v[186:187], 0, s[40:41]
	s_mov_b32 m0, s95
	s_nop 0
	global_load_lds_dwordx4 v[6:7], off
	s_waitcnt vmcnt(8)
	s_waitcnt lgkmcnt(0)
	s_barrier
	s_setprio 1
	s_waitcnt lgkmcnt(0)
	v_mfma_f32_16x16x32_bf16 v[64:67], v[140:143], v[190:193], v[64:67]
	v_mfma_f32_16x16x32_bf16 v[60:63], v[148:151], v[190:193], v[60:63]
	v_mfma_f32_16x16x32_bf16 v[48:51], v[140:143], v[198:201], v[48:51]
	v_mfma_f32_16x16x32_bf16 v[44:47], v[148:151], v[198:201], v[44:47]
	v_mfma_f32_16x16x32_bf16 v[32:35], v[140:143], v[206:209], v[32:35]
	v_mfma_f32_16x16x32_bf16 v[28:31], v[148:151], v[206:209], v[28:31]
	v_mfma_f32_16x16x32_bf16 v[16:19], v[140:143], v[214:217], v[16:19]
	v_mfma_f32_16x16x32_bf16 v[12:15], v[148:151], v[214:217], v[12:15]
	v_mfma_f32_16x16x32_bf16 v[64:67], v[144:147], v[194:197], v[64:67]
	v_mfma_f32_16x16x32_bf16 v[60:63], v[166:169], v[194:197], v[60:63]
	v_mfma_f32_16x16x32_bf16 v[48:51], v[144:147], v[202:205], v[48:51]
	v_mfma_f32_16x16x32_bf16 v[44:47], v[166:169], v[202:205], v[44:47]
	v_mfma_f32_16x16x32_bf16 v[32:35], v[144:147], v[210:213], v[32:35]
	v_mfma_f32_16x16x32_bf16 v[28:31], v[166:169], v[210:213], v[28:31]
	v_mfma_f32_16x16x32_bf16 v[16:19], v[144:147], v[220:223], v[16:19]
	v_mfma_f32_16x16x32_bf16 v[12:15], v[166:169], v[220:223], v[12:15]
	v_mfma_f32_16x16x32_bf16 v[56:59], v[170:173], v[190:193], v[56:59]
	v_mfma_f32_16x16x32_bf16 v[52:55], v[178:181], v[190:193], v[52:55]
	v_mfma_f32_16x16x32_bf16 v[40:43], v[170:173], v[198:201], v[40:43]
	v_mfma_f32_16x16x32_bf16 v[36:39], v[178:181], v[198:201], v[36:39]
	v_mfma_f32_16x16x32_bf16 v[24:27], v[170:173], v[206:209], v[24:27]
	v_mfma_f32_16x16x32_bf16 v[20:23], v[178:181], v[206:209], v[20:23]
	v_mfma_f32_16x16x32_bf16 v[6:9], v[170:173], v[214:217], v[8:11]
	v_mfma_f32_16x16x32_bf16 v[2:5], v[178:181], v[214:217], v[2:5]
	v_mfma_f32_16x16x32_bf16 v[56:59], v[174:177], v[194:197], v[56:59]
	v_mfma_f32_16x16x32_bf16 v[52:55], v[182:185], v[194:197], v[52:55]
	v_mfma_f32_16x16x32_bf16 v[40:43], v[174:177], v[202:205], v[40:43]
	v_mfma_f32_16x16x32_bf16 v[36:39], v[182:185], v[202:205], v[36:39]
	v_mfma_f32_16x16x32_bf16 v[24:27], v[174:177], v[210:213], v[24:27]
	v_mfma_f32_16x16x32_bf16 v[20:23], v[182:185], v[210:213], v[20:23]
	v_mfma_f32_16x16x32_bf16 v[8:11], v[174:177], v[220:223], v[6:9]
	v_mfma_f32_16x16x32_bf16 v[4:7], v[182:185], v[220:223], v[2:5]
	s_setprio 0
	s_barrier
	s_add_i32 s76, s76, 2
	s_add_u32 s4, s4, 0x10000
	s_addc_u32 s5, s5, 0
	s_add_u32 s74, s74, 0x10000
	s_addc_u32 s75, s75, 0
	s_cmp_gt_u32 s76, 13
	s_cbranch_scc0 .LBB0_315
	s_and_b64 vcc, exec, s[58:59]
	s_cbranch_vccz .LBB0_318
	s_barrier

; #define PG8_STAGE(bufoff, gbase, voff) do { _Pragma("unroll") for (int _i = 0; _i < 2; ++_i) \
;         __builtin_amdgcn_global_load_lds((const unsigned*)((const char*)(gbase) + (voff)[_i]), (PG8_LAS unsigned*)(lds + (bufoff) + ldsw + _i * 8192), 16, 0, 0); } while (0)
; #define PG8_LDA(dst, b, h) do { _Pragma("unroll") for (int m = 0; m < 4; ++m) _Pragma("unroll") for (int k = 0; k < 2; ++k) dst[m][k] = *(const PG8_LAS bf16x8*)(lds + PG8_SA(b, h) + aoff + m * 2048 + k * 1024); } while (0)
; #define PG8_LDB(dst, b, h) do { _Pragma("unroll") for (int n = 0; n < 2; ++n) _Pragma("unroll") for (int k = 0; k < 2; ++k) dst[n][k] = *(const PG8_LAS bf16x8*)(lds + PG8_SB(b, h) + boff + n * 2048 + k * 1024); } while (0)
; #define PG8_MMA(ai, bj, At, Bt) do { __builtin_amdgcn_s_setprio(1); _Pragma("unroll") for (int m = 0; m < 4; ++m) _Pragma("unroll") for (int n = 0; n < 2; ++n) _Pragma("unroll") for (int k = 0; k < 2; ++k) \
;         acc[ai][bj][m][n] = __builtin_amdgcn_mfma_f32_16x16x32_bf16(Bt[n][k], At[m][k], acc[ai][bj][m][n], 0, 0, 0); __builtin_amdgcn_s_setprio(0); } while (0)
; #define PG8_WAIT_V(n) asm volatile("s_waitcnt vmcnt(" #n ")" ::: "memory")
; #define PG8_WAIT_L(n) asm volatile("s_waitcnt lgkmcnt(" #n ")" ::: "memory")
; #define PG8_BAR __builtin_amdgcn_s_barrier()
; #define PG8_SCHED __builtin_amdgcn_sched_barrier(0)
; template <class Epi, class Sched, bool ALIGN_EPI = false, bool SP2 = false>
; __device__ __forceinline__ void gemm_phase(PG8_LAS unsigned char* lds, const Gemm g, const Sched& S, const Epi& E) {
;     ...
;             PG8_LDB(B0, 0, 0); PG8_LDB(B1, 0, 1); PG8_SCHED; PG8_LDA(At, 0, 0); PG8_STAGE(PG8_SA(1, 1), a1 + hstepA, voffA);
;             PG8_WAIT_V(8); PG8_WAIT_L(0); PG8_BAR; PG8_MMA(0, 0, At, B0); PG8_MMA(0, 1, At, B1); PG8_BAR; PG8_SCHED;
;             PG8_LDA(At, 0, 1); PG8_STAGE(PG8_SB(0, 0), b2, voffB); PG8_STAGE(PG8_SB(0, 1), b2 + hstepB, voffB); PG8_STAGE(PG8_SA(0, 0), a2, voffA);
.LBB0_646:
	ds_read_b128 v[128:131], v197
	ds_read_b128 v[132:135], v197 offset:1024
	ds_read_b128 v[136:139], v197 offset:2048
	ds_read_b128 v[140:143], v197 offset:3072
	ds_read_b128 v[144:147], v198
	ds_read_b128 v[148:151], v198 offset:1024
	ds_read_b128 v[152:155], v198 offset:2048
	ds_read_b128 v[156:159], v198 offset:3072
	s_add_u32 s8, s0, 0xfff10080
	s_addc_u32 s9, s1, -1
	s_cmp_eq_u32 s68, 12
	s_cselect_b32 s67, s63, s9
	s_cselect_b32 s66, s62, s8
	s_cselect_b32 s9, s61, s92
	s_cselect_b32 s8, s90, s91
	v_lshl_add_u64 v[236:237], s[0:1], 0, v[174:175]
	s_add_i32 m0, s17, 0xc000
	ds_read_b128 v[202:205], v199
	ds_read_b128 v[206:209], v199 offset:1024
	ds_read_b128 v[210:213], v199 offset:2048
	ds_read_b128 v[214:217], v199 offset:3072
	ds_read_b128 v[220:223], v199 offset:4096
	ds_read_b128 v[224:227], v199 offset:5120
	ds_read_b128 v[228:231], v199 offset:6144
	ds_read_b128 v[232:235], v199 offset:7168
	global_load_lds_dwordx4 v[236:237], off
	v_lshl_add_u64 v[236:237], s[0:1], 0, v[176:177]
	s_add_i32 m0, s17, 0xe000
	s_nop 0
	global_load_lds_dwordx4 v[236:237], off
	s_waitcnt vmcnt(8)
	s_waitcnt lgkmcnt(0)
	s_barrier
	s_setprio 1
	s_waitcnt lgkmcnt(0)
	v_mfma_f32_16x16x32_bf16 v[124:127], v[128:131], v[202:205], v[124:127]
	v_mfma_f32_16x16x32_bf16 v[120:123], v[136:139], v[202:205], v[120:123]
	v_mfma_f32_16x16x32_bf16 v[108:111], v[128:131], v[210:213], v[108:111]
	v_mfma_f32_16x16x32_bf16 v[104:107], v[136:139], v[210:213], v[104:107]
	v_mfma_f32_16x16x32_bf16 v[96:99], v[128:131], v[220:223], v[96:99]
	v_mfma_f32_16x16x32_bf16 v[88:91], v[136:139], v[220:223], v[88:91]
	v_mfma_f32_16x16x32_bf16 v[80:83], v[128:131], v[228:231], v[80:83]
	v_mfma_f32_16x16x32_bf16 v[72:75], v[136:139], v[228:231], v[72:75]
	v_mfma_f32_16x16x32_bf16 v[124:127], v[132:135], v[206:209], v[124:127]
	v_mfma_f32_16x16x32_bf16 v[120:123], v[140:143], v[206:209], v[120:123]
	v_mfma_f32_16x16x32_bf16 v[108:111], v[132:135], v[214:217], v[108:111]
	v_mfma_f32_16x16x32_bf16 v[104:107], v[140:143], v[214:217], v[104:107]
	v_mfma_f32_16x16x32_bf16 v[96:99], v[132:135], v[224:227], v[96:99]
	v_mfma_f32_16x16x32_bf16 v[88:91], v[140:143], v[224:227], v[88:91]
	v_mfma_f32_16x16x32_bf16 v[80:83], v[132:135], v[232:235], v[80:83]
	v_mfma_f32_16x16x32_bf16 v[72:75], v[140:143], v[232:235], v[72:75]
	v_mfma_f32_16x16x32_bf16 v[116:119], v[144:147], v[202:205], v[116:119]
	v_mfma_f32_16x16x32_bf16 v[112:115], v[152:155], v[202:205], v[112:115]
	v_mfma_f32_16x16x32_bf16 v[100:103], v[144:147], v[210:213], v[100:103]
	v_mfma_f32_16x16x32_bf16 v[92:95], v[152:155], v[210:213], v[92:95]
	v_mfma_f32_16x16x32_bf16 v[84:87], v[144:147], v[220:223], v[84:87]
	v_mfma_f32_16x16x32_bf16 v[76:79], v[152:155], v[220:223], v[76:79]
	v_mfma_f32_16x16x32_bf16 v[68:71], v[144:147], v[228:231], v[68:71]
	v_mfma_f32_16x16x32_bf16 v[64:67], v[152:155], v[228:231], v[64:67]
	v_mfma_f32_16x16x32_bf16 v[116:119], v[148:151], v[206:209], v[116:119]
	v_mfma_f32_16x16x32_bf16 v[112:115], v[156:159], v[206:209], v[112:115]
	v_mfma_f32_16x16x32_bf16 v[100:103], v[148:151], v[214:217], v[100:103]
	v_mfma_f32_16x16x32_bf16 v[92:95], v[156:159], v[214:217], v[92:95]
	v_mfma_f32_16x16x32_bf16 v[84:87], v[148:151], v[224:227], v[84:87]
	v_mfma_f32_16x16x32_bf16 v[76:79], v[156:159], v[224:227], v[76:79]
	v_mfma_f32_16x16x32_bf16 v[68:71], v[148:151], v[232:235], v[68:71]
	v_mfma_f32_16x16x32_bf16 v[64:67], v[156:159], v[232:235], v[64:67]
	s_setprio 0
	s_barrier
	v_lshl_add_u64 v[236:237], s[8:9], 0, v[190:191]
	s_add_i32 s8, s77, s15
	s_mov_b32 m0, s8
	ds_read_b128 v[202:205], v199 offset:16384
	ds_read_b128 v[206:209], v199 offset:17408
	ds_read_b128 v[210:213], v199 offset:18432
	ds_read_b128 v[214:217], v199 offset:19456
	ds_read_b128 v[220:223], v199 offset:20480
	ds_read_b128 v[224:227], v199 offset:21504
	ds_read_b128 v[228:231], v199 offset:22528
	ds_read_b128 v[232:235], v199 offset:23552
	global_load_lds_dwordx4 v[236:237], off
	v_lshl_add_u64 v[238:239], v[236:237], 0, s[36:37]
	s_add_i32 m0, s8, 0x2000
	s_add_i32 s8, s80, s15
	global_load_lds_dwordx4 v[238:239], off
	v_lshl_add_u64 v[238:239], v[236:237], 0, s[38:39]
	s_mov_b32 m0, s8
	v_lshl_add_u64 v[240:241], s[66:67], 0, v[162:163]
	global_load_lds_dwordx4 v[238:239], off
	v_lshl_add_u64 v[238:239], v[236:237], 0, s[40:41]
	s_add_i32 m0, s8, 0x2000
	s_nop 0
	global_load_lds_dwordx4 v[238:239], off
	v_lshl_add_u64 v[238:239], s[66:67], 0, v[160:161]
	s_mov_b32 m0, s17
	s_nop 0
	global_load_lds_dwordx4 v[238:239], off
	s_mov_b32 m0, s18
	s_nop 0
	global_load_lds_dwordx4 v[240:241], off
	s_waitcnt vmcnt(8)
	s_waitcnt lgkmcnt(0)
	s_barrier
; #define PG8_STAGE(bufoff, gbase, voff) do { _Pragma("unroll") for (int _i = 0; _i < 2; ++_i) \
;         __builtin_amdgcn_global_load_lds((const unsigned*)((const char*)(gbase) + (voff)[_i]), (PG8_LAS unsigned*)(lds + (bufoff) + ldsw + _i * 8192), 16, 0, 0); } while (0)
; #define PG8_LDA(dst, b, h) do { _Pragma("unroll") for (int m = 0; m < 4; ++m) _Pragma("unroll") for (int k = 0; k < 2; ++k) dst[m][k] = *(const PG8_LAS bf16x8*)(lds + PG8_SA(b, h) + aoff + m * 2048 + k * 1024); } while (0)
; #define PG8_LDB(dst, b, h) do { _Pragma("unroll") for (int n = 0; n < 2; ++n) _Pragma("unroll") for (int k = 0; k < 2; ++k) dst[n][k] = *(const PG8_LAS bf16x8*)(lds + PG8_SB(b, h) + boff + n * 2048 + k * 1024); } while (0)
; #define PG8_MMA(ai, bj, At, Bt) do { __builtin_amdgcn_s_setprio(1); _Pragma("unroll") for (int m = 0; m < 4; ++m) _Pragma("unroll") for (int n = 0; n < 2; ++n) _Pragma("unroll") for (int k = 0; k < 2; ++k) \
;         acc[ai][bj][m][n] = __builtin_amdgcn_mfma_f32_16x16x32_bf16(Bt[n][k], At[m][k], acc[ai][bj][m][n], 0, 0, 0); __builtin_amdgcn_s_setprio(0); } while (0)
; #define PG8_WAIT_V(n) asm volatile("s_waitcnt vmcnt(" #n ")" ::: "memory")
; #define PG8_WAIT_L(n) asm volatile("s_waitcnt lgkmcnt(" #n ")" ::: "memory")
; #define PG8_BAR __builtin_amdgcn_s_barrier()
; #define PG8_SCHED __builtin_amdgcn_sched_barrier(0)
; template <class Epi, class Sched, bool ALIGN_EPI = false, bool SP2 = false>
; __device__ __forceinline__ void gemm_phase(PG8_LAS unsigned char* lds, const Gemm g, const Sched& S, const Epi& E) {
;     ...
;             PG8_WAIT_V(8); PG8_WAIT_L(0); PG8_BAR; PG8_MMA(1, 0, At, B0); PG8_MMA(1, 1, At, B1); PG8_BAR; PG8_SCHED;
;             PG8_LDB(B0, 1, 0); PG8_LDB(B1, 1, 1); PG8_SCHED; PG8_LDA(At, 1, 0); PG8_STAGE(PG8_SA(0, 1), a2 + hstepA, voffA);
;             PG8_WAIT_V(8); PG8_WAIT_L(0); PG8_BAR; PG8_MMA(0, 0, At, B0); PG8_MMA(0, 1, At, B1); PG8_BAR; PG8_SCHED;
	s_setprio 1
	s_waitcnt lgkmcnt(0)
	v_mfma_f32_16x16x32_bf16 v[60:63], v[128:131], v[202:205], v[60:63]
	v_mfma_f32_16x16x32_bf16 v[56:59], v[136:139], v[202:205], v[56:59]
	v_mfma_f32_16x16x32_bf16 v[48:51], v[128:131], v[210:213], v[48:51]
	v_mfma_f32_16x16x32_bf16 v[40:43], v[136:139], v[210:213], v[40:43]
	v_mfma_f32_16x16x32_bf16 v[32:35], v[128:131], v[220:223], v[32:35]
	v_mfma_f32_16x16x32_bf16 v[24:27], v[136:139], v[220:223], v[24:27]
	v_mfma_f32_16x16x32_bf16 v[16:19], v[128:131], v[228:231], v[16:19]
	v_mfma_f32_16x16x32_bf16 v[8:11], v[136:139], v[228:231], v[8:11]
	v_mfma_f32_16x16x32_bf16 v[60:63], v[132:135], v[206:209], v[60:63]
	v_mfma_f32_16x16x32_bf16 v[56:59], v[140:143], v[206:209], v[56:59]
	v_mfma_f32_16x16x32_bf16 v[48:51], v[132:135], v[214:217], v[48:51]
	v_mfma_f32_16x16x32_bf16 v[40:43], v[140:143], v[214:217], v[40:43]
	v_mfma_f32_16x16x32_bf16 v[32:35], v[132:135], v[224:227], v[32:35]
	v_mfma_f32_16x16x32_bf16 v[24:27], v[140:143], v[224:227], v[24:27]
	v_mfma_f32_16x16x32_bf16 v[16:19], v[132:135], v[232:235], v[16:19]
	v_mfma_f32_16x16x32_bf16 v[8:11], v[140:143], v[232:235], v[8:11]
	v_mfma_f32_16x16x32_bf16 v[52:55], v[144:147], v[202:205], v[52:55]
	v_mfma_f32_16x16x32_bf16 v[44:47], v[152:155], v[202:205], v[44:47]
	v_mfma_f32_16x16x32_bf16 v[36:39], v[144:147], v[210:213], v[36:39]
	v_mfma_f32_16x16x32_bf16 v[28:31], v[152:155], v[210:213], v[28:31]
	v_mfma_f32_16x16x32_bf16 v[20:23], v[144:147], v[220:223], v[20:23]
	v_mfma_f32_16x16x32_bf16 v[12:15], v[152:155], v[220:223], v[12:15]
	v_mfma_f32_16x16x32_bf16 v[4:7], v[144:147], v[228:231], v[4:7]
	v_mfma_f32_16x16x32_bf16 v[0:3], v[152:155], v[228:231], v[0:3]
	v_mfma_f32_16x16x32_bf16 v[52:55], v[148:151], v[206:209], v[52:55]
	v_mfma_f32_16x16x32_bf16 v[44:47], v[156:159], v[206:209], v[44:47]
	v_mfma_f32_16x16x32_bf16 v[36:39], v[148:151], v[214:217], v[36:39]
	v_mfma_f32_16x16x32_bf16 v[28:31], v[156:159], v[214:217], v[28:31]
	v_mfma_f32_16x16x32_bf16 v[20:23], v[148:151], v[224:227], v[20:23]
	v_mfma_f32_16x16x32_bf16 v[12:15], v[156:159], v[224:227], v[12:15]
	v_mfma_f32_16x16x32_bf16 v[4:7], v[148:151], v[232:235], v[4:7]
	v_mfma_f32_16x16x32_bf16 v[0:3], v[156:159], v[232:235], v[0:3]
	s_setprio 0
	s_barrier
	ds_read_b128 v[128:131], v200
	ds_read_b128 v[132:135], v200 offset:1024
	ds_read_b128 v[136:139], v200 offset:2048
	ds_read_b128 v[140:143], v200 offset:3072
	ds_read_b128 v[144:147], v201
	ds_read_b128 v[148:151], v201 offset:1024
	ds_read_b128 v[152:155], v201 offset:2048
	ds_read_b128 v[156:159], v201 offset:3072
	s_add_u32 s8, s66, 0xf0000
	s_addc_u32 s9, s67, 0
	s_mov_b32 m0, s19
	v_lshl_add_u64 v[242:243], s[8:9], 0, v[160:161]
	ds_read_b128 v[202:205], v199 offset:32768
	ds_read_b128 v[206:209], v199 offset:33792
	ds_read_b128 v[210:213], v199 offset:34816
	ds_read_b128 v[214:217], v199 offset:35840
	ds_read_b128 v[220:223], v199 offset:36864
	ds_read_b128 v[224:227], v199 offset:37888
	ds_read_b128 v[228:231], v199 offset:38912
	ds_read_b128 v[232:235], v199 offset:39936
	global_load_lds_dwordx4 v[242:243], off
	v_lshl_add_u64 v[242:243], s[8:9], 0, v[162:163]
	s_mov_b32 m0, s59
	s_nop 0
	global_load_lds_dwordx4 v[242:243], off
	s_waitcnt vmcnt(8)
	s_waitcnt lgkmcnt(0)
	s_barrier
	s_setprio 1
	s_waitcnt lgkmcnt(0)
	v_mfma_f32_16x16x32_bf16 v[124:127], v[128:131], v[202:205], v[124:127]
	v_mfma_f32_16x16x32_bf16 v[120:123], v[136:139], v[202:205], v[120:123]
	v_mfma_f32_16x16x32_bf16 v[108:111], v[128:131], v[210:213], v[108:111]
	v_mfma_f32_16x16x32_bf16 v[104:107], v[136:139], v[210:213], v[104:107]
	v_mfma_f32_16x16x32_bf16 v[96:99], v[128:131], v[220:223], v[96:99]
	v_mfma_f32_16x16x32_bf16 v[88:91], v[136:139], v[220:223], v[88:91]
	v_mfma_f32_16x16x32_bf16 v[80:83], v[128:131], v[228:231], v[80:83]
	v_mfma_f32_16x16x32_bf16 v[72:75], v[136:139], v[228:231], v[72:75]
	v_mfma_f32_16x16x32_bf16 v[124:127], v[132:135], v[206:209], v[124:127]
	v_mfma_f32_16x16x32_bf16 v[120:123], v[140:143], v[206:209], v[120:123]
	v_mfma_f32_16x16x32_bf16 v[108:111], v[132:135], v[214:217], v[108:111]
	v_mfma_f32_16x16x32_bf16 v[104:107], v[140:143], v[214:217], v[104:107]
	v_mfma_f32_16x16x32_bf16 v[96:99], v[132:135], v[224:227], v[96:99]
	v_mfma_f32_16x16x32_bf16 v[88:91], v[140:143], v[224:227], v[88:91]
	v_mfma_f32_16x16x32_bf16 v[80:83], v[132:135], v[232:235], v[80:83]
	v_mfma_f32_16x16x32_bf16 v[72:75], v[140:143], v[232:235], v[72:75]
	v_mfma_f32_16x16x32_bf16 v[116:119], v[144:147], v[202:205], v[116:119]
	v_mfma_f32_16x16x32_bf16 v[112:115], v[152:155], v[202:205], v[112:115]
	v_mfma_f32_16x16x32_bf16 v[100:103], v[144:147], v[210:213], v[100:103]
	v_mfma_f32_16x16x32_bf16 v[92:95], v[152:155], v[210:213], v[92:95]
	v_mfma_f32_16x16x32_bf16 v[84:87], v[144:147], v[220:223], v[84:87]
	v_mfma_f32_16x16x32_bf16 v[76:79], v[152:155], v[220:223], v[76:79]
	v_mfma_f32_16x16x32_bf16 v[68:71], v[144:147], v[228:231], v[68:71]
	v_mfma_f32_16x16x32_bf16 v[64:67], v[152:155], v[228:231], v[64:67]
	v_mfma_f32_16x16x32_bf16 v[116:119], v[148:151], v[206:209], v[116:119]
	v_mfma_f32_16x16x32_bf16 v[112:115], v[156:159], v[206:209], v[112:115]
	v_mfma_f32_16x16x32_bf16 v[100:103], v[148:151], v[214:217], v[100:103]
	v_mfma_f32_16x16x32_bf16 v[92:95], v[156:159], v[214:217], v[92:95]
	v_mfma_f32_16x16x32_bf16 v[84:87], v[148:151], v[224:227], v[84:87]
	v_mfma_f32_16x16x32_bf16 v[76:79], v[156:159], v[224:227], v[76:79]
	v_mfma_f32_16x16x32_bf16 v[68:71], v[148:151], v[232:235], v[68:71]
	v_mfma_f32_16x16x32_bf16 v[64:67], v[156:159], v[232:235], v[64:67]
	s_setprio 0
	s_barrier
; #define PG8_STAGE(bufoff, gbase, voff) do { _Pragma("unroll") for (int _i = 0; _i < 2; ++_i) \
;         __builtin_amdgcn_global_load_lds((const unsigned*)((const char*)(gbase) + (voff)[_i]), (PG8_LAS unsigned*)(lds + (bufoff) + ldsw + _i * 8192), 16, 0, 0); } while (0)
; #define PG8_LDA(dst, b, h) do { _Pragma("unroll") for (int m = 0; m < 4; ++m) _Pragma("unroll") for (int k = 0; k < 2; ++k) dst[m][k] = *(const PG8_LAS bf16x8*)(lds + PG8_SA(b, h) + aoff + m * 2048 + k * 1024); } while (0)
; #define PG8_MMA(ai, bj, At, Bt) do { __builtin_amdgcn_s_setprio(1); _Pragma("unroll") for (int m = 0; m < 4; ++m) _Pragma("unroll") for (int n = 0; n < 2; ++n) _Pragma("unroll") for (int k = 0; k < 2; ++k) \
;         acc[ai][bj][m][n] = __builtin_amdgcn_mfma_f32_16x16x32_bf16(Bt[n][k], At[m][k], acc[ai][bj][m][n], 0, 0, 0); __builtin_amdgcn_s_setprio(0); } while (0)
; #define PG8_WAIT_V(n) asm volatile("s_waitcnt vmcnt(" #n ")" ::: "memory")
; #define PG8_WAIT_L(n) asm volatile("s_waitcnt lgkmcnt(" #n ")" ::: "memory")
; #define PG8_BAR __builtin_amdgcn_s_barrier()
; #define PG8_SCHED __builtin_amdgcn_sched_barrier(0)
; template <class Epi, class Sched, bool ALIGN_EPI = false, bool SP2 = false>
; __device__ __forceinline__ void gemm_phase(PG8_LAS unsigned char* lds, const Gemm g, const Sched& S, const Epi& E) {
;     ...
;             PG8_LDA(At, 1, 1); PG8_STAGE(PG8_SB(1, 0), b3, voffB); PG8_STAGE(PG8_SB(1, 1), b3 + hstepB, voffB); PG8_STAGE(PG8_SA(1, 0), a3, voffA);
;             PG8_WAIT_V(8); PG8_WAIT_L(0); PG8_BAR; PG8_MMA(1, 0, At, B0); PG8_MMA(1, 1, At, B1); PG8_BAR; PG8_SCHED;
	s_add_i32 s8, s81, s15
	v_lshl_add_u64 v[242:243], v[236:237], 0, s[42:43]
	s_mov_b32 m0, s8
	ds_read_b128 v[202:205], v199 offset:49152
	ds_read_b128 v[206:209], v199 offset:50176
	ds_read_b128 v[210:213], v199 offset:51200
	ds_read_b128 v[214:217], v199 offset:52224
	ds_read_b128 v[220:223], v199 offset:53248
	ds_read_b128 v[224:227], v199 offset:54272
	ds_read_b128 v[228:231], v199 offset:55296
	ds_read_b128 v[232:235], v199 offset:56320
	global_load_lds_dwordx4 v[242:243], off
	v_lshl_add_u64 v[242:243], v[236:237], 0, s[44:45]
	s_add_i32 m0, s8, 0x2000
	s_add_i32 s8, s82, s15
	global_load_lds_dwordx4 v[242:243], off
	v_lshl_add_u64 v[242:243], v[236:237], 0, s[48:49]
	s_mov_b32 m0, s8
	v_lshl_add_u64 v[236:237], v[236:237], 0, s[52:53]
	global_load_lds_dwordx4 v[242:243], off
	s_add_i32 m0, s8, 0x2000
	s_nop 0
	global_load_lds_dwordx4 v[236:237], off
	v_lshl_add_u64 v[236:237], v[238:239], 0, s[46:47]
	s_mov_b32 m0, s70
	s_nop 0
	global_load_lds_dwordx4 v[236:237], off
	v_lshl_add_u64 v[236:237], v[240:241], 0, s[46:47]
	s_mov_b32 m0, s71
	s_nop 0
	global_load_lds_dwordx4 v[236:237], off
	s_waitcnt vmcnt(8)
	s_waitcnt lgkmcnt(0)
	s_barrier
	s_setprio 1
	s_waitcnt lgkmcnt(0)
	v_mfma_f32_16x16x32_bf16 v[60:63], v[128:131], v[202:205], v[60:63]
	v_mfma_f32_16x16x32_bf16 v[56:59], v[136:139], v[202:205], v[56:59]
	v_mfma_f32_16x16x32_bf16 v[48:51], v[128:131], v[210:213], v[48:51]
	v_mfma_f32_16x16x32_bf16 v[40:43], v[136:139], v[210:213], v[40:43]
	v_mfma_f32_16x16x32_bf16 v[32:35], v[128:131], v[220:223], v[32:35]
	v_mfma_f32_16x16x32_bf16 v[24:27], v[136:139], v[220:223], v[24:27]
	v_mfma_f32_16x16x32_bf16 v[16:19], v[128:131], v[228:231], v[16:19]
	v_mfma_f32_16x16x32_bf16 v[8:11], v[136:139], v[228:231], v[8:11]
	v_mfma_f32_16x16x32_bf16 v[60:63], v[132:135], v[206:209], v[60:63]
	v_mfma_f32_16x16x32_bf16 v[56:59], v[140:143], v[206:209], v[56:59]
	v_mfma_f32_16x16x32_bf16 v[48:51], v[132:135], v[214:217], v[48:51]
	v_mfma_f32_16x16x32_bf16 v[40:43], v[140:143], v[214:217], v[40:43]
	v_mfma_f32_16x16x32_bf16 v[32:35], v[132:135], v[224:227], v[32:35]
	v_mfma_f32_16x16x32_bf16 v[24:27], v[140:143], v[224:227], v[24:27]
	v_mfma_f32_16x16x32_bf16 v[16:19], v[132:135], v[232:235], v[16:19]
	v_mfma_f32_16x16x32_bf16 v[8:11], v[140:143], v[232:235], v[8:11]
	v_mfma_f32_16x16x32_bf16 v[52:55], v[144:147], v[202:205], v[52:55]
	v_mfma_f32_16x16x32_bf16 v[44:47], v[152:155], v[202:205], v[44:47]
	v_mfma_f32_16x16x32_bf16 v[36:39], v[144:147], v[210:213], v[36:39]
	v_mfma_f32_16x16x32_bf16 v[28:31], v[152:155], v[210:213], v[28:31]
	v_mfma_f32_16x16x32_bf16 v[20:23], v[144:147], v[220:223], v[20:23]
	v_mfma_f32_16x16x32_bf16 v[12:15], v[152:155], v[220:223], v[12:15]
	v_mfma_f32_16x16x32_bf16 v[4:7], v[144:147], v[228:231], v[4:7]
	v_mfma_f32_16x16x32_bf16 v[0:3], v[152:155], v[228:231], v[0:3]
	v_mfma_f32_16x16x32_bf16 v[52:55], v[148:151], v[206:209], v[52:55]
	v_mfma_f32_16x16x32_bf16 v[44:47], v[156:159], v[206:209], v[44:47]
	v_mfma_f32_16x16x32_bf16 v[36:39], v[148:151], v[214:217], v[36:39]
	v_mfma_f32_16x16x32_bf16 v[28:31], v[156:159], v[214:217], v[28:31]
	v_mfma_f32_16x16x32_bf16 v[20:23], v[148:151], v[224:227], v[20:23]
	v_mfma_f32_16x16x32_bf16 v[12:15], v[156:159], v[224:227], v[12:15]
	v_mfma_f32_16x16x32_bf16 v[4:7], v[148:151], v[232:235], v[4:7]
	v_mfma_f32_16x16x32_bf16 v[0:3], v[156:159], v[232:235], v[0:3]
	s_setprio 0
	s_barrier
	s_add_i32 s68, s68, 2
	s_add_u32 s91, s91, 0x10000
	s_addc_u32 s92, s92, 0
	s_add_u32 s0, s0, 0x100
	s_addc_u32 s1, s1, 0
	s_cmp_gt_u32 s68, 13
	s_cbranch_scc0 .LBB0_646
	s_and_b64 vcc, exec, s[56:57]
	s_cbranch_vccz .LBB0_649
	s_barrier

; #define PG8_STAGE(bufoff, gbase, voff) do { _Pragma("unroll") for (int _i = 0; _i < 2; ++_i) \
;         __builtin_amdgcn_global_load_lds((const unsigned*)((const char*)(gbase) + (voff)[_i]), (PG8_LAS unsigned*)(lds + (bufoff) + ldsw + _i * 8192), 16, 0, 0); } while (0)
; #define PG8_LDA(dst, b, h) do { _Pragma("unroll") for (int m = 0; m < 4; ++m) _Pragma("unroll") for (int k = 0; k < 2; ++k) dst[m][k] = *(const PG8_LAS bf16x8*)(lds + PG8_SA(b, h) + aoff + m * 2048 + k * 1024); } while (0)
; #define PG8_LDB(dst, b, h) do { _Pragma("unroll") for (int n = 0; n < 2; ++n) _Pragma("unroll") for (int k = 0; k < 2; ++k) dst[n][k] = *(const PG8_LAS bf16x8*)(lds + PG8_SB(b, h) + boff + n * 2048 + k * 1024); } while (0)
; #define PG8_MMA(ai, bj, At, Bt) do { __builtin_amdgcn_s_setprio(1); _Pragma("unroll") for (int m = 0; m < 4; ++m) _Pragma("unroll") for (int n = 0; n < 2; ++n) _Pragma("unroll") for (int k = 0; k < 2; ++k) \
;         acc[ai][bj][m][n] = __builtin_amdgcn_mfma_f32_16x16x32_bf16(Bt[n][k], At[m][k], acc[ai][bj][m][n], 0, 0, 0); __builtin_amdgcn_s_setprio(0); } while (0)
; #define PG8_WAIT_V(n) asm volatile("s_waitcnt vmcnt(" #n ")" ::: "memory")
; #define PG8_WAIT_L(n) asm volatile("s_waitcnt lgkmcnt(" #n ")" ::: "memory")
; #define PG8_BAR __builtin_amdgcn_s_barrier()
; template <class Epi, class Sched, bool ALIGN_EPI = false, bool SP2 = false>
; __device__ __forceinline__ void gemm_phase(PG8_LAS unsigned char* lds, const Gemm g, const Sched& S, const Epi& E) {
;     ...
;             const char* a1 = cA + (size_t)(t + 1) * kstepA;
;             const char* a2 = last ? nA : cA + (size_t)(t + 2) * kstepA; const char* b2 = last ? nB : cB + (size_t)(t + 2) * kstep;
;             const char* a3 = a2 + kstepA; const char* b3 = b2 + kstep;
;             if (last && has_next) S.a_ready(nxt);
;             if constexpr (SP2) {
;             PG8_LDB(B0, 0, 0); PG8_LDB(B1, 0, 1); PG8_SCHED; PG8_LDA(At, 0, 0); PG8_STAGE(PG8_SA(1, 1), a1 + hstepA, voffA);
;             PG8_WAIT_V(8); PG8_WAIT_L(0); PG8_BAR; PG8_MMA(0, 0, At, B0); PG8_MMA(0, 1, At, B1); PG8_BAR; PG8_SCHED;
;             PG8_LDA(At, 0, 1); PG8_STAGE(PG8_SB(0, 0), b2, voffB); PG8_STAGE(PG8_SB(0, 1), b2 + hstepB, voffB); PG8_STAGE(PG8_SA(0, 0), a2, voffA);
;             PG8_WAIT_V(8); PG8_WAIT_L(0); PG8_BAR; PG8_MMA(1, 0, At, B0); PG8_MMA(1, 1, At, B1); PG8_BAR; PG8_SCHED;
.LBB0_670:
	ds_read_b128 v[108:111], v200
	ds_read_b128 v[132:135], v200 offset:1024
	ds_read_b128 v[136:139], v200 offset:2048
	ds_read_b128 v[140:143], v200 offset:3072
	ds_read_b128 v[144:147], v201
	ds_read_b128 v[148:151], v201 offset:1024
	ds_read_b128 v[152:155], v201 offset:2048
	ds_read_b128 v[156:159], v201 offset:3072
	s_add_u32 s8, s64, 0xfffe0080
	s_addc_u32 s9, s65, -1
	s_cmp_eq_u32 s86, 4
	s_cselect_b32 s67, s57, s9
	s_cselect_b32 s66, s68, s8
	s_cselect_b32 s9, s55, s85
	s_cselect_b32 s8, s69, s82
	v_lshl_add_u64 v[216:217], s[64:65], 0, v[186:187]
	s_add_i32 m0, s17, 0xc000
	ds_read_b128 v[160:163], v202
	ds_read_b128 v[164:167], v202 offset:1024
	ds_read_b128 v[168:171], v202 offset:2048
	ds_read_b128 v[204:207], v202 offset:3072
	ds_read_b128 v[208:211], v202 offset:4096
	ds_read_b128 v[212:215], v202 offset:5120
	ds_read_b128 v[220:223], v202 offset:6144
	ds_read_b128 v[224:227], v202 offset:7168
	global_load_lds_dwordx4 v[216:217], off
	v_lshl_add_u64 v[216:217], s[64:65], 0, v[192:193]
	s_add_i32 m0, s17, 0xe000
	s_nop 0
	global_load_lds_dwordx4 v[216:217], off
	s_waitcnt vmcnt(8)
	s_waitcnt lgkmcnt(0)
	s_barrier
	s_setprio 1
	s_waitcnt lgkmcnt(0)
	v_mfma_f32_16x16x32_bf16 v[128:131], v[108:111], v[160:163], v[128:131]
	v_mfma_f32_16x16x32_bf16 v[124:127], v[136:139], v[160:163], v[124:127]
	v_mfma_f32_16x16x32_bf16 v[112:115], v[108:111], v[168:171], v[112:115]
	v_mfma_f32_16x16x32_bf16 v[104:107], v[136:139], v[168:171], v[104:107]
	v_mfma_f32_16x16x32_bf16 v[92:95], v[108:111], v[208:211], v[92:95]
	v_mfma_f32_16x16x32_bf16 v[88:91], v[136:139], v[208:211], v[88:91]
	v_mfma_f32_16x16x32_bf16 v[76:79], v[108:111], v[220:223], v[76:79]
	v_mfma_f32_16x16x32_bf16 v[72:75], v[136:139], v[220:223], v[72:75]
	v_mfma_f32_16x16x32_bf16 v[128:131], v[132:135], v[164:167], v[128:131]
	v_mfma_f32_16x16x32_bf16 v[124:127], v[140:143], v[164:167], v[124:127]
	v_mfma_f32_16x16x32_bf16 v[112:115], v[132:135], v[204:207], v[112:115]
	v_mfma_f32_16x16x32_bf16 v[104:107], v[140:143], v[204:207], v[104:107]
	v_mfma_f32_16x16x32_bf16 v[92:95], v[132:135], v[212:215], v[92:95]
	v_mfma_f32_16x16x32_bf16 v[88:91], v[140:143], v[212:215], v[88:91]
	v_mfma_f32_16x16x32_bf16 v[76:79], v[132:135], v[224:227], v[76:79]
	v_mfma_f32_16x16x32_bf16 v[72:75], v[140:143], v[224:227], v[72:75]
	v_mfma_f32_16x16x32_bf16 v[120:123], v[144:147], v[160:163], v[120:123]
	v_mfma_f32_16x16x32_bf16 v[116:119], v[152:155], v[160:163], v[116:119]
	v_mfma_f32_16x16x32_bf16 v[100:103], v[144:147], v[168:171], v[100:103]
	v_mfma_f32_16x16x32_bf16 v[96:99], v[152:155], v[168:171], v[96:99]
	v_mfma_f32_16x16x32_bf16 v[84:87], v[144:147], v[208:211], v[84:87]
	v_mfma_f32_16x16x32_bf16 v[80:83], v[152:155], v[208:211], v[80:83]
	v_mfma_f32_16x16x32_bf16 v[68:71], v[144:147], v[220:223], v[68:71]
	v_mfma_f32_16x16x32_bf16 v[64:67], v[152:155], v[220:223], v[64:67]
	v_mfma_f32_16x16x32_bf16 v[120:123], v[148:151], v[164:167], v[120:123]
	v_mfma_f32_16x16x32_bf16 v[116:119], v[156:159], v[164:167], v[116:119]
	v_mfma_f32_16x16x32_bf16 v[100:103], v[148:151], v[204:207], v[100:103]
	v_mfma_f32_16x16x32_bf16 v[96:99], v[156:159], v[204:207], v[96:99]
	v_mfma_f32_16x16x32_bf16 v[84:87], v[148:151], v[212:215], v[84:87]
	v_mfma_f32_16x16x32_bf16 v[80:83], v[156:159], v[212:215], v[80:83]
	v_mfma_f32_16x16x32_bf16 v[68:71], v[148:151], v[224:227], v[68:71]
	v_mfma_f32_16x16x32_bf16 v[64:67], v[156:159], v[224:227], v[64:67]
	s_setprio 0
	s_barrier
	v_lshl_add_u64 v[216:217], s[8:9], 0, v[190:191]
	s_add_i32 s8, s11, s15
	s_mov_b32 m0, s8
	ds_read_b128 v[160:163], v202 offset:16384
	ds_read_b128 v[164:167], v202 offset:17408
	ds_read_b128 v[168:171], v202 offset:18432
	ds_read_b128 v[204:207], v202 offset:19456
	ds_read_b128 v[208:211], v202 offset:20480
	ds_read_b128 v[212:215], v202 offset:21504
	ds_read_b128 v[220:223], v202 offset:22528
	ds_read_b128 v[224:227], v202 offset:23552
	global_load_lds_dwordx4 v[216:217], off
	v_lshl_add_u64 v[228:229], v[216:217], 0, s[0:1]
	s_add_i32 m0, s8, 0x2000
	s_add_i32 s8, s80, s15
	global_load_lds_dwordx4 v[228:229], off
	v_lshl_add_u64 v[228:229], v[216:217], 0, s[34:35]
	s_mov_b32 m0, s8
	v_lshl_add_u64 v[230:231], s[66:67], 0, v[174:175]
	global_load_lds_dwordx4 v[228:229], off
	v_lshl_add_u64 v[228:229], v[216:217], 0, s[36:37]
	s_add_i32 m0, s8, 0x2000
	s_nop 0
	global_load_lds_dwordx4 v[228:229], off
	v_lshl_add_u64 v[228:229], s[66:67], 0, v[172:173]
	s_mov_b32 m0, s17
	s_nop 0
	global_load_lds_dwordx4 v[228:229], off
	s_mov_b32 m0, s18
	s_nop 0
	global_load_lds_dwordx4 v[230:231], off
	s_waitcnt vmcnt(8)
	s_waitcnt lgkmcnt(0)
	s_barrier
; #define PG8_STAGE(bufoff, gbase, voff) do { _Pragma("unroll") for (int _i = 0; _i < 2; ++_i) \
;         __builtin_amdgcn_global_load_lds((const unsigned*)((const char*)(gbase) + (voff)[_i]), (PG8_LAS unsigned*)(lds + (bufoff) + ldsw + _i * 8192), 16, 0, 0); } while (0)
; #define PG8_LDA(dst, b, h) do { _Pragma("unroll") for (int m = 0; m < 4; ++m) _Pragma("unroll") for (int k = 0; k < 2; ++k) dst[m][k] = *(const PG8_LAS bf16x8*)(lds + PG8_SA(b, h) + aoff + m * 2048 + k * 1024); } while (0)
; #define PG8_LDB(dst, b, h) do { _Pragma("unroll") for (int n = 0; n < 2; ++n) _Pragma("unroll") for (int k = 0; k < 2; ++k) dst[n][k] = *(const PG8_LAS bf16x8*)(lds + PG8_SB(b, h) + boff + n * 2048 + k * 1024); } while (0)
; #define PG8_MMA(ai, bj, At, Bt) do { __builtin_amdgcn_s_setprio(1); _Pragma("unroll") for (int m = 0; m < 4; ++m) _Pragma("unroll") for (int n = 0; n < 2; ++n) _Pragma("unroll") for (int k = 0; k < 2; ++k) \
;         acc[ai][bj][m][n] = __builtin_amdgcn_mfma_f32_16x16x32_bf16(Bt[n][k], At[m][k], acc[ai][bj][m][n], 0, 0, 0); __builtin_amdgcn_s_setprio(0); } while (0)
; #define PG8_WAIT_V(n) asm volatile("s_waitcnt vmcnt(" #n ")" ::: "memory")
; #define PG8_WAIT_L(n) asm volatile("s_waitcnt lgkmcnt(" #n ")" ::: "memory")
; #define PG8_BAR __builtin_amdgcn_s_barrier()
; #define PG8_SCHED __builtin_amdgcn_sched_barrier(0)
; template <class Epi, class Sched, bool ALIGN_EPI = false, bool SP2 = false>
; __device__ __forceinline__ void gemm_phase(PG8_LAS unsigned char* lds, const Gemm g, const Sched& S, const Epi& E) {
;     ...
;             PG8_WAIT_V(8); PG8_WAIT_L(0); PG8_BAR; PG8_MMA(1, 0, At, B0); PG8_MMA(1, 1, At, B1); PG8_BAR; PG8_SCHED;
;             PG8_LDB(B0, 1, 0); PG8_LDB(B1, 1, 1); PG8_SCHED; PG8_LDA(At, 1, 0); PG8_STAGE(PG8_SA(0, 1), a2 + hstepA, voffA);
;             PG8_WAIT_V(8); PG8_WAIT_L(0); PG8_BAR; PG8_MMA(0, 0, At, B0); PG8_MMA(0, 1, At, B1); PG8_BAR; PG8_SCHED;
	s_setprio 1
	s_waitcnt lgkmcnt(0)
	v_mfma_f32_16x16x32_bf16 v[60:63], v[108:111], v[160:163], v[60:63]
	v_mfma_f32_16x16x32_bf16 v[56:59], v[136:139], v[160:163], v[56:59]
	v_mfma_f32_16x16x32_bf16 v[44:47], v[108:111], v[168:171], v[44:47]
	v_mfma_f32_16x16x32_bf16 v[40:43], v[136:139], v[168:171], v[40:43]
	v_mfma_f32_16x16x32_bf16 v[28:31], v[108:111], v[208:211], v[28:31]
	v_mfma_f32_16x16x32_bf16 v[24:27], v[136:139], v[208:211], v[24:27]
	v_mfma_f32_16x16x32_bf16 v[12:15], v[108:111], v[220:223], v[12:15]
	v_mfma_f32_16x16x32_bf16 v[8:11], v[136:139], v[220:223], v[8:11]
	v_mfma_f32_16x16x32_bf16 v[60:63], v[132:135], v[164:167], v[60:63]
	v_mfma_f32_16x16x32_bf16 v[56:59], v[140:143], v[164:167], v[56:59]
	v_mfma_f32_16x16x32_bf16 v[44:47], v[132:135], v[204:207], v[44:47]
	v_mfma_f32_16x16x32_bf16 v[40:43], v[140:143], v[204:207], v[40:43]
	v_mfma_f32_16x16x32_bf16 v[28:31], v[132:135], v[212:215], v[28:31]
	v_mfma_f32_16x16x32_bf16 v[24:27], v[140:143], v[212:215], v[24:27]
	v_mfma_f32_16x16x32_bf16 v[12:15], v[132:135], v[224:227], v[12:15]
	v_mfma_f32_16x16x32_bf16 v[8:11], v[140:143], v[224:227], v[8:11]
	v_mfma_f32_16x16x32_bf16 v[52:55], v[144:147], v[160:163], v[52:55]
	v_mfma_f32_16x16x32_bf16 v[48:51], v[152:155], v[160:163], v[48:51]
	v_mfma_f32_16x16x32_bf16 v[36:39], v[144:147], v[168:171], v[36:39]
	v_mfma_f32_16x16x32_bf16 v[32:35], v[152:155], v[168:171], v[32:35]
	v_mfma_f32_16x16x32_bf16 v[20:23], v[144:147], v[208:211], v[20:23]
	v_mfma_f32_16x16x32_bf16 v[16:19], v[152:155], v[208:211], v[16:19]
	v_mfma_f32_16x16x32_bf16 v[4:7], v[144:147], v[220:223], v[4:7]
	v_mfma_f32_16x16x32_bf16 v[0:3], v[152:155], v[220:223], v[0:3]
	v_mfma_f32_16x16x32_bf16 v[52:55], v[148:151], v[164:167], v[52:55]
	v_mfma_f32_16x16x32_bf16 v[48:51], v[156:159], v[164:167], v[48:51]
	v_mfma_f32_16x16x32_bf16 v[36:39], v[148:151], v[204:207], v[36:39]
	v_mfma_f32_16x16x32_bf16 v[32:35], v[156:159], v[204:207], v[32:35]
	v_mfma_f32_16x16x32_bf16 v[20:23], v[148:151], v[212:215], v[20:23]
	v_mfma_f32_16x16x32_bf16 v[16:19], v[156:159], v[212:215], v[16:19]
	v_mfma_f32_16x16x32_bf16 v[4:7], v[148:151], v[224:227], v[4:7]
	v_mfma_f32_16x16x32_bf16 v[0:3], v[156:159], v[224:227], v[0:3]
	s_setprio 0
	s_barrier
	s_add_i32 s78, 0, 0x1c000
	v_add_u32_e32 v156, s78, v199
	ds_read_b128 v[108:111], v203
	ds_read_b128 v[132:135], v203 offset:1024
	ds_read_b128 v[136:139], v203 offset:2048
	ds_read_b128 v[140:143], v203 offset:3072
	ds_read_b128 v[144:147], v156
	ds_read_b128 v[148:151], v156 offset:1024
	ds_read_b128 v[152:155], v156 offset:2048
	ds_read_b128 v[156:159], v156 offset:3072
	s_add_u32 s8, s66, 0x20000
	s_addc_u32 s9, s67, 0
	s_mov_b32 m0, s19
	v_lshl_add_u64 v[232:233], s[8:9], 0, v[172:173]
	ds_read_b128 v[160:163], v202 offset:32768
	ds_read_b128 v[164:167], v202 offset:33792
	ds_read_b128 v[168:171], v202 offset:34816
	ds_read_b128 v[204:207], v202 offset:35840
	ds_read_b128 v[208:211], v202 offset:36864
	ds_read_b128 v[212:215], v202 offset:37888
	ds_read_b128 v[220:223], v202 offset:38912
	ds_read_b128 v[224:227], v202 offset:39936
	global_load_lds_dwordx4 v[232:233], off
	v_lshl_add_u64 v[232:233], s[8:9], 0, v[174:175]
	s_mov_b32 m0, s70
	s_nop 0
	global_load_lds_dwordx4 v[232:233], off
	s_waitcnt vmcnt(8)
	s_waitcnt lgkmcnt(0)
	s_barrier
	s_setprio 1
	s_waitcnt lgkmcnt(0)
	v_mfma_f32_16x16x32_bf16 v[128:131], v[108:111], v[160:163], v[128:131]
	v_mfma_f32_16x16x32_bf16 v[124:127], v[136:139], v[160:163], v[124:127]
	v_mfma_f32_16x16x32_bf16 v[112:115], v[108:111], v[168:171], v[112:115]
	v_mfma_f32_16x16x32_bf16 v[104:107], v[136:139], v[168:171], v[104:107]
	v_mfma_f32_16x16x32_bf16 v[92:95], v[108:111], v[208:211], v[92:95]
	v_mfma_f32_16x16x32_bf16 v[88:91], v[136:139], v[208:211], v[88:91]
	v_mfma_f32_16x16x32_bf16 v[76:79], v[108:111], v[220:223], v[76:79]
	v_mfma_f32_16x16x32_bf16 v[72:75], v[136:139], v[220:223], v[72:75]
	v_mfma_f32_16x16x32_bf16 v[128:131], v[132:135], v[164:167], v[128:131]
	v_mfma_f32_16x16x32_bf16 v[124:127], v[140:143], v[164:167], v[124:127]
	v_mfma_f32_16x16x32_bf16 v[112:115], v[132:135], v[204:207], v[112:115]
	v_mfma_f32_16x16x32_bf16 v[104:107], v[140:143], v[204:207], v[104:107]
	v_mfma_f32_16x16x32_bf16 v[92:95], v[132:135], v[212:215], v[92:95]
	v_mfma_f32_16x16x32_bf16 v[88:91], v[140:143], v[212:215], v[88:91]
	v_mfma_f32_16x16x32_bf16 v[76:79], v[132:135], v[224:227], v[76:79]
	v_mfma_f32_16x16x32_bf16 v[72:75], v[140:143], v[224:227], v[72:75]
	v_mfma_f32_16x16x32_bf16 v[120:123], v[144:147], v[160:163], v[120:123]
	v_mfma_f32_16x16x32_bf16 v[116:119], v[152:155], v[160:163], v[116:119]
	v_mfma_f32_16x16x32_bf16 v[100:103], v[144:147], v[168:171], v[100:103]
	v_mfma_f32_16x16x32_bf16 v[96:99], v[152:155], v[168:171], v[96:99]
	v_mfma_f32_16x16x32_bf16 v[84:87], v[144:147], v[208:211], v[84:87]
	v_mfma_f32_16x16x32_bf16 v[80:83], v[152:155], v[208:211], v[80:83]
	v_mfma_f32_16x16x32_bf16 v[68:71], v[144:147], v[220:223], v[68:71]
	v_mfma_f32_16x16x32_bf16 v[64:67], v[152:155], v[220:223], v[64:67]
	v_mfma_f32_16x16x32_bf16 v[120:123], v[148:151], v[164:167], v[120:123]
	v_mfma_f32_16x16x32_bf16 v[116:119], v[156:159], v[164:167], v[116:119]
	v_mfma_f32_16x16x32_bf16 v[100:103], v[148:151], v[204:207], v[100:103]
	v_mfma_f32_16x16x32_bf16 v[96:99], v[156:159], v[204:207], v[96:99]
	v_mfma_f32_16x16x32_bf16 v[84:87], v[148:151], v[212:215], v[84:87]
	v_mfma_f32_16x16x32_bf16 v[80:83], v[156:159], v[212:215], v[80:83]
	v_mfma_f32_16x16x32_bf16 v[68:71], v[148:151], v[224:227], v[68:71]
	v_mfma_f32_16x16x32_bf16 v[64:67], v[156:159], v[224:227], v[64:67]
	s_setprio 0
	s_barrier
; #define PG8_STAGE(bufoff, gbase, voff) do { _Pragma("unroll") for (int _i = 0; _i < 2; ++_i) \
;         __builtin_amdgcn_global_load_lds((const unsigned*)((const char*)(gbase) + (voff)[_i]), (PG8_LAS unsigned*)(lds + (bufoff) + ldsw + _i * 8192), 16, 0, 0); } while (0)
; #define PG8_LDA(dst, b, h) do { _Pragma("unroll") for (int m = 0; m < 4; ++m) _Pragma("unroll") for (int k = 0; k < 2; ++k) dst[m][k] = *(const PG8_LAS bf16x8*)(lds + PG8_SA(b, h) + aoff + m * 2048 + k * 1024); } while (0)
; #define PG8_MMA(ai, bj, At, Bt) do { __builtin_amdgcn_s_setprio(1); _Pragma("unroll") for (int m = 0; m < 4; ++m) _Pragma("unroll") for (int n = 0; n < 2; ++n) _Pragma("unroll") for (int k = 0; k < 2; ++k) \
;         acc[ai][bj][m][n] = __builtin_amdgcn_mfma_f32_16x16x32_bf16(Bt[n][k], At[m][k], acc[ai][bj][m][n], 0, 0, 0); __builtin_amdgcn_s_setprio(0); } while (0)
; #define PG8_WAIT_V(n) asm volatile("s_waitcnt vmcnt(" #n ")" ::: "memory")
; #define PG8_WAIT_L(n) asm volatile("s_waitcnt lgkmcnt(" #n ")" ::: "memory")
; #define PG8_BAR __builtin_amdgcn_s_barrier()
; #define PG8_SCHED __builtin_amdgcn_sched_barrier(0)
; template <class Epi, class Sched, bool ALIGN_EPI = false, bool SP2 = false>
; __device__ __forceinline__ void gemm_phase(PG8_LAS unsigned char* lds, const Gemm g, const Sched& S, const Epi& E) {
;     ...
;             PG8_LDA(At, 1, 1); PG8_STAGE(PG8_SB(1, 0), b3, voffB); PG8_STAGE(PG8_SB(1, 1), b3 + hstepB, voffB); PG8_STAGE(PG8_SA(1, 0), a3, voffA);
;             PG8_WAIT_V(8); PG8_WAIT_L(0); PG8_BAR; PG8_MMA(1, 0, At, B0); PG8_MMA(1, 1, At, B1); PG8_BAR; PG8_SCHED;
	s_add_i32 s8, s81, s15
	v_lshl_add_u64 v[232:233], v[216:217], 0, s[38:39]
	s_mov_b32 m0, s8
	ds_read_b128 v[160:163], v202 offset:49152
	ds_read_b128 v[164:167], v202 offset:50176
	ds_read_b128 v[168:171], v202 offset:51200
	ds_read_b128 v[204:207], v202 offset:52224
	ds_read_b128 v[208:211], v202 offset:53248
	ds_read_b128 v[212:215], v202 offset:54272
	ds_read_b128 v[220:223], v202 offset:55296
	ds_read_b128 v[224:227], v202 offset:56320
	global_load_lds_dwordx4 v[232:233], off
	v_lshl_add_u64 v[232:233], v[216:217], 0, s[40:41]
	s_add_i32 m0, s8, 0x2000
	s_add_i32 s8, s78, s15
	global_load_lds_dwordx4 v[232:233], off
	v_lshl_add_u64 v[232:233], v[216:217], 0, s[44:45]
	s_mov_b32 m0, s8
	v_lshl_add_u64 v[216:217], v[216:217], 0, s[46:47]
	global_load_lds_dwordx4 v[232:233], off
	s_add_i32 m0, s8, 0x2000
	s_nop 0
	global_load_lds_dwordx4 v[216:217], off
	v_lshl_add_u64 v[216:217], v[228:229], 0, s[42:43]
	s_mov_b32 m0, s71
	s_nop 0
	global_load_lds_dwordx4 v[216:217], off
	v_lshl_add_u64 v[216:217], v[230:231], 0, s[42:43]
	s_mov_b32 m0, s72
	s_nop 0
	global_load_lds_dwordx4 v[216:217], off
	s_waitcnt vmcnt(8)
	s_waitcnt lgkmcnt(0)
	s_barrier
	s_setprio 1
	s_waitcnt lgkmcnt(0)
	v_mfma_f32_16x16x32_bf16 v[60:63], v[108:111], v[160:163], v[60:63]
	v_mfma_f32_16x16x32_bf16 v[56:59], v[136:139], v[160:163], v[56:59]
	v_mfma_f32_16x16x32_bf16 v[44:47], v[108:111], v[168:171], v[44:47]
	v_mfma_f32_16x16x32_bf16 v[40:43], v[136:139], v[168:171], v[40:43]
	v_mfma_f32_16x16x32_bf16 v[28:31], v[108:111], v[208:211], v[28:31]
	v_mfma_f32_16x16x32_bf16 v[24:27], v[136:139], v[208:211], v[24:27]
	v_mfma_f32_16x16x32_bf16 v[12:15], v[108:111], v[220:223], v[12:15]
	v_mfma_f32_16x16x32_bf16 v[8:11], v[136:139], v[220:223], v[8:11]
	v_mfma_f32_16x16x32_bf16 v[60:63], v[132:135], v[164:167], v[60:63]
	v_mfma_f32_16x16x32_bf16 v[56:59], v[140:143], v[164:167], v[56:59]
	v_mfma_f32_16x16x32_bf16 v[44:47], v[132:135], v[204:207], v[44:47]
	v_mfma_f32_16x16x32_bf16 v[40:43], v[140:143], v[204:207], v[40:43]
	v_mfma_f32_16x16x32_bf16 v[28:31], v[132:135], v[212:215], v[28:31]
	v_mfma_f32_16x16x32_bf16 v[24:27], v[140:143], v[212:215], v[24:27]
	v_mfma_f32_16x16x32_bf16 v[12:15], v[132:135], v[224:227], v[12:15]
	v_mfma_f32_16x16x32_bf16 v[8:11], v[140:143], v[224:227], v[8:11]
	v_mfma_f32_16x16x32_bf16 v[52:55], v[144:147], v[160:163], v[52:55]
	v_mfma_f32_16x16x32_bf16 v[48:51], v[152:155], v[160:163], v[48:51]
	v_mfma_f32_16x16x32_bf16 v[36:39], v[144:147], v[168:171], v[36:39]
	v_mfma_f32_16x16x32_bf16 v[32:35], v[152:155], v[168:171], v[32:35]
	v_mfma_f32_16x16x32_bf16 v[20:23], v[144:147], v[208:211], v[20:23]
	v_mfma_f32_16x16x32_bf16 v[16:19], v[152:155], v[208:211], v[16:19]
	v_mfma_f32_16x16x32_bf16 v[4:7], v[144:147], v[220:223], v[4:7]
	v_mfma_f32_16x16x32_bf16 v[0:3], v[152:155], v[220:223], v[0:3]
	v_mfma_f32_16x16x32_bf16 v[52:55], v[148:151], v[164:167], v[52:55]
	v_mfma_f32_16x16x32_bf16 v[48:51], v[156:159], v[164:167], v[48:51]
	v_mfma_f32_16x16x32_bf16 v[36:39], v[148:151], v[204:207], v[36:39]
	v_mfma_f32_16x16x32_bf16 v[32:35], v[156:159], v[204:207], v[32:35]
	v_mfma_f32_16x16x32_bf16 v[20:23], v[148:151], v[212:215], v[20:23]
	v_mfma_f32_16x16x32_bf16 v[16:19], v[156:159], v[212:215], v[16:19]
	v_mfma_f32_16x16x32_bf16 v[4:7], v[148:151], v[224:227], v[4:7]
	v_mfma_f32_16x16x32_bf16 v[0:3], v[156:159], v[224:227], v[0:3]
	s_setprio 0
	s_barrier
	s_add_i32 s86, s86, 2
	s_add_u32 s82, s82, 0x10000
	s_addc_u32 s85, s85, 0
	s_add_u32 s64, s64, 0x100
	s_addc_u32 s65, s65, 0
	s_cmp_gt_u32 s86, 5
	s_cbranch_scc0 .LBB0_670
	s_and_b64 vcc, exec, s[52:53]
	s_cbranch_vccz .LBB0_673
	s_barrier

; #define PG8_STAGE(bufoff, gbase, voff) do { _Pragma("unroll") for (int _i = 0; _i < 2; ++_i) \
;         __builtin_amdgcn_global_load_lds((const unsigned*)((const char*)(gbase) + (voff)[_i]), (PG8_LAS unsigned*)(lds + (bufoff) + ldsw + _i * 8192), 16, 0, 0); } while (0)
; #define PG8_LDA(dst, b, h) do { _Pragma("unroll") for (int m = 0; m < 4; ++m) _Pragma("unroll") for (int k = 0; k < 2; ++k) dst[m][k] = *(const PG8_LAS bf16x8*)(lds + PG8_SA(b, h) + aoff + m * 2048 + k * 1024); } while (0)
; #define PG8_LDB(dst, b, h) do { _Pragma("unroll") for (int n = 0; n < 2; ++n) _Pragma("unroll") for (int k = 0; k < 2; ++k) dst[n][k] = *(const PG8_LAS bf16x8*)(lds + PG8_SB(b, h) + boff + n * 2048 + k * 1024); } while (0)
; #define PG8_MMA(ai, bj, At, Bt) do { __builtin_amdgcn_s_setprio(1); _Pragma("unroll") for (int m = 0; m < 4; ++m) _Pragma("unroll") for (int n = 0; n < 2; ++n) _Pragma("unroll") for (int k = 0; k < 2; ++k) \
;         acc[ai][bj][m][n] = __builtin_amdgcn_mfma_f32_16x16x32_bf16(Bt[n][k], At[m][k], acc[ai][bj][m][n], 0, 0, 0); __builtin_amdgcn_s_setprio(0); } while (0)
; #define PG8_WAIT_V(n) asm volatile("s_waitcnt vmcnt(" #n ")" ::: "memory")
; #define PG8_WAIT_L(n) asm volatile("s_waitcnt lgkmcnt(" #n ")" ::: "memory")
; #define PG8_BAR __builtin_amdgcn_s_barrier()
; template <class Epi, class Sched, bool ALIGN_EPI = false, bool SP2 = false>
; __device__ __forceinline__ void gemm_phase(PG8_LAS unsigned char* lds, const Gemm g, const Sched& S, const Epi& E) {
;     ...
;             const char* a1 = cA + (size_t)(t + 1) * kstepA;
;             const char* a2 = last ? nA : cA + (size_t)(t + 2) * kstepA; const char* b2 = last ? nB : cB + (size_t)(t + 2) * kstep;
;             const char* a3 = a2 + kstepA; const char* b3 = b2 + kstep;
;             if (last && has_next) S.a_ready(nxt);
;             if constexpr (SP2) {
;             PG8_LDB(B0, 0, 0); PG8_LDB(B1, 0, 1); PG8_SCHED; PG8_LDA(At, 0, 0); PG8_STAGE(PG8_SA(1, 1), a1 + hstepA, voffA);
;             PG8_WAIT_V(8); PG8_WAIT_L(0); PG8_BAR; PG8_MMA(0, 0, At, B0); PG8_MMA(0, 1, At, B1); PG8_BAR; PG8_SCHED;
;             PG8_LDA(At, 0, 1); PG8_STAGE(PG8_SB(0, 0), b2, voffB); PG8_STAGE(PG8_SB(0, 1), b2 + hstepB, voffB); PG8_STAGE(PG8_SA(0, 0), a2, voffA);
;             PG8_WAIT_V(8); PG8_WAIT_L(0); PG8_BAR; PG8_MMA(1, 0, At, B0); PG8_MMA(1, 1, At, B1); PG8_BAR; PG8_SCHED;
.LBB0_751:
	ds_read_b128 v[128:131], v211
	ds_read_b128 v[132:135], v211 offset:1024
	ds_read_b128 v[136:139], v211 offset:2048
	ds_read_b128 v[140:143], v211 offset:3072
	ds_read_b128 v[144:147], v212
	ds_read_b128 v[148:151], v212 offset:1024
	ds_read_b128 v[152:155], v212 offset:2048
	ds_read_b128 v[156:159], v212 offset:3072
	s_cmp_eq_u32 s72, 12
	s_cselect_b32 s79, s59, s69
	s_cselect_b32 s78, s65, s68
	s_cselect_b32 s91, s57, s71
	s_cselect_b32 s90, s67, s70
	v_lshl_add_u64 v[208:209], s[68:69], 0, v[190:191]
	v_lshl_add_u64 v[228:229], v[208:209], 0, s[52:53]
	s_add_i32 m0, s15, 0xc000
	ds_read_b128 v[160:163], v213
	ds_read_b128 v[164:167], v213 offset:1024
	ds_read_b128 v[168:171], v213 offset:2048
	ds_read_b128 v[172:175], v213 offset:3072
	ds_read_b128 v[176:179], v213 offset:4096
	ds_read_b128 v[180:183], v213 offset:5120
	ds_read_b128 v[220:223], v213 offset:6144
	ds_read_b128 v[224:227], v213 offset:7168
	global_load_lds_dwordx4 v[228:229], off
	v_lshl_add_u64 v[208:209], v[208:209], 0, s[54:55]
	s_add_i32 m0, s15, 0xe000
	s_nop 0
	global_load_lds_dwordx4 v[208:209], off
	s_waitcnt vmcnt(8)
	s_waitcnt lgkmcnt(0)
	s_barrier
	s_setprio 1
	s_waitcnt lgkmcnt(0)
	v_mfma_f32_16x16x32_bf16 v[124:127], v[128:131], v[160:163], v[124:127]
	v_mfma_f32_16x16x32_bf16 v[120:123], v[136:139], v[160:163], v[120:123]
	v_mfma_f32_16x16x32_bf16 v[108:111], v[128:131], v[168:171], v[108:111]
	v_mfma_f32_16x16x32_bf16 v[104:107], v[136:139], v[168:171], v[104:107]
	v_mfma_f32_16x16x32_bf16 v[92:95], v[128:131], v[176:179], v[92:95]
	v_mfma_f32_16x16x32_bf16 v[88:91], v[136:139], v[176:179], v[88:91]
	v_mfma_f32_16x16x32_bf16 v[76:79], v[128:131], v[220:223], v[76:79]
	v_mfma_f32_16x16x32_bf16 v[72:75], v[136:139], v[220:223], v[72:75]
	v_mfma_f32_16x16x32_bf16 v[124:127], v[132:135], v[164:167], v[124:127]
	v_mfma_f32_16x16x32_bf16 v[120:123], v[140:143], v[164:167], v[120:123]
	v_mfma_f32_16x16x32_bf16 v[108:111], v[132:135], v[172:175], v[108:111]
	v_mfma_f32_16x16x32_bf16 v[104:107], v[140:143], v[172:175], v[104:107]
	v_mfma_f32_16x16x32_bf16 v[92:95], v[132:135], v[180:183], v[92:95]
	v_mfma_f32_16x16x32_bf16 v[88:91], v[140:143], v[180:183], v[88:91]
	v_mfma_f32_16x16x32_bf16 v[76:79], v[132:135], v[224:227], v[76:79]
	v_mfma_f32_16x16x32_bf16 v[72:75], v[140:143], v[224:227], v[72:75]
	v_mfma_f32_16x16x32_bf16 v[116:119], v[144:147], v[160:163], v[116:119]
	v_mfma_f32_16x16x32_bf16 v[112:115], v[152:155], v[160:163], v[112:115]
	v_mfma_f32_16x16x32_bf16 v[100:103], v[144:147], v[168:171], v[100:103]
	v_mfma_f32_16x16x32_bf16 v[96:99], v[152:155], v[168:171], v[96:99]
	v_mfma_f32_16x16x32_bf16 v[84:87], v[144:147], v[176:179], v[84:87]
	v_mfma_f32_16x16x32_bf16 v[80:83], v[152:155], v[176:179], v[80:83]
	v_mfma_f32_16x16x32_bf16 v[68:71], v[144:147], v[220:223], v[68:71]
	v_mfma_f32_16x16x32_bf16 v[64:67], v[152:155], v[220:223], v[64:67]
	v_mfma_f32_16x16x32_bf16 v[116:119], v[148:151], v[164:167], v[116:119]
	v_mfma_f32_16x16x32_bf16 v[112:115], v[156:159], v[164:167], v[112:115]
	v_mfma_f32_16x16x32_bf16 v[100:103], v[148:151], v[172:175], v[100:103]
	v_mfma_f32_16x16x32_bf16 v[96:99], v[156:159], v[172:175], v[96:99]
	v_mfma_f32_16x16x32_bf16 v[84:87], v[148:151], v[180:183], v[84:87]
	v_mfma_f32_16x16x32_bf16 v[80:83], v[156:159], v[180:183], v[80:83]
	v_mfma_f32_16x16x32_bf16 v[68:71], v[148:151], v[224:227], v[68:71]
	v_mfma_f32_16x16x32_bf16 v[64:67], v[156:159], v[224:227], v[64:67]
	s_setprio 0
	s_barrier
	s_add_i32 s73, s85, s14
	v_lshl_add_u64 v[208:209], s[90:91], 0, v[190:191]
	s_mov_b32 m0, s73
	ds_read_b128 v[160:163], v213 offset:16384
	ds_read_b128 v[164:167], v213 offset:17408
	ds_read_b128 v[168:171], v213 offset:18432
	ds_read_b128 v[172:175], v213 offset:19456
	ds_read_b128 v[176:179], v213 offset:20480
	ds_read_b128 v[180:183], v213 offset:21504
	ds_read_b128 v[220:223], v213 offset:22528
	ds_read_b128 v[224:227], v213 offset:23552
	global_load_lds_dwordx4 v[208:209], off
	v_lshl_add_u64 v[228:229], v[208:209], 0, s[10:11]
	s_add_i32 m0, s73, 0x2000
	s_add_i32 s73, s86, s14
	global_load_lds_dwordx4 v[228:229], off
	v_lshl_add_u64 v[228:229], v[208:209], 0, s[34:35]
	s_mov_b32 m0, s73
	s_nop 0
	global_load_lds_dwordx4 v[228:229], off
	v_lshl_add_u64 v[228:229], v[208:209], 0, s[36:37]
	s_add_i32 m0, s73, 0x2000
	s_nop 0
	global_load_lds_dwordx4 v[228:229], off
	v_lshl_add_u64 v[228:229], s[78:79], 0, v[190:191]
	s_mov_b32 m0, s15
	v_lshl_add_u64 v[230:231], v[228:229], 0, s[10:11]
	global_load_lds_dwordx4 v[228:229], off
	s_mov_b32 m0, s17
	s_nop 0
	global_load_lds_dwordx4 v[230:231], off
	s_waitcnt vmcnt(8)
	s_waitcnt lgkmcnt(0)
	s_barrier
; #define PG8_STAGE(bufoff, gbase, voff) do { _Pragma("unroll") for (int _i = 0; _i < 2; ++_i) \
;         __builtin_amdgcn_global_load_lds((const unsigned*)((const char*)(gbase) + (voff)[_i]), (PG8_LAS unsigned*)(lds + (bufoff) + ldsw + _i * 8192), 16, 0, 0); } while (0)
; #define PG8_LDA(dst, b, h) do { _Pragma("unroll") for (int m = 0; m < 4; ++m) _Pragma("unroll") for (int k = 0; k < 2; ++k) dst[m][k] = *(const PG8_LAS bf16x8*)(lds + PG8_SA(b, h) + aoff + m * 2048 + k * 1024); } while (0)
; #define PG8_LDB(dst, b, h) do { _Pragma("unroll") for (int n = 0; n < 2; ++n) _Pragma("unroll") for (int k = 0; k < 2; ++k) dst[n][k] = *(const PG8_LAS bf16x8*)(lds + PG8_SB(b, h) + boff + n * 2048 + k * 1024); } while (0)
; #define PG8_MMA(ai, bj, At, Bt) do { __builtin_amdgcn_s_setprio(1); _Pragma("unroll") for (int m = 0; m < 4; ++m) _Pragma("unroll") for (int n = 0; n < 2; ++n) _Pragma("unroll") for (int k = 0; k < 2; ++k) \
;         acc[ai][bj][m][n] = __builtin_amdgcn_mfma_f32_16x16x32_bf16(Bt[n][k], At[m][k], acc[ai][bj][m][n], 0, 0, 0); __builtin_amdgcn_s_setprio(0); } while (0)
; #define PG8_WAIT_V(n) asm volatile("s_waitcnt vmcnt(" #n ")" ::: "memory")
; #define PG8_WAIT_L(n) asm volatile("s_waitcnt lgkmcnt(" #n ")" ::: "memory")
; #define PG8_BAR __builtin_amdgcn_s_barrier()
; #define PG8_SCHED __builtin_amdgcn_sched_barrier(0)
; template <class Epi, class Sched, bool ALIGN_EPI = false, bool SP2 = false>
; __device__ __forceinline__ void gemm_phase(PG8_LAS unsigned char* lds, const Gemm g, const Sched& S, const Epi& E) {
;     ...
;             PG8_WAIT_V(8); PG8_WAIT_L(0); PG8_BAR; PG8_MMA(1, 0, At, B0); PG8_MMA(1, 1, At, B1); PG8_BAR; PG8_SCHED;
;             PG8_LDB(B0, 1, 0); PG8_LDB(B1, 1, 1); PG8_SCHED; PG8_LDA(At, 1, 0); PG8_STAGE(PG8_SA(0, 1), a2 + hstepA, voffA);
;             PG8_WAIT_V(8); PG8_WAIT_L(0); PG8_BAR; PG8_MMA(0, 0, At, B0); PG8_MMA(0, 1, At, B1); PG8_BAR; PG8_SCHED;
	s_setprio 1
	s_waitcnt lgkmcnt(0)
	v_mfma_f32_16x16x32_bf16 v[60:63], v[128:131], v[160:163], v[60:63]
	v_mfma_f32_16x16x32_bf16 v[56:59], v[136:139], v[160:163], v[56:59]
	v_mfma_f32_16x16x32_bf16 v[44:47], v[128:131], v[168:171], v[44:47]
	v_mfma_f32_16x16x32_bf16 v[40:43], v[136:139], v[168:171], v[40:43]
	v_mfma_f32_16x16x32_bf16 v[28:31], v[128:131], v[176:179], v[28:31]
	v_mfma_f32_16x16x32_bf16 v[24:27], v[136:139], v[176:179], v[24:27]
	v_mfma_f32_16x16x32_bf16 v[12:15], v[128:131], v[220:223], v[12:15]
	v_mfma_f32_16x16x32_bf16 v[8:11], v[136:139], v[220:223], v[8:11]
	v_mfma_f32_16x16x32_bf16 v[60:63], v[132:135], v[164:167], v[60:63]
	v_mfma_f32_16x16x32_bf16 v[56:59], v[140:143], v[164:167], v[56:59]
	v_mfma_f32_16x16x32_bf16 v[44:47], v[132:135], v[172:175], v[44:47]
	v_mfma_f32_16x16x32_bf16 v[40:43], v[140:143], v[172:175], v[40:43]
	v_mfma_f32_16x16x32_bf16 v[28:31], v[132:135], v[180:183], v[28:31]
	v_mfma_f32_16x16x32_bf16 v[24:27], v[140:143], v[180:183], v[24:27]
	v_mfma_f32_16x16x32_bf16 v[12:15], v[132:135], v[224:227], v[12:15]
	v_mfma_f32_16x16x32_bf16 v[8:11], v[140:143], v[224:227], v[8:11]
	v_mfma_f32_16x16x32_bf16 v[52:55], v[144:147], v[160:163], v[52:55]
	v_mfma_f32_16x16x32_bf16 v[48:51], v[152:155], v[160:163], v[48:51]
	v_mfma_f32_16x16x32_bf16 v[36:39], v[144:147], v[168:171], v[36:39]
	v_mfma_f32_16x16x32_bf16 v[32:35], v[152:155], v[168:171], v[32:35]
	v_mfma_f32_16x16x32_bf16 v[20:23], v[144:147], v[176:179], v[20:23]
	v_mfma_f32_16x16x32_bf16 v[16:19], v[152:155], v[176:179], v[16:19]
	v_mfma_f32_16x16x32_bf16 v[4:7], v[144:147], v[220:223], v[4:7]
	v_mfma_f32_16x16x32_bf16 v[0:3], v[152:155], v[220:223], v[0:3]
	v_mfma_f32_16x16x32_bf16 v[52:55], v[148:151], v[164:167], v[52:55]
	v_mfma_f32_16x16x32_bf16 v[48:51], v[156:159], v[164:167], v[48:51]
	v_mfma_f32_16x16x32_bf16 v[36:39], v[148:151], v[172:175], v[36:39]
	v_mfma_f32_16x16x32_bf16 v[32:35], v[156:159], v[172:175], v[32:35]
	v_mfma_f32_16x16x32_bf16 v[20:23], v[148:151], v[180:183], v[20:23]
	v_mfma_f32_16x16x32_bf16 v[16:19], v[156:159], v[180:183], v[16:19]
	v_mfma_f32_16x16x32_bf16 v[4:7], v[148:151], v[224:227], v[4:7]
	v_mfma_f32_16x16x32_bf16 v[0:3], v[156:159], v[224:227], v[0:3]
	s_setprio 0
	s_barrier
	ds_read_b128 v[128:131], v214
	ds_read_b128 v[132:135], v214 offset:1024
	ds_read_b128 v[136:139], v214 offset:2048
	ds_read_b128 v[140:143], v214 offset:3072
	ds_read_b128 v[144:147], v215
	ds_read_b128 v[148:151], v215 offset:1024
	ds_read_b128 v[152:155], v215 offset:2048
	ds_read_b128 v[156:159], v215 offset:3072
	s_mov_b32 m0, s18
	v_lshl_add_u64 v[230:231], v[228:229], 0, s[34:35]
	ds_read_b128 v[160:163], v213 offset:32768
	ds_read_b128 v[164:167], v213 offset:33792
	ds_read_b128 v[168:171], v213 offset:34816
	ds_read_b128 v[172:175], v213 offset:35840
	ds_read_b128 v[176:179], v213 offset:36864
	ds_read_b128 v[180:183], v213 offset:37888
	ds_read_b128 v[220:223], v213 offset:38912
	ds_read_b128 v[224:227], v213 offset:39936
	global_load_lds_dwordx4 v[230:231], off
	v_lshl_add_u64 v[230:231], v[228:229], 0, s[36:37]
	s_mov_b32 m0, s19
	s_nop 0
	global_load_lds_dwordx4 v[230:231], off
	s_waitcnt vmcnt(8)
	s_waitcnt lgkmcnt(0)
	s_barrier
	s_setprio 1
	s_waitcnt lgkmcnt(0)
	v_mfma_f32_16x16x32_bf16 v[124:127], v[128:131], v[160:163], v[124:127]
	v_mfma_f32_16x16x32_bf16 v[120:123], v[136:139], v[160:163], v[120:123]
	v_mfma_f32_16x16x32_bf16 v[108:111], v[128:131], v[168:171], v[108:111]
	v_mfma_f32_16x16x32_bf16 v[104:107], v[136:139], v[168:171], v[104:107]
	v_mfma_f32_16x16x32_bf16 v[92:95], v[128:131], v[176:179], v[92:95]
	v_mfma_f32_16x16x32_bf16 v[88:91], v[136:139], v[176:179], v[88:91]
	v_mfma_f32_16x16x32_bf16 v[76:79], v[128:131], v[220:223], v[76:79]
	v_mfma_f32_16x16x32_bf16 v[72:75], v[136:139], v[220:223], v[72:75]
	v_mfma_f32_16x16x32_bf16 v[124:127], v[132:135], v[164:167], v[124:127]
	v_mfma_f32_16x16x32_bf16 v[120:123], v[140:143], v[164:167], v[120:123]
	v_mfma_f32_16x16x32_bf16 v[108:111], v[132:135], v[172:175], v[108:111]
	v_mfma_f32_16x16x32_bf16 v[104:107], v[140:143], v[172:175], v[104:107]
	v_mfma_f32_16x16x32_bf16 v[92:95], v[132:135], v[180:183], v[92:95]
	v_mfma_f32_16x16x32_bf16 v[88:91], v[140:143], v[180:183], v[88:91]
	v_mfma_f32_16x16x32_bf16 v[76:79], v[132:135], v[224:227], v[76:79]
	v_mfma_f32_16x16x32_bf16 v[72:75], v[140:143], v[224:227], v[72:75]
	v_mfma_f32_16x16x32_bf16 v[116:119], v[144:147], v[160:163], v[116:119]
	v_mfma_f32_16x16x32_bf16 v[112:115], v[152:155], v[160:163], v[112:115]
	v_mfma_f32_16x16x32_bf16 v[100:103], v[144:147], v[168:171], v[100:103]
	v_mfma_f32_16x16x32_bf16 v[96:99], v[152:155], v[168:171], v[96:99]
	v_mfma_f32_16x16x32_bf16 v[84:87], v[144:147], v[176:179], v[84:87]
	v_mfma_f32_16x16x32_bf16 v[80:83], v[152:155], v[176:179], v[80:83]
	v_mfma_f32_16x16x32_bf16 v[68:71], v[144:147], v[220:223], v[68:71]
	v_mfma_f32_16x16x32_bf16 v[64:67], v[152:155], v[220:223], v[64:67]
	v_mfma_f32_16x16x32_bf16 v[116:119], v[148:151], v[164:167], v[116:119]
	v_mfma_f32_16x16x32_bf16 v[112:115], v[156:159], v[164:167], v[112:115]
	v_mfma_f32_16x16x32_bf16 v[100:103], v[148:151], v[172:175], v[100:103]
	v_mfma_f32_16x16x32_bf16 v[96:99], v[156:159], v[172:175], v[96:99]
	v_mfma_f32_16x16x32_bf16 v[84:87], v[148:151], v[180:183], v[84:87]
	v_mfma_f32_16x16x32_bf16 v[80:83], v[156:159], v[180:183], v[80:83]
	v_mfma_f32_16x16x32_bf16 v[68:71], v[148:151], v[224:227], v[68:71]
	v_mfma_f32_16x16x32_bf16 v[64:67], v[156:159], v[224:227], v[64:67]
	s_setprio 0
	s_barrier
; #define PG8_STAGE(bufoff, gbase, voff) do { _Pragma("unroll") for (int _i = 0; _i < 2; ++_i) \
;         __builtin_amdgcn_global_load_lds((const unsigned*)((const char*)(gbase) + (voff)[_i]), (PG8_LAS unsigned*)(lds + (bufoff) + ldsw + _i * 8192), 16, 0, 0); } while (0)
; #define PG8_LDA(dst, b, h) do { _Pragma("unroll") for (int m = 0; m < 4; ++m) _Pragma("unroll") for (int k = 0; k < 2; ++k) dst[m][k] = *(const PG8_LAS bf16x8*)(lds + PG8_SA(b, h) + aoff + m * 2048 + k * 1024); } while (0)
; #define PG8_MMA(ai, bj, At, Bt) do { __builtin_amdgcn_s_setprio(1); _Pragma("unroll") for (int m = 0; m < 4; ++m) _Pragma("unroll") for (int n = 0; n < 2; ++n) _Pragma("unroll") for (int k = 0; k < 2; ++k) \
;         acc[ai][bj][m][n] = __builtin_amdgcn_mfma_f32_16x16x32_bf16(Bt[n][k], At[m][k], acc[ai][bj][m][n], 0, 0, 0); __builtin_amdgcn_s_setprio(0); } while (0)
; #define PG8_WAIT_V(n) asm volatile("s_waitcnt vmcnt(" #n ")" ::: "memory")
; #define PG8_WAIT_L(n) asm volatile("s_waitcnt lgkmcnt(" #n ")" ::: "memory")
; #define PG8_BAR __builtin_amdgcn_s_barrier()
; #define PG8_SCHED __builtin_amdgcn_sched_barrier(0)
; template <class Epi, class Sched, bool ALIGN_EPI = false, bool SP2 = false>
; __device__ __forceinline__ void gemm_phase(PG8_LAS unsigned char* lds, const Gemm g, const Sched& S, const Epi& E) {
;     ...
;             PG8_LDA(At, 1, 1); PG8_STAGE(PG8_SB(1, 0), b3, voffB); PG8_STAGE(PG8_SB(1, 1), b3 + hstepB, voffB); PG8_STAGE(PG8_SA(1, 0), a3, voffA);
;             PG8_WAIT_V(8); PG8_WAIT_L(0); PG8_BAR; PG8_MMA(1, 0, At, B0); PG8_MMA(1, 1, At, B1); PG8_BAR; PG8_SCHED;
	s_add_i32 s73, s87, s14
	v_lshl_add_u64 v[230:231], v[208:209], 0, s[38:39]
	s_mov_b32 m0, s73
	ds_read_b128 v[160:163], v213 offset:49152
	ds_read_b128 v[164:167], v213 offset:50176
	ds_read_b128 v[168:171], v213 offset:51200
	ds_read_b128 v[172:175], v213 offset:52224
	ds_read_b128 v[176:179], v213 offset:53248
	ds_read_b128 v[180:183], v213 offset:54272
	ds_read_b128 v[220:223], v213 offset:55296
	ds_read_b128 v[224:227], v213 offset:56320
	global_load_lds_dwordx4 v[230:231], off
	v_lshl_add_u64 v[230:231], v[208:209], 0, s[40:41]
	s_add_i32 m0, s73, 0x2000
	s_add_i32 s73, s88, s14
	global_load_lds_dwordx4 v[230:231], off
	v_lshl_add_u64 v[230:231], v[208:209], 0, s[42:43]
	s_mov_b32 m0, s73
	v_lshl_add_u64 v[208:209], v[208:209], 0, s[44:45]
	global_load_lds_dwordx4 v[230:231], off
	s_add_i32 m0, s73, 0x2000
	s_nop 0
	global_load_lds_dwordx4 v[208:209], off
	v_lshl_add_u64 v[208:209], v[228:229], 0, s[38:39]
	s_mov_b32 m0, s74
	s_nop 0
	global_load_lds_dwordx4 v[208:209], off
	v_lshl_add_u64 v[208:209], v[228:229], 0, s[40:41]
	s_mov_b32 m0, s75
	s_nop 0
	global_load_lds_dwordx4 v[208:209], off
	s_waitcnt vmcnt(8)
	s_waitcnt lgkmcnt(0)
	s_barrier
	s_setprio 1
	s_waitcnt lgkmcnt(0)
	v_mfma_f32_16x16x32_bf16 v[60:63], v[128:131], v[160:163], v[60:63]
	v_mfma_f32_16x16x32_bf16 v[56:59], v[136:139], v[160:163], v[56:59]
	v_mfma_f32_16x16x32_bf16 v[44:47], v[128:131], v[168:171], v[44:47]
	v_mfma_f32_16x16x32_bf16 v[40:43], v[136:139], v[168:171], v[40:43]
	v_mfma_f32_16x16x32_bf16 v[28:31], v[128:131], v[176:179], v[28:31]
	v_mfma_f32_16x16x32_bf16 v[24:27], v[136:139], v[176:179], v[24:27]
	v_mfma_f32_16x16x32_bf16 v[12:15], v[128:131], v[220:223], v[12:15]
	v_mfma_f32_16x16x32_bf16 v[8:11], v[136:139], v[220:223], v[8:11]
	v_mfma_f32_16x16x32_bf16 v[60:63], v[132:135], v[164:167], v[60:63]
	v_mfma_f32_16x16x32_bf16 v[56:59], v[140:143], v[164:167], v[56:59]
	v_mfma_f32_16x16x32_bf16 v[44:47], v[132:135], v[172:175], v[44:47]
	v_mfma_f32_16x16x32_bf16 v[40:43], v[140:143], v[172:175], v[40:43]
	v_mfma_f32_16x16x32_bf16 v[28:31], v[132:135], v[180:183], v[28:31]
	v_mfma_f32_16x16x32_bf16 v[24:27], v[140:143], v[180:183], v[24:27]
	v_mfma_f32_16x16x32_bf16 v[12:15], v[132:135], v[224:227], v[12:15]
	v_mfma_f32_16x16x32_bf16 v[8:11], v[140:143], v[224:227], v[8:11]
	v_mfma_f32_16x16x32_bf16 v[52:55], v[144:147], v[160:163], v[52:55]
	v_mfma_f32_16x16x32_bf16 v[48:51], v[152:155], v[160:163], v[48:51]
	v_mfma_f32_16x16x32_bf16 v[36:39], v[144:147], v[168:171], v[36:39]
	v_mfma_f32_16x16x32_bf16 v[32:35], v[152:155], v[168:171], v[32:35]
	v_mfma_f32_16x16x32_bf16 v[20:23], v[144:147], v[176:179], v[20:23]
	v_mfma_f32_16x16x32_bf16 v[16:19], v[152:155], v[176:179], v[16:19]
	v_mfma_f32_16x16x32_bf16 v[4:7], v[144:147], v[220:223], v[4:7]
	v_mfma_f32_16x16x32_bf16 v[0:3], v[152:155], v[220:223], v[0:3]
	v_mfma_f32_16x16x32_bf16 v[52:55], v[148:151], v[164:167], v[52:55]
	v_mfma_f32_16x16x32_bf16 v[48:51], v[156:159], v[164:167], v[48:51]
	v_mfma_f32_16x16x32_bf16 v[36:39], v[148:151], v[172:175], v[36:39]
	v_mfma_f32_16x16x32_bf16 v[32:35], v[156:159], v[172:175], v[32:35]
	v_mfma_f32_16x16x32_bf16 v[20:23], v[148:151], v[180:183], v[20:23]
	v_mfma_f32_16x16x32_bf16 v[16:19], v[156:159], v[180:183], v[16:19]
	v_mfma_f32_16x16x32_bf16 v[4:7], v[148:151], v[224:227], v[4:7]
	v_mfma_f32_16x16x32_bf16 v[0:3], v[156:159], v[224:227], v[0:3]
	s_setprio 0
	s_barrier
	s_add_i32 s72, s72, 2
	s_add_u32 s68, s68, 0x10000
	s_addc_u32 s69, s69, 0
	s_add_u32 s70, s70, 0x10000
	s_addc_u32 s71, s71, 0
	s_cmp_gt_u32 s72, 13
	s_cbranch_scc0 .LBB0_751
	s_and_b64 vcc, exec, s[48:49]
	s_cbranch_vccz .LBB0_754
	s_barrier

; #define PG8_STAGE(bufoff, gbase, voff) do { _Pragma("unroll") for (int _i = 0; _i < 2; ++_i) \
;         __builtin_amdgcn_global_load_lds((const unsigned*)((const char*)(gbase) + (voff)[_i]), (PG8_LAS unsigned*)(lds + (bufoff) + ldsw + _i * 8192), 16, 0, 0); } while (0)
; #define PG8_LDA(dst, b, h) do { _Pragma("unroll") for (int m = 0; m < 4; ++m) _Pragma("unroll") for (int k = 0; k < 2; ++k) dst[m][k] = *(const PG8_LAS bf16x8*)(lds + PG8_SA(b, h) + aoff + m * 2048 + k * 1024); } while (0)
; #define PG8_LDB(dst, b, h) do { _Pragma("unroll") for (int n = 0; n < 2; ++n) _Pragma("unroll") for (int k = 0; k < 2; ++k) dst[n][k] = *(const PG8_LAS bf16x8*)(lds + PG8_SB(b, h) + boff + n * 2048 + k * 1024); } while (0)
; #define PG8_MMA(ai, bj, At, Bt) do { __builtin_amdgcn_s_setprio(1); _Pragma("unroll") for (int m = 0; m < 4; ++m) _Pragma("unroll") for (int n = 0; n < 2; ++n) _Pragma("unroll") for (int k = 0; k < 2; ++k) \
;         acc[ai][bj][m][n] = __builtin_amdgcn_mfma_f32_16x16x32_bf16(Bt[n][k], At[m][k], acc[ai][bj][m][n], 0, 0, 0); __builtin_amdgcn_s_setprio(0); } while (0)
; #define PG8_WAIT_V(n) asm volatile("s_waitcnt vmcnt(" #n ")" ::: "memory")
; #define PG8_WAIT_L(n) asm volatile("s_waitcnt lgkmcnt(" #n ")" ::: "memory")
; #define PG8_BAR __builtin_amdgcn_s_barrier()
; template <class Epi, class Sched, bool ALIGN_EPI = false, bool SP2 = false>
; __device__ __forceinline__ void gemm_phase(PG8_LAS unsigned char* lds, const Gemm g, const Sched& S, const Epi& E) {
;     ...
;             const char* a1 = cA + (size_t)(t + 1) * kstepA;
;             const char* a2 = last ? nA : cA + (size_t)(t + 2) * kstepA; const char* b2 = last ? nB : cB + (size_t)(t + 2) * kstep;
;             const char* a3 = a2 + kstepA; const char* b3 = b2 + kstep;
;             if (last && has_next) S.a_ready(nxt);
;             if constexpr (SP2) {
;             PG8_LDB(B0, 0, 0); PG8_LDB(B1, 0, 1); PG8_SCHED; PG8_LDA(At, 0, 0); PG8_STAGE(PG8_SA(1, 1), a1 + hstepA, voffA);
;             PG8_WAIT_V(8); PG8_WAIT_L(0); PG8_BAR; PG8_MMA(0, 0, At, B0); PG8_MMA(0, 1, At, B1); PG8_BAR; PG8_SCHED;
;             PG8_LDA(At, 0, 1); PG8_STAGE(PG8_SB(0, 0), b2, voffB); PG8_STAGE(PG8_SB(0, 1), b2 + hstepB, voffB); PG8_STAGE(PG8_SA(0, 0), a2, voffA);
;             PG8_WAIT_V(8); PG8_WAIT_L(0); PG8_BAR; PG8_MMA(1, 0, At, B0); PG8_MMA(1, 1, At, B1); PG8_BAR; PG8_SCHED;
.LBB0_838:
	ds_read_b128 v[148:151], v141
	ds_read_b128 v[152:155], v141 offset:1024
	ds_read_b128 v[156:159], v141 offset:2048
	ds_read_b128 v[160:163], v141 offset:3072
	ds_read_b128 v[164:167], v142
	ds_read_b128 v[168:171], v142 offset:1024
	ds_read_b128 v[172:175], v142 offset:2048
	ds_read_b128 v[176:179], v142 offset:3072
	s_cmp_eq_u32 s82, 12
	s_cselect_b32 s79, s55, s63
	s_cselect_b32 s78, s80, s62
	s_cselect_b32 s85, s53, s65
	s_cselect_b32 s84, s81, s64
	v_lshl_add_u64 v[216:217], s[62:63], 0, v[190:191]
	v_lshl_add_u64 v[220:221], v[216:217], 0, s[46:47]
	s_add_i32 m0, s18, 0xc000
	ds_read_b128 v[180:183], v143
	ds_read_b128 v[184:187], v143 offset:1024
	ds_read_b128 v[192:195], v143 offset:2048
	ds_read_b128 v[196:199], v143 offset:3072
	ds_read_b128 v[200:203], v143 offset:4096
	ds_read_b128 v[204:207], v143 offset:5120
	ds_read_b128 v[208:211], v143 offset:6144
	ds_read_b128 v[212:215], v143 offset:7168
	global_load_lds_dwordx4 v[220:221], off
	v_lshl_add_u64 v[216:217], v[216:217], 0, s[48:49]
	s_add_i32 m0, s18, 0xe000
	s_nop 0
	global_load_lds_dwordx4 v[216:217], off
	s_waitcnt vmcnt(8)
	s_waitcnt lgkmcnt(0)
	s_barrier
	s_setprio 1
	s_waitcnt lgkmcnt(0)
	v_mfma_f32_16x16x32_bf16 v[116:119], v[148:151], v[180:183], v[116:119]
	v_mfma_f32_16x16x32_bf16 v[112:115], v[156:159], v[180:183], v[112:115]
	v_mfma_f32_16x16x32_bf16 v[108:111], v[148:151], v[192:195], v[108:111]
	v_mfma_f32_16x16x32_bf16 v[100:103], v[156:159], v[192:195], v[100:103]
	v_mfma_f32_16x16x32_bf16 v[92:95], v[148:151], v[200:203], v[92:95]
	v_mfma_f32_16x16x32_bf16 v[84:87], v[156:159], v[200:203], v[84:87]
	v_mfma_f32_16x16x32_bf16 v[76:79], v[148:151], v[208:211], v[76:79]
	v_mfma_f32_16x16x32_bf16 v[68:71], v[156:159], v[208:211], v[68:71]
	v_mfma_f32_16x16x32_bf16 v[116:119], v[152:155], v[184:187], v[116:119]
	v_mfma_f32_16x16x32_bf16 v[112:115], v[160:163], v[184:187], v[112:115]
	v_mfma_f32_16x16x32_bf16 v[108:111], v[152:155], v[196:199], v[108:111]
	v_mfma_f32_16x16x32_bf16 v[100:103], v[160:163], v[196:199], v[100:103]
	v_mfma_f32_16x16x32_bf16 v[92:95], v[152:155], v[204:207], v[92:95]
	v_mfma_f32_16x16x32_bf16 v[84:87], v[160:163], v[204:207], v[84:87]
	v_mfma_f32_16x16x32_bf16 v[76:79], v[152:155], v[212:215], v[76:79]
	v_mfma_f32_16x16x32_bf16 v[68:71], v[160:163], v[212:215], v[68:71]
	v_mfma_f32_16x16x32_bf16 v[124:127], v[164:167], v[180:183], v[124:127]
	v_mfma_f32_16x16x32_bf16 v[120:123], v[172:175], v[180:183], v[120:123]
	v_mfma_f32_16x16x32_bf16 v[104:107], v[164:167], v[192:195], v[104:107]
	v_mfma_f32_16x16x32_bf16 v[96:99], v[172:175], v[192:195], v[96:99]
	v_mfma_f32_16x16x32_bf16 v[88:91], v[164:167], v[200:203], v[88:91]
	v_mfma_f32_16x16x32_bf16 v[80:83], v[172:175], v[200:203], v[80:83]
	v_mfma_f32_16x16x32_bf16 v[72:75], v[164:167], v[208:211], v[72:75]
	v_mfma_f32_16x16x32_bf16 v[64:67], v[172:175], v[208:211], v[64:67]
	v_mfma_f32_16x16x32_bf16 v[124:127], v[168:171], v[184:187], v[124:127]
	v_mfma_f32_16x16x32_bf16 v[120:123], v[176:179], v[184:187], v[120:123]
	v_mfma_f32_16x16x32_bf16 v[104:107], v[168:171], v[196:199], v[104:107]
	v_mfma_f32_16x16x32_bf16 v[96:99], v[176:179], v[196:199], v[96:99]
	v_mfma_f32_16x16x32_bf16 v[88:91], v[168:171], v[204:207], v[88:91]
	v_mfma_f32_16x16x32_bf16 v[80:83], v[176:179], v[204:207], v[80:83]
	v_mfma_f32_16x16x32_bf16 v[72:75], v[168:171], v[212:215], v[72:75]
	v_mfma_f32_16x16x32_bf16 v[64:67], v[176:179], v[212:215], v[64:67]
	s_setprio 0
	s_barrier
	v_lshl_add_u64 v[216:217], s[84:85], 0, v[190:191]
	s_add_i32 s84, s74, s14
	s_mov_b32 m0, s84
	ds_read_b128 v[180:183], v143 offset:16384
	ds_read_b128 v[184:187], v143 offset:17408
	ds_read_b128 v[192:195], v143 offset:18432
	ds_read_b128 v[196:199], v143 offset:19456
	ds_read_b128 v[200:203], v143 offset:20480
	ds_read_b128 v[204:207], v143 offset:21504
	ds_read_b128 v[208:211], v143 offset:22528
	ds_read_b128 v[212:215], v143 offset:23552
	global_load_lds_dwordx4 v[216:217], off
	v_lshl_add_u64 v[220:221], v[216:217], 0, s[6:7]
	s_add_i32 m0, s84, 0x2000
	s_add_i32 s84, s75, s14
	global_load_lds_dwordx4 v[220:221], off
	v_lshl_add_u64 v[220:221], v[216:217], 0, s[8:9]
	s_mov_b32 m0, s84
	s_nop 0
	global_load_lds_dwordx4 v[220:221], off
	v_lshl_add_u64 v[220:221], v[216:217], 0, s[10:11]
	s_add_i32 m0, s84, 0x2000
	s_nop 0
	global_load_lds_dwordx4 v[220:221], off
	v_lshl_add_u64 v[220:221], s[78:79], 0, v[190:191]
	s_mov_b32 m0, s18
	v_lshl_add_u64 v[222:223], v[220:221], 0, s[6:7]
	global_load_lds_dwordx4 v[220:221], off
	s_mov_b32 m0, s19
	s_nop 0
	global_load_lds_dwordx4 v[222:223], off
	s_waitcnt vmcnt(8)
	s_waitcnt lgkmcnt(0)
	s_barrier
; #define PG8_STAGE(bufoff, gbase, voff) do { _Pragma("unroll") for (int _i = 0; _i < 2; ++_i) \
;         __builtin_amdgcn_global_load_lds((const unsigned*)((const char*)(gbase) + (voff)[_i]), (PG8_LAS unsigned*)(lds + (bufoff) + ldsw + _i * 8192), 16, 0, 0); } while (0)
; #define PG8_LDA(dst, b, h) do { _Pragma("unroll") for (int m = 0; m < 4; ++m) _Pragma("unroll") for (int k = 0; k < 2; ++k) dst[m][k] = *(const PG8_LAS bf16x8*)(lds + PG8_SA(b, h) + aoff + m * 2048 + k * 1024); } while (0)
; #define PG8_LDB(dst, b, h) do { _Pragma("unroll") for (int n = 0; n < 2; ++n) _Pragma("unroll") for (int k = 0; k < 2; ++k) dst[n][k] = *(const PG8_LAS bf16x8*)(lds + PG8_SB(b, h) + boff + n * 2048 + k * 1024); } while (0)
; #define PG8_MMA(ai, bj, At, Bt) do { __builtin_amdgcn_s_setprio(1); _Pragma("unroll") for (int m = 0; m < 4; ++m) _Pragma("unroll") for (int n = 0; n < 2; ++n) _Pragma("unroll") for (int k = 0; k < 2; ++k) \
;         acc[ai][bj][m][n] = __builtin_amdgcn_mfma_f32_16x16x32_bf16(Bt[n][k], At[m][k], acc[ai][bj][m][n], 0, 0, 0); __builtin_amdgcn_s_setprio(0); } while (0)
; #define PG8_WAIT_V(n) asm volatile("s_waitcnt vmcnt(" #n ")" ::: "memory")
; #define PG8_WAIT_L(n) asm volatile("s_waitcnt lgkmcnt(" #n ")" ::: "memory")
; #define PG8_BAR __builtin_amdgcn_s_barrier()
; #define PG8_SCHED __builtin_amdgcn_sched_barrier(0)
; template <class Epi, class Sched, bool ALIGN_EPI = false, bool SP2 = false>
; __device__ __forceinline__ void gemm_phase(PG8_LAS unsigned char* lds, const Gemm g, const Sched& S, const Epi& E) {
;     ...
;             PG8_WAIT_V(8); PG8_WAIT_L(0); PG8_BAR; PG8_MMA(1, 0, At, B0); PG8_MMA(1, 1, At, B1); PG8_BAR; PG8_SCHED;
;             PG8_LDB(B0, 1, 0); PG8_LDB(B1, 1, 1); PG8_SCHED; PG8_LDA(At, 1, 0); PG8_STAGE(PG8_SA(0, 1), a2 + hstepA, voffA);
;             PG8_WAIT_V(8); PG8_WAIT_L(0); PG8_BAR; PG8_MMA(0, 0, At, B0); PG8_MMA(0, 1, At, B1); PG8_BAR; PG8_SCHED;
	s_setprio 1
	s_waitcnt lgkmcnt(0)
	v_mfma_f32_16x16x32_bf16 v[60:63], v[148:151], v[180:183], v[60:63]
	v_mfma_f32_16x16x32_bf16 v[52:55], v[156:159], v[180:183], v[52:55]
	v_mfma_f32_16x16x32_bf16 v[44:47], v[148:151], v[192:195], v[44:47]
	v_mfma_f32_16x16x32_bf16 v[36:39], v[156:159], v[192:195], v[36:39]
	v_mfma_f32_16x16x32_bf16 v[28:31], v[148:151], v[200:203], v[28:31]
	v_mfma_f32_16x16x32_bf16 v[20:23], v[156:159], v[200:203], v[20:23]
	v_mfma_f32_16x16x32_bf16 v[12:15], v[148:151], v[208:211], v[12:15]
	v_mfma_f32_16x16x32_bf16 v[4:7], v[156:159], v[208:211], v[4:7]
	v_mfma_f32_16x16x32_bf16 v[60:63], v[152:155], v[184:187], v[60:63]
	v_mfma_f32_16x16x32_bf16 v[52:55], v[160:163], v[184:187], v[52:55]
	v_mfma_f32_16x16x32_bf16 v[44:47], v[152:155], v[196:199], v[44:47]
	v_mfma_f32_16x16x32_bf16 v[36:39], v[160:163], v[196:199], v[36:39]
	v_mfma_f32_16x16x32_bf16 v[28:31], v[152:155], v[204:207], v[28:31]
	v_mfma_f32_16x16x32_bf16 v[20:23], v[160:163], v[204:207], v[20:23]
	v_mfma_f32_16x16x32_bf16 v[12:15], v[152:155], v[212:215], v[12:15]
	v_mfma_f32_16x16x32_bf16 v[4:7], v[160:163], v[212:215], v[4:7]
	v_mfma_f32_16x16x32_bf16 v[56:59], v[164:167], v[180:183], v[56:59]
	v_mfma_f32_16x16x32_bf16 v[48:51], v[172:175], v[180:183], v[48:51]
	v_mfma_f32_16x16x32_bf16 v[40:43], v[164:167], v[192:195], v[40:43]
	v_mfma_f32_16x16x32_bf16 v[32:35], v[172:175], v[192:195], v[32:35]
	v_mfma_f32_16x16x32_bf16 v[24:27], v[164:167], v[200:203], v[24:27]
	v_mfma_f32_16x16x32_bf16 v[16:19], v[172:175], v[200:203], v[16:19]
	v_mfma_f32_16x16x32_bf16 v[8:11], v[164:167], v[208:211], v[8:11]
	v_mfma_f32_16x16x32_bf16 v[0:3], v[172:175], v[208:211], v[0:3]
	v_mfma_f32_16x16x32_bf16 v[56:59], v[168:171], v[184:187], v[56:59]
	v_mfma_f32_16x16x32_bf16 v[48:51], v[176:179], v[184:187], v[48:51]
	v_mfma_f32_16x16x32_bf16 v[40:43], v[168:171], v[196:199], v[40:43]
	v_mfma_f32_16x16x32_bf16 v[32:35], v[176:179], v[196:199], v[32:35]
	v_mfma_f32_16x16x32_bf16 v[24:27], v[168:171], v[204:207], v[24:27]
	v_mfma_f32_16x16x32_bf16 v[16:19], v[176:179], v[204:207], v[16:19]
	v_mfma_f32_16x16x32_bf16 v[8:11], v[168:171], v[212:215], v[8:11]
	v_mfma_f32_16x16x32_bf16 v[0:3], v[176:179], v[212:215], v[0:3]
	s_setprio 0
	s_barrier
	ds_read_b128 v[148:151], v144
	ds_read_b128 v[152:155], v144 offset:1024
	ds_read_b128 v[156:159], v144 offset:2048
	ds_read_b128 v[160:163], v144 offset:3072
	ds_read_b128 v[164:167], v145
	ds_read_b128 v[168:171], v145 offset:1024
	ds_read_b128 v[172:175], v145 offset:2048
	ds_read_b128 v[176:179], v145 offset:3072
	s_mov_b32 m0, s66
	v_lshl_add_u64 v[222:223], v[220:221], 0, s[8:9]
	ds_read_b128 v[180:183], v143 offset:32768
	ds_read_b128 v[184:187], v143 offset:33792
	ds_read_b128 v[192:195], v143 offset:34816
	ds_read_b128 v[196:199], v143 offset:35840
	ds_read_b128 v[200:203], v143 offset:36864
	ds_read_b128 v[204:207], v143 offset:37888
	ds_read_b128 v[208:211], v143 offset:38912
	ds_read_b128 v[212:215], v143 offset:39936
	global_load_lds_dwordx4 v[222:223], off
	v_lshl_add_u64 v[222:223], v[220:221], 0, s[10:11]
	s_mov_b32 m0, s67
	s_nop 0
	global_load_lds_dwordx4 v[222:223], off
	s_waitcnt vmcnt(8)
	s_waitcnt lgkmcnt(0)
	s_barrier
	s_setprio 1
	s_waitcnt lgkmcnt(0)
	v_mfma_f32_16x16x32_bf16 v[116:119], v[148:151], v[180:183], v[116:119]
	v_mfma_f32_16x16x32_bf16 v[112:115], v[156:159], v[180:183], v[112:115]
	v_mfma_f32_16x16x32_bf16 v[108:111], v[148:151], v[192:195], v[108:111]
	v_mfma_f32_16x16x32_bf16 v[100:103], v[156:159], v[192:195], v[100:103]
	v_mfma_f32_16x16x32_bf16 v[92:95], v[148:151], v[200:203], v[92:95]
	v_mfma_f32_16x16x32_bf16 v[84:87], v[156:159], v[200:203], v[84:87]
	v_mfma_f32_16x16x32_bf16 v[76:79], v[148:151], v[208:211], v[76:79]
	v_mfma_f32_16x16x32_bf16 v[68:71], v[156:159], v[208:211], v[68:71]
	v_mfma_f32_16x16x32_bf16 v[116:119], v[152:155], v[184:187], v[116:119]
	v_mfma_f32_16x16x32_bf16 v[112:115], v[160:163], v[184:187], v[112:115]
	v_mfma_f32_16x16x32_bf16 v[108:111], v[152:155], v[196:199], v[108:111]
	v_mfma_f32_16x16x32_bf16 v[100:103], v[160:163], v[196:199], v[100:103]
	v_mfma_f32_16x16x32_bf16 v[92:95], v[152:155], v[204:207], v[92:95]
	v_mfma_f32_16x16x32_bf16 v[84:87], v[160:163], v[204:207], v[84:87]
	v_mfma_f32_16x16x32_bf16 v[76:79], v[152:155], v[212:215], v[76:79]
	v_mfma_f32_16x16x32_bf16 v[68:71], v[160:163], v[212:215], v[68:71]
	v_mfma_f32_16x16x32_bf16 v[124:127], v[164:167], v[180:183], v[124:127]
	v_mfma_f32_16x16x32_bf16 v[120:123], v[172:175], v[180:183], v[120:123]
	v_mfma_f32_16x16x32_bf16 v[104:107], v[164:167], v[192:195], v[104:107]
	v_mfma_f32_16x16x32_bf16 v[96:99], v[172:175], v[192:195], v[96:99]
	v_mfma_f32_16x16x32_bf16 v[88:91], v[164:167], v[200:203], v[88:91]
	v_mfma_f32_16x16x32_bf16 v[80:83], v[172:175], v[200:203], v[80:83]
	v_mfma_f32_16x16x32_bf16 v[72:75], v[164:167], v[208:211], v[72:75]
	v_mfma_f32_16x16x32_bf16 v[64:67], v[172:175], v[208:211], v[64:67]
	v_mfma_f32_16x16x32_bf16 v[124:127], v[168:171], v[184:187], v[124:127]
	v_mfma_f32_16x16x32_bf16 v[120:123], v[176:179], v[184:187], v[120:123]
	v_mfma_f32_16x16x32_bf16 v[104:107], v[168:171], v[196:199], v[104:107]
	v_mfma_f32_16x16x32_bf16 v[96:99], v[176:179], v[196:199], v[96:99]
	v_mfma_f32_16x16x32_bf16 v[88:91], v[168:171], v[204:207], v[88:91]
	v_mfma_f32_16x16x32_bf16 v[80:83], v[176:179], v[204:207], v[80:83]
	v_mfma_f32_16x16x32_bf16 v[72:75], v[168:171], v[212:215], v[72:75]
	v_mfma_f32_16x16x32_bf16 v[64:67], v[176:179], v[212:215], v[64:67]
	s_setprio 0
	s_barrier
; #define PG8_STAGE(bufoff, gbase, voff) do { _Pragma("unroll") for (int _i = 0; _i < 2; ++_i) \
;         __builtin_amdgcn_global_load_lds((const unsigned*)((const char*)(gbase) + (voff)[_i]), (PG8_LAS unsigned*)(lds + (bufoff) + ldsw + _i * 8192), 16, 0, 0); } while (0)
; #define PG8_LDA(dst, b, h) do { _Pragma("unroll") for (int m = 0; m < 4; ++m) _Pragma("unroll") for (int k = 0; k < 2; ++k) dst[m][k] = *(const PG8_LAS bf16x8*)(lds + PG8_SA(b, h) + aoff + m * 2048 + k * 1024); } while (0)
; #define PG8_MMA(ai, bj, At, Bt) do { __builtin_amdgcn_s_setprio(1); _Pragma("unroll") for (int m = 0; m < 4; ++m) _Pragma("unroll") for (int n = 0; n < 2; ++n) _Pragma("unroll") for (int k = 0; k < 2; ++k) \
;         acc[ai][bj][m][n] = __builtin_amdgcn_mfma_f32_16x16x32_bf16(Bt[n][k], At[m][k], acc[ai][bj][m][n], 0, 0, 0); __builtin_amdgcn_s_setprio(0); } while (0)
; #define PG8_WAIT_V(n) asm volatile("s_waitcnt vmcnt(" #n ")" ::: "memory")
; #define PG8_WAIT_L(n) asm volatile("s_waitcnt lgkmcnt(" #n ")" ::: "memory")
; #define PG8_BAR __builtin_amdgcn_s_barrier()
; #define PG8_SCHED __builtin_amdgcn_sched_barrier(0)
; template <class Epi, class Sched, bool ALIGN_EPI = false, bool SP2 = false>
; __device__ __forceinline__ void gemm_phase(PG8_LAS unsigned char* lds, const Gemm g, const Sched& S, const Epi& E) {
;     ...
;             PG8_LDA(At, 1, 1); PG8_STAGE(PG8_SB(1, 0), b3, voffB); PG8_STAGE(PG8_SB(1, 1), b3 + hstepB, voffB); PG8_STAGE(PG8_SA(1, 0), a3, voffA);
;             PG8_WAIT_V(8); PG8_WAIT_L(0); PG8_BAR; PG8_MMA(1, 0, At, B0); PG8_MMA(1, 1, At, B1); PG8_BAR; PG8_SCHED;
	s_add_i32 s78, s76, s14
	v_lshl_add_u64 v[222:223], v[216:217], 0, s[34:35]
	s_mov_b32 m0, s78
	ds_read_b128 v[180:183], v143 offset:49152
	ds_read_b128 v[184:187], v143 offset:50176
	ds_read_b128 v[192:195], v143 offset:51200
	ds_read_b128 v[196:199], v143 offset:52224
	ds_read_b128 v[200:203], v143 offset:53248
	ds_read_b128 v[204:207], v143 offset:54272
	ds_read_b128 v[208:211], v143 offset:55296
	ds_read_b128 v[212:215], v143 offset:56320
	global_load_lds_dwordx4 v[222:223], off
	v_lshl_add_u64 v[222:223], v[216:217], 0, s[36:37]
	s_add_i32 m0, s78, 0x2000
	s_add_i32 s78, s77, s14
	global_load_lds_dwordx4 v[222:223], off
	v_lshl_add_u64 v[222:223], v[216:217], 0, s[38:39]
	s_mov_b32 m0, s78
	v_lshl_add_u64 v[216:217], v[216:217], 0, s[40:41]
	global_load_lds_dwordx4 v[222:223], off
	s_add_i32 m0, s78, 0x2000
	s_nop 0
	global_load_lds_dwordx4 v[216:217], off
	v_lshl_add_u64 v[216:217], v[220:221], 0, s[34:35]
	s_mov_b32 m0, s68
	s_nop 0
	global_load_lds_dwordx4 v[216:217], off
	v_lshl_add_u64 v[216:217], v[220:221], 0, s[36:37]
	s_mov_b32 m0, s69
	s_nop 0
	global_load_lds_dwordx4 v[216:217], off
	s_waitcnt vmcnt(8)
	s_waitcnt lgkmcnt(0)
	s_barrier
	s_setprio 1
	s_waitcnt lgkmcnt(0)
	v_mfma_f32_16x16x32_bf16 v[60:63], v[148:151], v[180:183], v[60:63]
	v_mfma_f32_16x16x32_bf16 v[52:55], v[156:159], v[180:183], v[52:55]
	v_mfma_f32_16x16x32_bf16 v[44:47], v[148:151], v[192:195], v[44:47]
	v_mfma_f32_16x16x32_bf16 v[36:39], v[156:159], v[192:195], v[36:39]
	v_mfma_f32_16x16x32_bf16 v[28:31], v[148:151], v[200:203], v[28:31]
	v_mfma_f32_16x16x32_bf16 v[20:23], v[156:159], v[200:203], v[20:23]
	v_mfma_f32_16x16x32_bf16 v[12:15], v[148:151], v[208:211], v[12:15]
	v_mfma_f32_16x16x32_bf16 v[4:7], v[156:159], v[208:211], v[4:7]
	v_mfma_f32_16x16x32_bf16 v[60:63], v[152:155], v[184:187], v[60:63]
	v_mfma_f32_16x16x32_bf16 v[52:55], v[160:163], v[184:187], v[52:55]
	v_mfma_f32_16x16x32_bf16 v[44:47], v[152:155], v[196:199], v[44:47]
	v_mfma_f32_16x16x32_bf16 v[36:39], v[160:163], v[196:199], v[36:39]
	v_mfma_f32_16x16x32_bf16 v[28:31], v[152:155], v[204:207], v[28:31]
	v_mfma_f32_16x16x32_bf16 v[20:23], v[160:163], v[204:207], v[20:23]
	v_mfma_f32_16x16x32_bf16 v[12:15], v[152:155], v[212:215], v[12:15]
	v_mfma_f32_16x16x32_bf16 v[4:7], v[160:163], v[212:215], v[4:7]
	v_mfma_f32_16x16x32_bf16 v[56:59], v[164:167], v[180:183], v[56:59]
	v_mfma_f32_16x16x32_bf16 v[48:51], v[172:175], v[180:183], v[48:51]
	v_mfma_f32_16x16x32_bf16 v[40:43], v[164:167], v[192:195], v[40:43]
	v_mfma_f32_16x16x32_bf16 v[32:35], v[172:175], v[192:195], v[32:35]
	v_mfma_f32_16x16x32_bf16 v[24:27], v[164:167], v[200:203], v[24:27]
	v_mfma_f32_16x16x32_bf16 v[16:19], v[172:175], v[200:203], v[16:19]
	v_mfma_f32_16x16x32_bf16 v[8:11], v[164:167], v[208:211], v[8:11]
	v_mfma_f32_16x16x32_bf16 v[0:3], v[172:175], v[208:211], v[0:3]
	v_mfma_f32_16x16x32_bf16 v[56:59], v[168:171], v[184:187], v[56:59]
	v_mfma_f32_16x16x32_bf16 v[48:51], v[176:179], v[184:187], v[48:51]
	v_mfma_f32_16x16x32_bf16 v[40:43], v[168:171], v[196:199], v[40:43]
	v_mfma_f32_16x16x32_bf16 v[32:35], v[176:179], v[196:199], v[32:35]
	v_mfma_f32_16x16x32_bf16 v[24:27], v[168:171], v[204:207], v[24:27]
	v_mfma_f32_16x16x32_bf16 v[16:19], v[176:179], v[204:207], v[16:19]
	v_mfma_f32_16x16x32_bf16 v[8:11], v[168:171], v[212:215], v[8:11]
	v_mfma_f32_16x16x32_bf16 v[0:3], v[176:179], v[212:215], v[0:3]
	s_setprio 0
	s_barrier
	s_add_i32 s82, s82, 2
	s_add_u32 s62, s62, 0x10000
	s_addc_u32 s63, s63, 0
	s_add_u32 s64, s64, 0x10000
	s_addc_u32 s65, s65, 0
	s_cmp_gt_u32 s82, 13
	s_cbranch_scc0 .LBB0_838
	s_and_b64 vcc, exec, s[44:45]
	s_cbranch_vccz .LBB0_841
	s_barrier

; #define PG8_STAGE(bufoff, gbase, voff) do { _Pragma("unroll") for (int _i = 0; _i < 2; ++_i) \
;         __builtin_amdgcn_global_load_lds((const unsigned*)((const char*)(gbase) + (voff)[_i]), (PG8_LAS unsigned*)(lds + (bufoff) + ldsw + _i * 8192), 16, 0, 0); } while (0)
; #define PG8_LDA(dst, b, h) do { _Pragma("unroll") for (int m = 0; m < 4; ++m) _Pragma("unroll") for (int k = 0; k < 2; ++k) dst[m][k] = *(const PG8_LAS bf16x8*)(lds + PG8_SA(b, h) + aoff + m * 2048 + k * 1024); } while (0)
; #define PG8_LDB(dst, b, h) do { _Pragma("unroll") for (int n = 0; n < 2; ++n) _Pragma("unroll") for (int k = 0; k < 2; ++k) dst[n][k] = *(const PG8_LAS bf16x8*)(lds + PG8_SB(b, h) + boff + n * 2048 + k * 1024); } while (0)
; #define PG8_MMA(ai, bj, At, Bt) do { __builtin_amdgcn_s_setprio(1); _Pragma("unroll") for (int m = 0; m < 4; ++m) _Pragma("unroll") for (int n = 0; n < 2; ++n) _Pragma("unroll") for (int k = 0; k < 2; ++k) \
;         acc[ai][bj][m][n] = __builtin_amdgcn_mfma_f32_16x16x32_bf16(Bt[n][k], At[m][k], acc[ai][bj][m][n], 0, 0, 0); __builtin_amdgcn_s_setprio(0); } while (0)
; #define PG8_WAIT_V(n) asm volatile("s_waitcnt vmcnt(" #n ")" ::: "memory")
; #define PG8_WAIT_L(n) asm volatile("s_waitcnt lgkmcnt(" #n ")" ::: "memory")
; #define PG8_BAR __builtin_amdgcn_s_barrier()
; template <class Epi, class Sched, bool ALIGN_EPI = false, bool SP2 = false>
; __device__ __forceinline__ void gemm_phase(PG8_LAS unsigned char* lds, const Gemm g, const Sched& S, const Epi& E) {
;     ...
;             const char* a1 = cA + (size_t)(t + 1) * kstepA;
;             const char* a2 = last ? nA : cA + (size_t)(t + 2) * kstepA; const char* b2 = last ? nB : cB + (size_t)(t + 2) * kstep;
;             const char* a3 = a2 + kstepA; const char* b3 = b2 + kstep;
;             if (last && has_next) S.a_ready(nxt);
;             if constexpr (SP2) {
;             PG8_LDB(B0, 0, 0); PG8_LDB(B1, 0, 1); PG8_SCHED; PG8_LDA(At, 0, 0); PG8_STAGE(PG8_SA(1, 1), a1 + hstepA, voffA);
;             PG8_WAIT_V(8); PG8_WAIT_L(0); PG8_BAR; PG8_MMA(0, 0, At, B0); PG8_MMA(0, 1, At, B1); PG8_BAR; PG8_SCHED;
;             PG8_LDA(At, 0, 1); PG8_STAGE(PG8_SB(0, 0), b2, voffB); PG8_STAGE(PG8_SB(0, 1), b2 + hstepB, voffB); PG8_STAGE(PG8_SA(0, 0), a2, voffA);
;             PG8_WAIT_V(8); PG8_WAIT_L(0); PG8_BAR; PG8_MMA(1, 0, At, B0); PG8_MMA(1, 1, At, B1); PG8_BAR; PG8_SCHED;
.LBB0_924:
	ds_read_b128 v[84:87], v221
	ds_read_b128 v[92:95], v221 offset:1024
	ds_read_b128 v[104:107], v221 offset:2048
	ds_read_b128 v[116:119], v221 offset:3072
	ds_read_b128 v[128:131], v222
	ds_read_b128 v[140:143], v222 offset:1024
	ds_read_b128 v[152:155], v222 offset:2048
	ds_read_b128 v[156:159], v222 offset:3072
	s_cmp_eq_u32 s66, 40
	s_cselect_b32 s69, s1, s7
	s_cselect_b32 s68, s0, s6
	s_cselect_b32 s71, s63, s65
	s_cselect_b32 s70, s62, s64
	v_lshl_add_u64 v[216:217], s[6:7], 0, v[190:191]
	v_lshl_add_u64 v[228:229], v[216:217], 0, s[58:59]
	s_add_i32 m0, s15, 0xc000
	ds_read_b128 v[160:163], v223
	ds_read_b128 v[164:167], v223 offset:1024
	ds_read_b128 v[168:171], v223 offset:2048
	ds_read_b128 v[172:175], v223 offset:3072
	ds_read_b128 v[176:179], v223 offset:4096
	ds_read_b128 v[180:183], v223 offset:5120
	ds_read_b128 v[184:187], v223 offset:6144
	ds_read_b128 v[212:215], v223 offset:7168
	global_load_lds_dwordx4 v[228:229], off
	v_lshl_add_u64 v[216:217], v[216:217], 0, s[60:61]
	s_add_i32 m0, s15, 0xe000
	s_nop 0
	global_load_lds_dwordx4 v[216:217], off
	s_waitcnt vmcnt(8)
	s_waitcnt lgkmcnt(0)
	s_barrier
	s_setprio 1
	s_waitcnt lgkmcnt(0)
	v_mfma_f32_16x16x32_bf16 v[148:151], v[84:87], v[160:163], v[148:151]
	v_mfma_f32_16x16x32_bf16 v[144:147], v[104:107], v[160:163], v[144:147]
	v_mfma_f32_16x16x32_bf16 v[124:127], v[84:87], v[168:171], v[124:127]
	v_mfma_f32_16x16x32_bf16 v[120:123], v[104:107], v[168:171], v[120:123]
	v_mfma_f32_16x16x32_bf16 v[100:103], v[84:87], v[176:179], v[100:103]
	v_mfma_f32_16x16x32_bf16 v[96:99], v[104:107], v[176:179], v[96:99]
	v_mfma_f32_16x16x32_bf16 v[76:79], v[84:87], v[184:187], v[76:79]
	v_mfma_f32_16x16x32_bf16 v[72:75], v[104:107], v[184:187], v[72:75]
	v_mfma_f32_16x16x32_bf16 v[148:151], v[92:95], v[164:167], v[148:151]
	v_mfma_f32_16x16x32_bf16 v[144:147], v[116:119], v[164:167], v[144:147]
	v_mfma_f32_16x16x32_bf16 v[124:127], v[92:95], v[172:175], v[124:127]
	v_mfma_f32_16x16x32_bf16 v[120:123], v[116:119], v[172:175], v[120:123]
	v_mfma_f32_16x16x32_bf16 v[100:103], v[92:95], v[180:183], v[100:103]
	v_mfma_f32_16x16x32_bf16 v[96:99], v[116:119], v[180:183], v[96:99]
	v_mfma_f32_16x16x32_bf16 v[76:79], v[92:95], v[212:215], v[76:79]
	v_mfma_f32_16x16x32_bf16 v[72:75], v[116:119], v[212:215], v[72:75]
	v_mfma_f32_16x16x32_bf16 v[136:139], v[128:131], v[160:163], v[136:139]
	v_mfma_f32_16x16x32_bf16 v[132:135], v[152:155], v[160:163], v[132:135]
	v_mfma_f32_16x16x32_bf16 v[112:115], v[128:131], v[168:171], v[112:115]
	v_mfma_f32_16x16x32_bf16 v[108:111], v[152:155], v[168:171], v[108:111]
	v_mfma_f32_16x16x32_bf16 v[88:91], v[128:131], v[176:179], v[88:91]
	v_mfma_f32_16x16x32_bf16 v[80:83], v[152:155], v[176:179], v[80:83]
	v_mfma_f32_16x16x32_bf16 v[68:71], v[128:131], v[184:187], v[68:71]
	v_mfma_f32_16x16x32_bf16 v[64:67], v[152:155], v[184:187], v[64:67]
	v_mfma_f32_16x16x32_bf16 v[136:139], v[140:143], v[164:167], v[136:139]
	v_mfma_f32_16x16x32_bf16 v[132:135], v[156:159], v[164:167], v[132:135]
	v_mfma_f32_16x16x32_bf16 v[112:115], v[140:143], v[172:175], v[112:115]
	v_mfma_f32_16x16x32_bf16 v[108:111], v[156:159], v[172:175], v[108:111]
	v_mfma_f32_16x16x32_bf16 v[88:91], v[140:143], v[180:183], v[88:91]
	v_mfma_f32_16x16x32_bf16 v[80:83], v[156:159], v[180:183], v[80:83]
	v_mfma_f32_16x16x32_bf16 v[68:71], v[140:143], v[212:215], v[68:71]
	v_mfma_f32_16x16x32_bf16 v[64:67], v[156:159], v[212:215], v[64:67]
	s_setprio 0
	s_barrier
	s_add_i32 s33, s81, s14
	v_lshl_add_u64 v[216:217], s[70:71], 0, v[190:191]
	s_mov_b32 m0, s33
	ds_read_b128 v[160:163], v223 offset:16384
	ds_read_b128 v[164:167], v223 offset:17408
	ds_read_b128 v[168:171], v223 offset:18432
	ds_read_b128 v[172:175], v223 offset:19456
	ds_read_b128 v[176:179], v223 offset:20480
	ds_read_b128 v[180:183], v223 offset:21504
	ds_read_b128 v[184:187], v223 offset:22528
	ds_read_b128 v[212:215], v223 offset:23552
	global_load_lds_dwordx4 v[216:217], off
	v_lshl_add_u64 v[228:229], v[216:217], 0, s[8:9]
	s_add_i32 m0, s33, 0x2000
	s_add_i32 s33, s82, s14
	global_load_lds_dwordx4 v[228:229], off
	v_lshl_add_u64 v[228:229], v[216:217], 0, s[10:11]
	s_mov_b32 m0, s33
	s_nop 0
	global_load_lds_dwordx4 v[228:229], off
	v_lshl_add_u64 v[228:229], v[216:217], 0, s[40:41]
	s_add_i32 m0, s33, 0x2000
	s_nop 0
	global_load_lds_dwordx4 v[228:229], off
	v_lshl_add_u64 v[228:229], s[68:69], 0, v[190:191]
	s_mov_b32 m0, s15
	v_lshl_add_u64 v[230:231], v[228:229], 0, s[8:9]
	global_load_lds_dwordx4 v[228:229], off
	s_mov_b32 m0, s17
	s_nop 0
	global_load_lds_dwordx4 v[230:231], off
	s_waitcnt vmcnt(8)
	s_waitcnt lgkmcnt(0)
	s_barrier
; #define PG8_STAGE(bufoff, gbase, voff) do { _Pragma("unroll") for (int _i = 0; _i < 2; ++_i) \
;         __builtin_amdgcn_global_load_lds((const unsigned*)((const char*)(gbase) + (voff)[_i]), (PG8_LAS unsigned*)(lds + (bufoff) + ldsw + _i * 8192), 16, 0, 0); } while (0)
; #define PG8_LDA(dst, b, h) do { _Pragma("unroll") for (int m = 0; m < 4; ++m) _Pragma("unroll") for (int k = 0; k < 2; ++k) dst[m][k] = *(const PG8_LAS bf16x8*)(lds + PG8_SA(b, h) + aoff + m * 2048 + k * 1024); } while (0)
; #define PG8_LDB(dst, b, h) do { _Pragma("unroll") for (int n = 0; n < 2; ++n) _Pragma("unroll") for (int k = 0; k < 2; ++k) dst[n][k] = *(const PG8_LAS bf16x8*)(lds + PG8_SB(b, h) + boff + n * 2048 + k * 1024); } while (0)
; #define PG8_MMA(ai, bj, At, Bt) do { __builtin_amdgcn_s_setprio(1); _Pragma("unroll") for (int m = 0; m < 4; ++m) _Pragma("unroll") for (int n = 0; n < 2; ++n) _Pragma("unroll") for (int k = 0; k < 2; ++k) \
;         acc[ai][bj][m][n] = __builtin_amdgcn_mfma_f32_16x16x32_bf16(Bt[n][k], At[m][k], acc[ai][bj][m][n], 0, 0, 0); __builtin_amdgcn_s_setprio(0); } while (0)
; #define PG8_WAIT_V(n) asm volatile("s_waitcnt vmcnt(" #n ")" ::: "memory")
; #define PG8_WAIT_L(n) asm volatile("s_waitcnt lgkmcnt(" #n ")" ::: "memory")
; #define PG8_BAR __builtin_amdgcn_s_barrier()
; #define PG8_SCHED __builtin_amdgcn_sched_barrier(0)
; template <class Epi, class Sched, bool ALIGN_EPI = false, bool SP2 = false>
; __device__ __forceinline__ void gemm_phase(PG8_LAS unsigned char* lds, const Gemm g, const Sched& S, const Epi& E) {
;     ...
;             PG8_WAIT_V(8); PG8_WAIT_L(0); PG8_BAR; PG8_MMA(1, 0, At, B0); PG8_MMA(1, 1, At, B1); PG8_BAR; PG8_SCHED;
;             PG8_LDB(B0, 1, 0); PG8_LDB(B1, 1, 1); PG8_SCHED; PG8_LDA(At, 1, 0); PG8_STAGE(PG8_SA(0, 1), a2 + hstepA, voffA);
;             PG8_WAIT_V(8); PG8_WAIT_L(0); PG8_BAR; PG8_MMA(0, 0, At, B0); PG8_MMA(0, 1, At, B1); PG8_BAR; PG8_SCHED;
	s_setprio 1
	s_waitcnt lgkmcnt(0)
	v_mfma_f32_16x16x32_bf16 v[60:63], v[84:87], v[160:163], v[60:63]
	v_mfma_f32_16x16x32_bf16 v[56:59], v[104:107], v[160:163], v[56:59]
	v_mfma_f32_16x16x32_bf16 v[44:47], v[84:87], v[168:171], v[44:47]
	v_mfma_f32_16x16x32_bf16 v[40:43], v[104:107], v[168:171], v[40:43]
	v_mfma_f32_16x16x32_bf16 v[28:31], v[84:87], v[176:179], v[28:31]
	v_mfma_f32_16x16x32_bf16 v[24:27], v[104:107], v[176:179], v[24:27]
	v_mfma_f32_16x16x32_bf16 v[12:15], v[84:87], v[184:187], v[12:15]
	v_mfma_f32_16x16x32_bf16 v[8:11], v[104:107], v[184:187], v[8:11]
	v_mfma_f32_16x16x32_bf16 v[60:63], v[92:95], v[164:167], v[60:63]
	v_mfma_f32_16x16x32_bf16 v[56:59], v[116:119], v[164:167], v[56:59]
	v_mfma_f32_16x16x32_bf16 v[44:47], v[92:95], v[172:175], v[44:47]
	v_mfma_f32_16x16x32_bf16 v[40:43], v[116:119], v[172:175], v[40:43]
	v_mfma_f32_16x16x32_bf16 v[28:31], v[92:95], v[180:183], v[28:31]
	v_mfma_f32_16x16x32_bf16 v[24:27], v[116:119], v[180:183], v[24:27]
	v_mfma_f32_16x16x32_bf16 v[12:15], v[92:95], v[212:215], v[12:15]
	v_mfma_f32_16x16x32_bf16 v[8:11], v[116:119], v[212:215], v[8:11]
	v_mfma_f32_16x16x32_bf16 v[52:55], v[128:131], v[160:163], v[52:55]
	v_mfma_f32_16x16x32_bf16 v[48:51], v[152:155], v[160:163], v[48:51]
	v_mfma_f32_16x16x32_bf16 v[36:39], v[128:131], v[168:171], v[36:39]
	v_mfma_f32_16x16x32_bf16 v[32:35], v[152:155], v[168:171], v[32:35]
	v_mfma_f32_16x16x32_bf16 v[20:23], v[128:131], v[176:179], v[20:23]
	v_mfma_f32_16x16x32_bf16 v[16:19], v[152:155], v[176:179], v[16:19]
	v_mfma_f32_16x16x32_bf16 v[4:7], v[128:131], v[184:187], v[4:7]
	v_mfma_f32_16x16x32_bf16 v[0:3], v[152:155], v[184:187], v[0:3]
	v_mfma_f32_16x16x32_bf16 v[52:55], v[140:143], v[164:167], v[52:55]
	v_mfma_f32_16x16x32_bf16 v[48:51], v[156:159], v[164:167], v[48:51]
	v_mfma_f32_16x16x32_bf16 v[36:39], v[140:143], v[172:175], v[36:39]
	v_mfma_f32_16x16x32_bf16 v[32:35], v[156:159], v[172:175], v[32:35]
	v_mfma_f32_16x16x32_bf16 v[20:23], v[140:143], v[180:183], v[20:23]
	v_mfma_f32_16x16x32_bf16 v[16:19], v[156:159], v[180:183], v[16:19]
	v_mfma_f32_16x16x32_bf16 v[4:7], v[140:143], v[212:215], v[4:7]
	v_mfma_f32_16x16x32_bf16 v[0:3], v[156:159], v[212:215], v[0:3]
	s_setprio 0
	s_barrier
	ds_read_b128 v[84:87], v224
	ds_read_b128 v[92:95], v224 offset:1024
	ds_read_b128 v[104:107], v224 offset:2048
	ds_read_b128 v[116:119], v224 offset:3072
	ds_read_b128 v[128:131], v225
	ds_read_b128 v[140:143], v225 offset:1024
	ds_read_b128 v[152:155], v225 offset:2048
	ds_read_b128 v[156:159], v225 offset:3072
	s_mov_b32 m0, s18
	v_lshl_add_u64 v[230:231], v[228:229], 0, s[10:11]
	ds_read_b128 v[160:163], v223 offset:32768
	ds_read_b128 v[164:167], v223 offset:33792
	ds_read_b128 v[168:171], v223 offset:34816
	ds_read_b128 v[172:175], v223 offset:35840
	ds_read_b128 v[176:179], v223 offset:36864
	ds_read_b128 v[180:183], v223 offset:37888
	ds_read_b128 v[184:187], v223 offset:38912
	ds_read_b128 v[212:215], v223 offset:39936
	global_load_lds_dwordx4 v[230:231], off
	v_lshl_add_u64 v[230:231], v[228:229], 0, s[40:41]
	s_mov_b32 m0, s19
	s_nop 0
	global_load_lds_dwordx4 v[230:231], off
	s_waitcnt vmcnt(8)
	s_waitcnt lgkmcnt(0)
	s_barrier
	s_setprio 1
	s_waitcnt lgkmcnt(0)
	v_mfma_f32_16x16x32_bf16 v[148:151], v[84:87], v[160:163], v[148:151]
	v_mfma_f32_16x16x32_bf16 v[144:147], v[104:107], v[160:163], v[144:147]
	v_mfma_f32_16x16x32_bf16 v[124:127], v[84:87], v[168:171], v[124:127]
	v_mfma_f32_16x16x32_bf16 v[120:123], v[104:107], v[168:171], v[120:123]
	v_mfma_f32_16x16x32_bf16 v[100:103], v[84:87], v[176:179], v[100:103]
	v_mfma_f32_16x16x32_bf16 v[96:99], v[104:107], v[176:179], v[96:99]
	v_mfma_f32_16x16x32_bf16 v[76:79], v[84:87], v[184:187], v[76:79]
	v_mfma_f32_16x16x32_bf16 v[72:75], v[104:107], v[184:187], v[72:75]
	v_mfma_f32_16x16x32_bf16 v[148:151], v[92:95], v[164:167], v[148:151]
	v_mfma_f32_16x16x32_bf16 v[144:147], v[116:119], v[164:167], v[144:147]
	v_mfma_f32_16x16x32_bf16 v[124:127], v[92:95], v[172:175], v[124:127]
	v_mfma_f32_16x16x32_bf16 v[120:123], v[116:119], v[172:175], v[120:123]
	v_mfma_f32_16x16x32_bf16 v[100:103], v[92:95], v[180:183], v[100:103]
	v_mfma_f32_16x16x32_bf16 v[96:99], v[116:119], v[180:183], v[96:99]
	v_mfma_f32_16x16x32_bf16 v[76:79], v[92:95], v[212:215], v[76:79]
	v_mfma_f32_16x16x32_bf16 v[72:75], v[116:119], v[212:215], v[72:75]
	v_mfma_f32_16x16x32_bf16 v[136:139], v[128:131], v[160:163], v[136:139]
	v_mfma_f32_16x16x32_bf16 v[132:135], v[152:155], v[160:163], v[132:135]
	v_mfma_f32_16x16x32_bf16 v[112:115], v[128:131], v[168:171], v[112:115]
	v_mfma_f32_16x16x32_bf16 v[108:111], v[152:155], v[168:171], v[108:111]
	v_mfma_f32_16x16x32_bf16 v[88:91], v[128:131], v[176:179], v[88:91]
	v_mfma_f32_16x16x32_bf16 v[80:83], v[152:155], v[176:179], v[80:83]
	v_mfma_f32_16x16x32_bf16 v[68:71], v[128:131], v[184:187], v[68:71]
	v_mfma_f32_16x16x32_bf16 v[64:67], v[152:155], v[184:187], v[64:67]
	v_mfma_f32_16x16x32_bf16 v[136:139], v[140:143], v[164:167], v[136:139]
	v_mfma_f32_16x16x32_bf16 v[132:135], v[156:159], v[164:167], v[132:135]
	v_mfma_f32_16x16x32_bf16 v[112:115], v[140:143], v[172:175], v[112:115]
	v_mfma_f32_16x16x32_bf16 v[108:111], v[156:159], v[172:175], v[108:111]
	v_mfma_f32_16x16x32_bf16 v[88:91], v[140:143], v[180:183], v[88:91]
	v_mfma_f32_16x16x32_bf16 v[80:83], v[156:159], v[180:183], v[80:83]
	v_mfma_f32_16x16x32_bf16 v[68:71], v[140:143], v[212:215], v[68:71]
	v_mfma_f32_16x16x32_bf16 v[64:67], v[156:159], v[212:215], v[64:67]
	s_setprio 0
	s_barrier
; #define PG8_STAGE(bufoff, gbase, voff) do { _Pragma("unroll") for (int _i = 0; _i < 2; ++_i) \
;         __builtin_amdgcn_global_load_lds((const unsigned*)((const char*)(gbase) + (voff)[_i]), (PG8_LAS unsigned*)(lds + (bufoff) + ldsw + _i * 8192), 16, 0, 0); } while (0)
; #define PG8_LDA(dst, b, h) do { _Pragma("unroll") for (int m = 0; m < 4; ++m) _Pragma("unroll") for (int k = 0; k < 2; ++k) dst[m][k] = *(const PG8_LAS bf16x8*)(lds + PG8_SA(b, h) + aoff + m * 2048 + k * 1024); } while (0)
; #define PG8_MMA(ai, bj, At, Bt) do { __builtin_amdgcn_s_setprio(1); _Pragma("unroll") for (int m = 0; m < 4; ++m) _Pragma("unroll") for (int n = 0; n < 2; ++n) _Pragma("unroll") for (int k = 0; k < 2; ++k) \
;         acc[ai][bj][m][n] = __builtin_amdgcn_mfma_f32_16x16x32_bf16(Bt[n][k], At[m][k], acc[ai][bj][m][n], 0, 0, 0); __builtin_amdgcn_s_setprio(0); } while (0)
; #define PG8_WAIT_V(n) asm volatile("s_waitcnt vmcnt(" #n ")" ::: "memory")
; #define PG8_WAIT_L(n) asm volatile("s_waitcnt lgkmcnt(" #n ")" ::: "memory")
; #define PG8_BAR __builtin_amdgcn_s_barrier()
; #define PG8_SCHED __builtin_amdgcn_sched_barrier(0)
; template <class Epi, class Sched, bool ALIGN_EPI = false, bool SP2 = false>
; __device__ __forceinline__ void gemm_phase(PG8_LAS unsigned char* lds, const Gemm g, const Sched& S, const Epi& E) {
;     ...
;             PG8_LDA(At, 1, 1); PG8_STAGE(PG8_SB(1, 0), b3, voffB); PG8_STAGE(PG8_SB(1, 1), b3 + hstepB, voffB); PG8_STAGE(PG8_SA(1, 0), a3, voffA);
;             PG8_WAIT_V(8); PG8_WAIT_L(0); PG8_BAR; PG8_MMA(1, 0, At, B0); PG8_MMA(1, 1, At, B1); PG8_BAR; PG8_SCHED;
	s_add_i32 s33, s83, s14
	v_lshl_add_u64 v[230:231], v[216:217], 0, s[42:43]
	s_mov_b32 m0, s33
	ds_read_b128 v[160:163], v223 offset:49152
	ds_read_b128 v[164:167], v223 offset:50176
	ds_read_b128 v[168:171], v223 offset:51200
	ds_read_b128 v[172:175], v223 offset:52224
	ds_read_b128 v[176:179], v223 offset:53248
	ds_read_b128 v[180:183], v223 offset:54272
	ds_read_b128 v[184:187], v223 offset:55296
	ds_read_b128 v[212:215], v223 offset:56320
	global_load_lds_dwordx4 v[230:231], off
	v_lshl_add_u64 v[230:231], v[216:217], 0, s[44:45]
	s_add_i32 m0, s33, 0x2000
	s_add_i32 s33, s84, s14
	global_load_lds_dwordx4 v[230:231], off
	v_lshl_add_u64 v[230:231], v[216:217], 0, s[46:47]
	s_mov_b32 m0, s33
	v_lshl_add_u64 v[216:217], v[216:217], 0, s[48:49]
	global_load_lds_dwordx4 v[230:231], off
	s_add_i32 m0, s33, 0x2000
	s_nop 0
	global_load_lds_dwordx4 v[216:217], off
	v_lshl_add_u64 v[216:217], v[228:229], 0, s[42:43]
	s_mov_b32 m0, s74
	s_nop 0
	global_load_lds_dwordx4 v[216:217], off
	v_lshl_add_u64 v[216:217], v[228:229], 0, s[44:45]
	s_mov_b32 m0, s75
	s_nop 0
	global_load_lds_dwordx4 v[216:217], off
	s_waitcnt vmcnt(8)
	s_waitcnt lgkmcnt(0)
	s_barrier
	s_setprio 1
	s_waitcnt lgkmcnt(0)
	v_mfma_f32_16x16x32_bf16 v[60:63], v[84:87], v[160:163], v[60:63]
	v_mfma_f32_16x16x32_bf16 v[56:59], v[104:107], v[160:163], v[56:59]
	v_mfma_f32_16x16x32_bf16 v[44:47], v[84:87], v[168:171], v[44:47]
	v_mfma_f32_16x16x32_bf16 v[40:43], v[104:107], v[168:171], v[40:43]
	v_mfma_f32_16x16x32_bf16 v[28:31], v[84:87], v[176:179], v[28:31]
	v_mfma_f32_16x16x32_bf16 v[24:27], v[104:107], v[176:179], v[24:27]
	v_mfma_f32_16x16x32_bf16 v[12:15], v[84:87], v[184:187], v[12:15]
	v_mfma_f32_16x16x32_bf16 v[8:11], v[104:107], v[184:187], v[8:11]
	v_mfma_f32_16x16x32_bf16 v[60:63], v[92:95], v[164:167], v[60:63]
	v_mfma_f32_16x16x32_bf16 v[56:59], v[116:119], v[164:167], v[56:59]
	v_mfma_f32_16x16x32_bf16 v[44:47], v[92:95], v[172:175], v[44:47]
	v_mfma_f32_16x16x32_bf16 v[40:43], v[116:119], v[172:175], v[40:43]
	v_mfma_f32_16x16x32_bf16 v[28:31], v[92:95], v[180:183], v[28:31]
	v_mfma_f32_16x16x32_bf16 v[24:27], v[116:119], v[180:183], v[24:27]
	v_mfma_f32_16x16x32_bf16 v[12:15], v[92:95], v[212:215], v[12:15]
	v_mfma_f32_16x16x32_bf16 v[8:11], v[116:119], v[212:215], v[8:11]
	v_mfma_f32_16x16x32_bf16 v[52:55], v[128:131], v[160:163], v[52:55]
	v_mfma_f32_16x16x32_bf16 v[48:51], v[152:155], v[160:163], v[48:51]
	v_mfma_f32_16x16x32_bf16 v[36:39], v[128:131], v[168:171], v[36:39]
	v_mfma_f32_16x16x32_bf16 v[32:35], v[152:155], v[168:171], v[32:35]
	v_mfma_f32_16x16x32_bf16 v[20:23], v[128:131], v[176:179], v[20:23]
	v_mfma_f32_16x16x32_bf16 v[16:19], v[152:155], v[176:179], v[16:19]
	v_mfma_f32_16x16x32_bf16 v[4:7], v[128:131], v[184:187], v[4:7]
	v_mfma_f32_16x16x32_bf16 v[0:3], v[152:155], v[184:187], v[0:3]
	v_mfma_f32_16x16x32_bf16 v[52:55], v[140:143], v[164:167], v[52:55]
	v_mfma_f32_16x16x32_bf16 v[48:51], v[156:159], v[164:167], v[48:51]
	v_mfma_f32_16x16x32_bf16 v[36:39], v[140:143], v[172:175], v[36:39]
	v_mfma_f32_16x16x32_bf16 v[32:35], v[156:159], v[172:175], v[32:35]
	v_mfma_f32_16x16x32_bf16 v[20:23], v[140:143], v[180:183], v[20:23]
	v_mfma_f32_16x16x32_bf16 v[16:19], v[156:159], v[180:183], v[16:19]
	v_mfma_f32_16x16x32_bf16 v[4:7], v[140:143], v[212:215], v[4:7]
	v_mfma_f32_16x16x32_bf16 v[0:3], v[156:159], v[212:215], v[0:3]
	s_setprio 0
	s_barrier
	s_add_i32 s66, s66, 2
	s_add_u32 s6, s6, 0x10000
	s_addc_u32 s7, s7, 0
	s_add_u32 s64, s64, 0x10000
	s_addc_u32 s65, s65, 0
	s_cmp_gt_u32 s66, 41
	s_cbranch_scc0 .LBB0_924
	s_and_b64 vcc, exec, s[54:55]
	s_cbranch_vccz .LBB0_927
	s_barrier

; #define PG8_STAGE(bufoff, gbase, voff) do { _Pragma("unroll") for (int _i = 0; _i < 2; ++_i) \
;         __builtin_amdgcn_global_load_lds((const unsigned*)((const char*)(gbase) + (voff)[_i]), (PG8_LAS unsigned*)(lds + (bufoff) + ldsw + _i * 8192), 16, 0, 0); } while (0)
; #define PG8_LDA(dst, b, h) do { _Pragma("unroll") for (int m = 0; m < 4; ++m) _Pragma("unroll") for (int k = 0; k < 2; ++k) dst[m][k] = *(const PG8_LAS bf16x8*)(lds + PG8_SA(b, h) + aoff + m * 2048 + k * 1024); } while (0)
; #define PG8_LDB(dst, b, h) do { _Pragma("unroll") for (int n = 0; n < 2; ++n) _Pragma("unroll") for (int k = 0; k < 2; ++k) dst[n][k] = *(const PG8_LAS bf16x8*)(lds + PG8_SB(b, h) + boff + n * 2048 + k * 1024); } while (0)
; #define PG8_MMA(ai, bj, At, Bt) do { __builtin_amdgcn_s_setprio(1); _Pragma("unroll") for (int m = 0; m < 4; ++m) _Pragma("unroll") for (int n = 0; n < 2; ++n) _Pragma("unroll") for (int k = 0; k < 2; ++k) \
;         acc[ai][bj][m][n] = __builtin_amdgcn_mfma_f32_16x16x32_bf16(Bt[n][k], At[m][k], acc[ai][bj][m][n], 0, 0, 0); __builtin_amdgcn_s_setprio(0); } while (0)
; #define PG8_WAIT_V(n) asm volatile("s_waitcnt vmcnt(" #n ")" ::: "memory")
; #define PG8_WAIT_L(n) asm volatile("s_waitcnt lgkmcnt(" #n ")" ::: "memory")
; #define PG8_BAR __builtin_amdgcn_s_barrier()
; template <class Epi, class Sched, bool ALIGN_EPI = false, bool SP2 = false>
; __device__ __forceinline__ void gemm_phase(PG8_LAS unsigned char* lds, const Gemm g, const Sched& S, const Epi& E) {
;     ...
;             const char* a1 = cA + (size_t)(t + 1) * kstepA;
;             const char* a2 = last ? nA : cA + (size_t)(t + 2) * kstepA; const char* b2 = last ? nB : cB + (size_t)(t + 2) * kstep;
;             const char* a3 = a2 + kstepA; const char* b3 = b2 + kstep;
;             if (last && has_next) S.a_ready(nxt);
;             if constexpr (SP2) {
;             PG8_LDB(B0, 0, 0); PG8_LDB(B1, 0, 1); PG8_SCHED; PG8_LDA(At, 0, 0); PG8_STAGE(PG8_SA(1, 1), a1 + hstepA, voffA);
;             PG8_WAIT_V(8); PG8_WAIT_L(0); PG8_BAR; PG8_MMA(0, 0, At, B0); PG8_MMA(0, 1, At, B1); PG8_BAR; PG8_SCHED;
;             PG8_LDA(At, 0, 1); PG8_STAGE(PG8_SB(0, 0), b2, voffB); PG8_STAGE(PG8_SB(0, 1), b2 + hstepB, voffB); PG8_STAGE(PG8_SA(0, 0), a2, voffA);
;             PG8_WAIT_V(8); PG8_WAIT_L(0); PG8_BAR; PG8_MMA(1, 0, At, B0); PG8_MMA(1, 1, At, B1); PG8_BAR; PG8_SCHED;
.LBB0_1004:
	ds_read_b128 v[128:131], v220
	ds_read_b128 v[132:135], v220 offset:1024
	ds_read_b128 v[136:139], v220 offset:2048
	ds_read_b128 v[140:143], v220 offset:3072
	ds_read_b128 v[144:147], v221
	ds_read_b128 v[148:151], v221 offset:1024
	ds_read_b128 v[152:155], v221 offset:2048
	ds_read_b128 v[156:159], v221 offset:3072
	s_cmp_eq_u32 s73, 40
	s_cselect_b32 s75, s1, s71
	s_cselect_b32 s74, s0, s70
	s_cselect_b32 s77, s67, s72
	s_cselect_b32 s76, s66, s69
	v_lshl_add_u64 v[238:239], s[70:71], 0, v[190:191]
	v_lshl_add_u64 v[240:241], v[238:239], 0, s[62:63]
	s_add_i32 m0, s15, 0xc000
	ds_read_b128 v[160:163], v222
	ds_read_b128 v[164:167], v222 offset:1024
	ds_read_b128 v[168:171], v222 offset:2048
	ds_read_b128 v[172:175], v222 offset:3072
	ds_read_b128 v[176:179], v222 offset:4096
	ds_read_b128 v[180:183], v222 offset:5120
	ds_read_b128 v[230:233], v222 offset:6144
	ds_read_b128 v[234:237], v222 offset:7168
	global_load_lds_dwordx4 v[240:241], off
	v_lshl_add_u64 v[238:239], v[238:239], 0, s[64:65]
	s_add_i32 m0, s15, 0xe000
	s_nop 0
	global_load_lds_dwordx4 v[238:239], off
	s_waitcnt vmcnt(8)
	s_waitcnt lgkmcnt(0)
	s_barrier
	s_setprio 1
	s_waitcnt lgkmcnt(0)
	v_mfma_f32_16x16x32_bf16 v[124:127], v[128:131], v[160:163], v[124:127]
	v_mfma_f32_16x16x32_bf16 v[120:123], v[136:139], v[160:163], v[120:123]
	v_mfma_f32_16x16x32_bf16 v[108:111], v[128:131], v[168:171], v[108:111]
	v_mfma_f32_16x16x32_bf16 v[104:107], v[136:139], v[168:171], v[104:107]
	v_mfma_f32_16x16x32_bf16 v[92:95], v[128:131], v[176:179], v[92:95]
	v_mfma_f32_16x16x32_bf16 v[88:91], v[136:139], v[176:179], v[88:91]
	v_mfma_f32_16x16x32_bf16 v[76:79], v[128:131], v[230:233], v[76:79]
	v_mfma_f32_16x16x32_bf16 v[72:75], v[136:139], v[230:233], v[72:75]
	v_mfma_f32_16x16x32_bf16 v[124:127], v[132:135], v[164:167], v[124:127]
	v_mfma_f32_16x16x32_bf16 v[120:123], v[140:143], v[164:167], v[120:123]
	v_mfma_f32_16x16x32_bf16 v[108:111], v[132:135], v[172:175], v[108:111]
	v_mfma_f32_16x16x32_bf16 v[104:107], v[140:143], v[172:175], v[104:107]
	v_mfma_f32_16x16x32_bf16 v[92:95], v[132:135], v[180:183], v[92:95]
	v_mfma_f32_16x16x32_bf16 v[88:91], v[140:143], v[180:183], v[88:91]
	v_mfma_f32_16x16x32_bf16 v[76:79], v[132:135], v[234:237], v[76:79]
	v_mfma_f32_16x16x32_bf16 v[72:75], v[140:143], v[234:237], v[72:75]
	v_mfma_f32_16x16x32_bf16 v[116:119], v[144:147], v[160:163], v[116:119]
	v_mfma_f32_16x16x32_bf16 v[112:115], v[152:155], v[160:163], v[112:115]
	v_mfma_f32_16x16x32_bf16 v[100:103], v[144:147], v[168:171], v[100:103]
	v_mfma_f32_16x16x32_bf16 v[96:99], v[152:155], v[168:171], v[96:99]
	v_mfma_f32_16x16x32_bf16 v[84:87], v[144:147], v[176:179], v[84:87]
	v_mfma_f32_16x16x32_bf16 v[80:83], v[152:155], v[176:179], v[80:83]
	v_mfma_f32_16x16x32_bf16 v[68:71], v[144:147], v[230:233], v[68:71]
	v_mfma_f32_16x16x32_bf16 v[64:67], v[152:155], v[230:233], v[64:67]
	v_mfma_f32_16x16x32_bf16 v[116:119], v[148:151], v[164:167], v[116:119]
	v_mfma_f32_16x16x32_bf16 v[112:115], v[156:159], v[164:167], v[112:115]
	v_mfma_f32_16x16x32_bf16 v[100:103], v[148:151], v[172:175], v[100:103]
	v_mfma_f32_16x16x32_bf16 v[96:99], v[156:159], v[172:175], v[96:99]
	v_mfma_f32_16x16x32_bf16 v[84:87], v[148:151], v[180:183], v[84:87]
	v_mfma_f32_16x16x32_bf16 v[80:83], v[156:159], v[180:183], v[80:83]
	v_mfma_f32_16x16x32_bf16 v[68:71], v[148:151], v[234:237], v[68:71]
	v_mfma_f32_16x16x32_bf16 v[64:67], v[156:159], v[234:237], v[64:67]
	s_setprio 0
	s_barrier
	s_add_i32 s33, s86, s14
	v_lshl_add_u64 v[238:239], s[76:77], 0, v[190:191]
	s_mov_b32 m0, s33
	ds_read_b128 v[160:163], v222 offset:16384
	ds_read_b128 v[164:167], v222 offset:17408
	ds_read_b128 v[168:171], v222 offset:18432
	ds_read_b128 v[172:175], v222 offset:19456
	ds_read_b128 v[176:179], v222 offset:20480
	ds_read_b128 v[180:183], v222 offset:21504
	ds_read_b128 v[230:233], v222 offset:22528
	ds_read_b128 v[234:237], v222 offset:23552
	global_load_lds_dwordx4 v[238:239], off
	v_lshl_add_u64 v[240:241], v[238:239], 0, s[40:41]
	s_add_i32 m0, s33, 0x2000
	s_add_i32 s33, s87, s14
	global_load_lds_dwordx4 v[240:241], off
	v_lshl_add_u64 v[240:241], v[238:239], 0, s[42:43]
	s_mov_b32 m0, s33
	s_nop 0
	global_load_lds_dwordx4 v[240:241], off
	v_lshl_add_u64 v[240:241], v[238:239], 0, s[44:45]
	s_add_i32 m0, s33, 0x2000
	s_nop 0
	global_load_lds_dwordx4 v[240:241], off
	v_lshl_add_u64 v[240:241], s[74:75], 0, v[190:191]
	s_mov_b32 m0, s15
	v_lshl_add_u64 v[242:243], v[240:241], 0, s[40:41]
	global_load_lds_dwordx4 v[240:241], off
	s_mov_b32 m0, s17
	s_nop 0
	global_load_lds_dwordx4 v[242:243], off
	s_waitcnt vmcnt(8)
	s_waitcnt lgkmcnt(0)
	s_barrier
; #define PG8_STAGE(bufoff, gbase, voff) do { _Pragma("unroll") for (int _i = 0; _i < 2; ++_i) \
;         __builtin_amdgcn_global_load_lds((const unsigned*)((const char*)(gbase) + (voff)[_i]), (PG8_LAS unsigned*)(lds + (bufoff) + ldsw + _i * 8192), 16, 0, 0); } while (0)
; #define PG8_LDA(dst, b, h) do { _Pragma("unroll") for (int m = 0; m < 4; ++m) _Pragma("unroll") for (int k = 0; k < 2; ++k) dst[m][k] = *(const PG8_LAS bf16x8*)(lds + PG8_SA(b, h) + aoff + m * 2048 + k * 1024); } while (0)
; #define PG8_LDB(dst, b, h) do { _Pragma("unroll") for (int n = 0; n < 2; ++n) _Pragma("unroll") for (int k = 0; k < 2; ++k) dst[n][k] = *(const PG8_LAS bf16x8*)(lds + PG8_SB(b, h) + boff + n * 2048 + k * 1024); } while (0)
; #define PG8_MMA(ai, bj, At, Bt) do { __builtin_amdgcn_s_setprio(1); _Pragma("unroll") for (int m = 0; m < 4; ++m) _Pragma("unroll") for (int n = 0; n < 2; ++n) _Pragma("unroll") for (int k = 0; k < 2; ++k) \
;         acc[ai][bj][m][n] = __builtin_amdgcn_mfma_f32_16x16x32_bf16(Bt[n][k], At[m][k], acc[ai][bj][m][n], 0, 0, 0); __builtin_amdgcn_s_setprio(0); } while (0)
; #define PG8_WAIT_V(n) asm volatile("s_waitcnt vmcnt(" #n ")" ::: "memory")
; #define PG8_WAIT_L(n) asm volatile("s_waitcnt lgkmcnt(" #n ")" ::: "memory")
; #define PG8_BAR __builtin_amdgcn_s_barrier()
; #define PG8_SCHED __builtin_amdgcn_sched_barrier(0)
; template <class Epi, class Sched, bool ALIGN_EPI = false, bool SP2 = false>
; __device__ __forceinline__ void gemm_phase(PG8_LAS unsigned char* lds, const Gemm g, const Sched& S, const Epi& E) {
;     ...
;             PG8_WAIT_V(8); PG8_WAIT_L(0); PG8_BAR; PG8_MMA(1, 0, At, B0); PG8_MMA(1, 1, At, B1); PG8_BAR; PG8_SCHED;
;             PG8_LDB(B0, 1, 0); PG8_LDB(B1, 1, 1); PG8_SCHED; PG8_LDA(At, 1, 0); PG8_STAGE(PG8_SA(0, 1), a2 + hstepA, voffA);
;             PG8_WAIT_V(8); PG8_WAIT_L(0); PG8_BAR; PG8_MMA(0, 0, At, B0); PG8_MMA(0, 1, At, B1); PG8_BAR; PG8_SCHED;
	s_setprio 1
	s_waitcnt lgkmcnt(0)
	v_mfma_f32_16x16x32_bf16 v[60:63], v[128:131], v[160:163], v[60:63]
	v_mfma_f32_16x16x32_bf16 v[56:59], v[136:139], v[160:163], v[56:59]
	v_mfma_f32_16x16x32_bf16 v[44:47], v[128:131], v[168:171], v[44:47]
	v_mfma_f32_16x16x32_bf16 v[40:43], v[136:139], v[168:171], v[40:43]
	v_mfma_f32_16x16x32_bf16 v[28:31], v[128:131], v[176:179], v[28:31]
	v_mfma_f32_16x16x32_bf16 v[24:27], v[136:139], v[176:179], v[24:27]
	v_mfma_f32_16x16x32_bf16 v[12:15], v[128:131], v[230:233], v[12:15]
	v_mfma_f32_16x16x32_bf16 v[8:11], v[136:139], v[230:233], v[8:11]
	v_mfma_f32_16x16x32_bf16 v[60:63], v[132:135], v[164:167], v[60:63]
	v_mfma_f32_16x16x32_bf16 v[56:59], v[140:143], v[164:167], v[56:59]
	v_mfma_f32_16x16x32_bf16 v[44:47], v[132:135], v[172:175], v[44:47]
	v_mfma_f32_16x16x32_bf16 v[40:43], v[140:143], v[172:175], v[40:43]
	v_mfma_f32_16x16x32_bf16 v[28:31], v[132:135], v[180:183], v[28:31]
	v_mfma_f32_16x16x32_bf16 v[24:27], v[140:143], v[180:183], v[24:27]
	v_mfma_f32_16x16x32_bf16 v[12:15], v[132:135], v[234:237], v[12:15]
	v_mfma_f32_16x16x32_bf16 v[8:11], v[140:143], v[234:237], v[8:11]
	v_mfma_f32_16x16x32_bf16 v[52:55], v[144:147], v[160:163], v[52:55]
	v_mfma_f32_16x16x32_bf16 v[48:51], v[152:155], v[160:163], v[48:51]
	v_mfma_f32_16x16x32_bf16 v[36:39], v[144:147], v[168:171], v[36:39]
	v_mfma_f32_16x16x32_bf16 v[32:35], v[152:155], v[168:171], v[32:35]
	v_mfma_f32_16x16x32_bf16 v[20:23], v[144:147], v[176:179], v[20:23]
	v_mfma_f32_16x16x32_bf16 v[16:19], v[152:155], v[176:179], v[16:19]
	v_mfma_f32_16x16x32_bf16 v[4:7], v[144:147], v[230:233], v[4:7]
	v_mfma_f32_16x16x32_bf16 v[0:3], v[152:155], v[230:233], v[0:3]
	v_mfma_f32_16x16x32_bf16 v[52:55], v[148:151], v[164:167], v[52:55]
	v_mfma_f32_16x16x32_bf16 v[48:51], v[156:159], v[164:167], v[48:51]
	v_mfma_f32_16x16x32_bf16 v[36:39], v[148:151], v[172:175], v[36:39]
	v_mfma_f32_16x16x32_bf16 v[32:35], v[156:159], v[172:175], v[32:35]
	v_mfma_f32_16x16x32_bf16 v[20:23], v[148:151], v[180:183], v[20:23]
	v_mfma_f32_16x16x32_bf16 v[16:19], v[156:159], v[180:183], v[16:19]
	v_mfma_f32_16x16x32_bf16 v[4:7], v[148:151], v[234:237], v[4:7]
	v_mfma_f32_16x16x32_bf16 v[0:3], v[156:159], v[234:237], v[0:3]
	s_setprio 0
	s_barrier
	ds_read_b128 v[128:131], v223
	ds_read_b128 v[132:135], v223 offset:1024
	ds_read_b128 v[136:139], v223 offset:2048
	ds_read_b128 v[140:143], v223 offset:3072
	ds_read_b128 v[144:147], v224
	ds_read_b128 v[148:151], v224 offset:1024
	ds_read_b128 v[152:155], v224 offset:2048
	ds_read_b128 v[156:159], v224 offset:3072
	s_mov_b32 m0, s18
	v_lshl_add_u64 v[242:243], v[240:241], 0, s[42:43]
	ds_read_b128 v[160:163], v222 offset:32768
	ds_read_b128 v[164:167], v222 offset:33792
	ds_read_b128 v[168:171], v222 offset:34816
	ds_read_b128 v[172:175], v222 offset:35840
	ds_read_b128 v[176:179], v222 offset:36864
	ds_read_b128 v[180:183], v222 offset:37888
	ds_read_b128 v[230:233], v222 offset:38912
	ds_read_b128 v[234:237], v222 offset:39936
	global_load_lds_dwordx4 v[242:243], off
	v_lshl_add_u64 v[242:243], v[240:241], 0, s[44:45]
	s_mov_b32 m0, s19
	s_nop 0
	global_load_lds_dwordx4 v[242:243], off
	s_waitcnt vmcnt(8)
	s_waitcnt lgkmcnt(0)
	s_barrier
	s_setprio 1
	s_waitcnt lgkmcnt(0)
	v_mfma_f32_16x16x32_bf16 v[124:127], v[128:131], v[160:163], v[124:127]
	v_mfma_f32_16x16x32_bf16 v[120:123], v[136:139], v[160:163], v[120:123]
	v_mfma_f32_16x16x32_bf16 v[108:111], v[128:131], v[168:171], v[108:111]
	v_mfma_f32_16x16x32_bf16 v[104:107], v[136:139], v[168:171], v[104:107]
	v_mfma_f32_16x16x32_bf16 v[92:95], v[128:131], v[176:179], v[92:95]
	v_mfma_f32_16x16x32_bf16 v[88:91], v[136:139], v[176:179], v[88:91]
	v_mfma_f32_16x16x32_bf16 v[76:79], v[128:131], v[230:233], v[76:79]
	v_mfma_f32_16x16x32_bf16 v[72:75], v[136:139], v[230:233], v[72:75]
	v_mfma_f32_16x16x32_bf16 v[124:127], v[132:135], v[164:167], v[124:127]
	v_mfma_f32_16x16x32_bf16 v[120:123], v[140:143], v[164:167], v[120:123]
	v_mfma_f32_16x16x32_bf16 v[108:111], v[132:135], v[172:175], v[108:111]
	v_mfma_f32_16x16x32_bf16 v[104:107], v[140:143], v[172:175], v[104:107]
	v_mfma_f32_16x16x32_bf16 v[92:95], v[132:135], v[180:183], v[92:95]
	v_mfma_f32_16x16x32_bf16 v[88:91], v[140:143], v[180:183], v[88:91]
	v_mfma_f32_16x16x32_bf16 v[76:79], v[132:135], v[234:237], v[76:79]
	v_mfma_f32_16x16x32_bf16 v[72:75], v[140:143], v[234:237], v[72:75]
	v_mfma_f32_16x16x32_bf16 v[116:119], v[144:147], v[160:163], v[116:119]
	v_mfma_f32_16x16x32_bf16 v[112:115], v[152:155], v[160:163], v[112:115]
	v_mfma_f32_16x16x32_bf16 v[100:103], v[144:147], v[168:171], v[100:103]
	v_mfma_f32_16x16x32_bf16 v[96:99], v[152:155], v[168:171], v[96:99]
	v_mfma_f32_16x16x32_bf16 v[84:87], v[144:147], v[176:179], v[84:87]
	v_mfma_f32_16x16x32_bf16 v[80:83], v[152:155], v[176:179], v[80:83]
	v_mfma_f32_16x16x32_bf16 v[68:71], v[144:147], v[230:233], v[68:71]
	v_mfma_f32_16x16x32_bf16 v[64:67], v[152:155], v[230:233], v[64:67]
	v_mfma_f32_16x16x32_bf16 v[116:119], v[148:151], v[164:167], v[116:119]
	v_mfma_f32_16x16x32_bf16 v[112:115], v[156:159], v[164:167], v[112:115]
	v_mfma_f32_16x16x32_bf16 v[100:103], v[148:151], v[172:175], v[100:103]
	v_mfma_f32_16x16x32_bf16 v[96:99], v[156:159], v[172:175], v[96:99]
	v_mfma_f32_16x16x32_bf16 v[84:87], v[148:151], v[180:183], v[84:87]
	v_mfma_f32_16x16x32_bf16 v[80:83], v[156:159], v[180:183], v[80:83]
	v_mfma_f32_16x16x32_bf16 v[68:71], v[148:151], v[234:237], v[68:71]
	v_mfma_f32_16x16x32_bf16 v[64:67], v[156:159], v[234:237], v[64:67]
	s_setprio 0
	s_barrier
; #define PG8_STAGE(bufoff, gbase, voff) do { _Pragma("unroll") for (int _i = 0; _i < 2; ++_i) \
;         __builtin_amdgcn_global_load_lds((const unsigned*)((const char*)(gbase) + (voff)[_i]), (PG8_LAS unsigned*)(lds + (bufoff) + ldsw + _i * 8192), 16, 0, 0); } while (0)
; #define PG8_LDA(dst, b, h) do { _Pragma("unroll") for (int m = 0; m < 4; ++m) _Pragma("unroll") for (int k = 0; k < 2; ++k) dst[m][k] = *(const PG8_LAS bf16x8*)(lds + PG8_SA(b, h) + aoff + m * 2048 + k * 1024); } while (0)
; #define PG8_MMA(ai, bj, At, Bt) do { __builtin_amdgcn_s_setprio(1); _Pragma("unroll") for (int m = 0; m < 4; ++m) _Pragma("unroll") for (int n = 0; n < 2; ++n) _Pragma("unroll") for (int k = 0; k < 2; ++k) \
;         acc[ai][bj][m][n] = __builtin_amdgcn_mfma_f32_16x16x32_bf16(Bt[n][k], At[m][k], acc[ai][bj][m][n], 0, 0, 0); __builtin_amdgcn_s_setprio(0); } while (0)
; #define PG8_WAIT_V(n) asm volatile("s_waitcnt vmcnt(" #n ")" ::: "memory")
; #define PG8_WAIT_L(n) asm volatile("s_waitcnt lgkmcnt(" #n ")" ::: "memory")
; #define PG8_BAR __builtin_amdgcn_s_barrier()
; #define PG8_SCHED __builtin_amdgcn_sched_barrier(0)
; template <class Epi, class Sched, bool ALIGN_EPI = false, bool SP2 = false>
; __device__ __forceinline__ void gemm_phase(PG8_LAS unsigned char* lds, const Gemm g, const Sched& S, const Epi& E) {
;     ...
;             PG8_LDA(At, 1, 1); PG8_STAGE(PG8_SB(1, 0), b3, voffB); PG8_STAGE(PG8_SB(1, 1), b3 + hstepB, voffB); PG8_STAGE(PG8_SA(1, 0), a3, voffA);
;             PG8_WAIT_V(8); PG8_WAIT_L(0); PG8_BAR; PG8_MMA(1, 0, At, B0); PG8_MMA(1, 1, At, B1); PG8_BAR; PG8_SCHED;
	s_add_i32 s33, s88, s14
	v_lshl_add_u64 v[242:243], v[238:239], 0, s[46:47]
	s_mov_b32 m0, s33
	ds_read_b128 v[160:163], v222 offset:49152
	ds_read_b128 v[164:167], v222 offset:50176
	ds_read_b128 v[168:171], v222 offset:51200
	ds_read_b128 v[172:175], v222 offset:52224
	ds_read_b128 v[176:179], v222 offset:53248
	ds_read_b128 v[180:183], v222 offset:54272
	ds_read_b128 v[230:233], v222 offset:55296
	ds_read_b128 v[234:237], v222 offset:56320
	global_load_lds_dwordx4 v[242:243], off
	v_lshl_add_u64 v[242:243], v[238:239], 0, s[48:49]
	s_add_i32 m0, s33, 0x2000
	s_add_i32 s33, s89, s14
	global_load_lds_dwordx4 v[242:243], off
	v_lshl_add_u64 v[242:243], v[238:239], 0, s[52:53]
	s_mov_b32 m0, s33
	v_lshl_add_u64 v[238:239], v[238:239], 0, s[54:55]
	global_load_lds_dwordx4 v[242:243], off
	s_add_i32 m0, s33, 0x2000
	s_nop 0
	global_load_lds_dwordx4 v[238:239], off
	v_lshl_add_u64 v[238:239], v[240:241], 0, s[46:47]
	s_mov_b32 m0, s80
	s_nop 0
	global_load_lds_dwordx4 v[238:239], off
	v_lshl_add_u64 v[238:239], v[240:241], 0, s[48:49]
	s_mov_b32 m0, s81
	s_nop 0
	global_load_lds_dwordx4 v[238:239], off
	s_waitcnt vmcnt(8)
	s_waitcnt lgkmcnt(0)
	s_barrier
	s_setprio 1
	s_waitcnt lgkmcnt(0)
	v_mfma_f32_16x16x32_bf16 v[60:63], v[128:131], v[160:163], v[60:63]
	v_mfma_f32_16x16x32_bf16 v[56:59], v[136:139], v[160:163], v[56:59]
	v_mfma_f32_16x16x32_bf16 v[44:47], v[128:131], v[168:171], v[44:47]
	v_mfma_f32_16x16x32_bf16 v[40:43], v[136:139], v[168:171], v[40:43]
	v_mfma_f32_16x16x32_bf16 v[28:31], v[128:131], v[176:179], v[28:31]
	v_mfma_f32_16x16x32_bf16 v[24:27], v[136:139], v[176:179], v[24:27]
	v_mfma_f32_16x16x32_bf16 v[12:15], v[128:131], v[230:233], v[12:15]
	v_mfma_f32_16x16x32_bf16 v[8:11], v[136:139], v[230:233], v[8:11]
	v_mfma_f32_16x16x32_bf16 v[60:63], v[132:135], v[164:167], v[60:63]
	v_mfma_f32_16x16x32_bf16 v[56:59], v[140:143], v[164:167], v[56:59]
	v_mfma_f32_16x16x32_bf16 v[44:47], v[132:135], v[172:175], v[44:47]
	v_mfma_f32_16x16x32_bf16 v[40:43], v[140:143], v[172:175], v[40:43]
	v_mfma_f32_16x16x32_bf16 v[28:31], v[132:135], v[180:183], v[28:31]
	v_mfma_f32_16x16x32_bf16 v[24:27], v[140:143], v[180:183], v[24:27]
	v_mfma_f32_16x16x32_bf16 v[12:15], v[132:135], v[234:237], v[12:15]
	v_mfma_f32_16x16x32_bf16 v[8:11], v[140:143], v[234:237], v[8:11]
	v_mfma_f32_16x16x32_bf16 v[52:55], v[144:147], v[160:163], v[52:55]
	v_mfma_f32_16x16x32_bf16 v[48:51], v[152:155], v[160:163], v[48:51]
	v_mfma_f32_16x16x32_bf16 v[36:39], v[144:147], v[168:171], v[36:39]
	v_mfma_f32_16x16x32_bf16 v[32:35], v[152:155], v[168:171], v[32:35]
	v_mfma_f32_16x16x32_bf16 v[20:23], v[144:147], v[176:179], v[20:23]
	v_mfma_f32_16x16x32_bf16 v[16:19], v[152:155], v[176:179], v[16:19]
	v_mfma_f32_16x16x32_bf16 v[4:7], v[144:147], v[230:233], v[4:7]
	v_mfma_f32_16x16x32_bf16 v[0:3], v[152:155], v[230:233], v[0:3]
	v_mfma_f32_16x16x32_bf16 v[52:55], v[148:151], v[164:167], v[52:55]
	v_mfma_f32_16x16x32_bf16 v[48:51], v[156:159], v[164:167], v[48:51]
	v_mfma_f32_16x16x32_bf16 v[36:39], v[148:151], v[172:175], v[36:39]
	v_mfma_f32_16x16x32_bf16 v[32:35], v[156:159], v[172:175], v[32:35]
	v_mfma_f32_16x16x32_bf16 v[20:23], v[148:151], v[180:183], v[20:23]
	v_mfma_f32_16x16x32_bf16 v[16:19], v[156:159], v[180:183], v[16:19]
	v_mfma_f32_16x16x32_bf16 v[4:7], v[148:151], v[234:237], v[4:7]
	v_mfma_f32_16x16x32_bf16 v[0:3], v[156:159], v[234:237], v[0:3]
	s_setprio 0
	s_barrier
	s_add_i32 s73, s73, 2
	s_add_u32 s70, s70, 0x10000
	s_addc_u32 s71, s71, 0
	s_add_u32 s69, s69, 0x10000
	s_addc_u32 s72, s72, 0
	s_cmp_gt_u32 s73, 41
	s_cbranch_scc0 .LBB0_1004
	s_and_b64 vcc, exec, s[60:61]
	s_cbranch_vccz .LBB0_1007
	s_barrier
